# v25 + Hyena spec_mul fused into the preceding FFT's last Stockham store (X operands stay in registers: -16 ds_write, -16 ds_read, -1 barrier per call)
# speedup vs baseline: 1.0173x; 1.0097x over previous
.LBB0_432:
	s_or_b64 exec, exec, s[0:1]
	v_mov_b32_e32 v120, v32
	s_waitcnt lgkmcnt(0)
	s_barrier
	s_mov_b32 s11, s14
	v_and_b32_e32 v121, 31, v120
	v_cvt_f32_ubyte0_e32 v24, v121
	v_mul_f32_e32 v102, 0x3b000000, v24
	v_sin_f32_e32 v24, v102
	v_ashrrev_i32_e32 v0, 4, v120
	v_lshlrev_b32_e32 v0, 3, v0
	v_lshlrev_b32_e32 v1, 3, v120
	v_cos_f32_e32 v102, v102
	v_add3_u32 v25, 0, v0, v1
	ds_read_b64 v[0:1], v25
	ds_read_b64 v[2:3], v25 offset:4352
	ds_read_b64 v[4:5], v25 offset:8704
	ds_read_b64 v[6:7], v25 offset:13056
	ds_read_b64 v[8:9], v25 offset:17408
	ds_read_b64 v[10:11], v25 offset:21760
	ds_read_b64 v[12:13], v25 offset:26112
	ds_read_b64 v[14:15], v25 offset:30464
	ds_read_b64 v[16:17], v25 offset:34816
	ds_read_b64 v[18:19], v25 offset:39168
	ds_read_b64 v[20:21], v25 offset:43520
	ds_read_b64 v[22:23], v25 offset:47872
	v_xor_b32_e32 v103, 0x80000000, v24
	s_waitcnt lgkmcnt(10)
	v_pk_mul_f32 v[110:111], v[2:3], v[24:25] op_sel:[1,0] op_sel_hi:[0,0] neg_hi:[0,1]
	v_pk_fma_f32 v[2:3], v[2:3], v[102:103], v[110:111] op_sel_hi:[1,0,1]
	v_pk_mul_f32 v[110:111], v[24:25], v[102:103] op_sel:[0,1] op_sel_hi:[0,0] neg_hi:[1,0]
	v_pk_fma_f32 v[110:111], v[102:103], v[102:103], v[110:111] op_sel_hi:[0,1,1]
	ds_read_b64 v[26:27], v25 offset:52224
	ds_read_b64 v[28:29], v25 offset:56576
	ds_read_b64 v[30:31], v25 offset:60928
	ds_read_b64 v[80:81], v25 offset:65280
	s_waitcnt lgkmcnt(13)
	v_pk_mul_f32 v[118:119], v[4:5], v[110:111] op_sel:[1,1] op_sel_hi:[0,1] neg_lo:[0,1]
	v_pk_fma_f32 v[4:5], v[4:5], v[110:111], v[118:119] op_sel_hi:[1,0,1]
	v_pk_mul_f32 v[118:119], v[24:25], v[110:111] op_sel:[0,1] op_sel_hi:[0,0] neg_hi:[1,0]
	v_pk_fma_f32 v[110:111], v[102:103], v[110:111], v[118:119] op_sel_hi:[0,1,1]
	s_mov_b32 s35, s30
	s_waitcnt lgkmcnt(12)
	v_pk_mul_f32 v[118:119], v[6:7], v[110:111] op_sel:[1,1] op_sel_hi:[0,1] neg_lo:[0,1]
	v_pk_fma_f32 v[6:7], v[6:7], v[110:111], v[118:119] op_sel_hi:[1,0,1]
	v_pk_mul_f32 v[118:119], v[24:25], v[110:111] op_sel:[0,1] op_sel_hi:[0,0] neg_hi:[1,0]
	v_pk_fma_f32 v[110:111], v[102:103], v[110:111], v[118:119] op_sel_hi:[0,1,1]
	s_mov_b32 s0, s19
	s_waitcnt lgkmcnt(11)
	v_pk_mul_f32 v[118:119], v[8:9], v[110:111] op_sel:[1,1] op_sel_hi:[0,1] neg_lo:[0,1]
	v_pk_fma_f32 v[8:9], v[8:9], v[110:111], v[118:119] op_sel_hi:[1,0,1]
	v_pk_mul_f32 v[118:119], v[24:25], v[110:111] op_sel:[0,1] op_sel_hi:[0,0] neg_hi:[1,0]
	v_pk_fma_f32 v[110:111], v[102:103], v[110:111], v[118:119] op_sel_hi:[0,1,1]
	s_waitcnt lgkmcnt(0)
	v_pk_mul_f32 v[118:119], v[10:11], v[110:111] op_sel:[1,1] op_sel_hi:[0,1] neg_lo:[0,1]
	v_pk_fma_f32 v[10:11], v[10:11], v[110:111], v[118:119] op_sel_hi:[1,0,1]
	v_pk_mul_f32 v[118:119], v[24:25], v[110:111] op_sel:[0,1] op_sel_hi:[0,0] neg_hi:[1,0]
	v_pk_fma_f32 v[110:111], v[102:103], v[110:111], v[118:119] op_sel_hi:[0,1,1]
	s_barrier
	v_pk_mul_f32 v[118:119], v[12:13], v[110:111] op_sel:[1,1] op_sel_hi:[0,1] neg_lo:[0,1]
	v_pk_fma_f32 v[12:13], v[12:13], v[110:111], v[118:119] op_sel_hi:[1,0,1]
	v_pk_mul_f32 v[118:119], v[24:25], v[110:111] op_sel:[0,1] op_sel_hi:[0,0] neg_hi:[1,0]
	v_pk_fma_f32 v[110:111], v[102:103], v[110:111], v[118:119] op_sel_hi:[0,1,1]
	s_nop 0
	v_pk_mul_f32 v[118:119], v[14:15], v[110:111] op_sel:[1,1] op_sel_hi:[0,1] neg_lo:[0,1]
	v_pk_fma_f32 v[14:15], v[14:15], v[110:111], v[118:119] op_sel_hi:[1,0,1]
	v_pk_mul_f32 v[118:119], v[24:25], v[110:111] op_sel:[0,1] op_sel_hi:[0,0] neg_hi:[1,0]
	v_pk_fma_f32 v[110:111], v[102:103], v[110:111], v[118:119] op_sel_hi:[0,1,1]
	v_lshlrev_b32_e32 v155, 3, v47
	v_pk_mul_f32 v[118:119], v[16:17], v[110:111] op_sel:[1,1] op_sel_hi:[0,1] neg_lo:[0,1]
	v_pk_fma_f32 v[16:17], v[16:17], v[110:111], v[118:119] op_sel_hi:[1,0,1]
	v_pk_mul_f32 v[118:119], v[24:25], v[110:111] op_sel:[0,1] op_sel_hi:[0,0] neg_hi:[1,0]
	v_pk_fma_f32 v[110:111], v[102:103], v[110:111], v[118:119] op_sel_hi:[0,1,1]
	s_nop 0
	v_pk_mul_f32 v[118:119], v[18:19], v[110:111] op_sel:[1,1] op_sel_hi:[0,1] neg_lo:[0,1]
	v_pk_fma_f32 v[18:19], v[18:19], v[110:111], v[118:119] op_sel_hi:[1,0,1]
	v_pk_mul_f32 v[118:119], v[24:25], v[110:111] op_sel:[0,1] op_sel_hi:[0,0] neg_hi:[1,0]
	v_pk_fma_f32 v[110:111], v[102:103], v[110:111], v[118:119] op_sel_hi:[0,1,1]
	s_nop 0
	v_pk_mul_f32 v[118:119], v[20:21], v[110:111] op_sel:[1,1] op_sel_hi:[0,1] neg_lo:[0,1]
	v_pk_fma_f32 v[20:21], v[20:21], v[110:111], v[118:119] op_sel_hi:[1,0,1]
	v_pk_mul_f32 v[118:119], v[24:25], v[110:111] op_sel:[0,1] op_sel_hi:[0,0] neg_hi:[1,0]
	v_pk_fma_f32 v[110:111], v[102:103], v[110:111], v[118:119] op_sel_hi:[0,1,1]
	s_nop 0
	v_pk_mul_f32 v[118:119], v[22:23], v[110:111] op_sel:[1,1] op_sel_hi:[0,1] neg_lo:[0,1]
	v_pk_fma_f32 v[22:23], v[22:23], v[110:111], v[118:119] op_sel_hi:[1,0,1]
	v_pk_mul_f32 v[118:119], v[24:25], v[110:111] op_sel:[0,1] op_sel_hi:[0,0] neg_hi:[1,0]
	v_pk_fma_f32 v[110:111], v[102:103], v[110:111], v[118:119] op_sel_hi:[0,1,1]
	s_nop 0
	v_pk_mul_f32 v[118:119], v[26:27], v[110:111] op_sel:[1,1] op_sel_hi:[0,1] neg_lo:[0,1]
	v_pk_fma_f32 v[26:27], v[26:27], v[110:111], v[118:119] op_sel_hi:[1,0,1]
	v_pk_mul_f32 v[118:119], v[24:25], v[110:111] op_sel:[0,1] op_sel_hi:[0,0] neg_hi:[1,0]
	v_pk_fma_f32 v[110:111], v[102:103], v[110:111], v[118:119] op_sel_hi:[0,1,1]
	s_nop 0
	v_pk_mul_f32 v[118:119], v[28:29], v[110:111] op_sel:[1,1] op_sel_hi:[0,1] neg_lo:[0,1]
	v_pk_fma_f32 v[28:29], v[28:29], v[110:111], v[118:119] op_sel_hi:[1,0,1]
	v_pk_mul_f32 v[118:119], v[24:25], v[110:111] op_sel:[0,1] op_sel_hi:[0,0] neg_hi:[1,0]
	v_pk_fma_f32 v[110:111], v[102:103], v[110:111], v[118:119] op_sel_hi:[0,1,1]
	v_pk_mul_f32 v[24:25], v[24:25], v[110:111] op_sel:[0,1] op_sel_hi:[0,0] neg_hi:[1,0]
	v_pk_fma_f32 v[24:25], v[102:103], v[110:111], v[24:25] op_sel_hi:[0,1,1]
	v_pk_mul_f32 v[102:103], v[80:81], v[24:25] op_sel:[1,1] op_sel_hi:[0,1] neg_lo:[0,1]
	v_pk_fma_f32 v[24:25], v[80:81], v[24:25], v[102:103] op_sel_hi:[1,0,1]
	v_pk_add_f32 v[80:81], v[0:1], v[16:17]
	v_pk_add_f32 v[0:1], v[0:1], v[16:17] neg_lo:[0,1] neg_hi:[0,1]
	v_pk_add_f32 v[16:17], v[2:3], v[18:19]
	v_pk_add_f32 v[2:3], v[2:3], v[18:19] neg_lo:[0,1] neg_hi:[0,1]
	v_pk_mul_f32 v[118:119], v[30:31], v[110:111] op_sel:[1,1] op_sel_hi:[0,1] neg_lo:[0,1]
	v_pk_mul_f32 v[18:19], v[2:3], s[18:19]
	v_pk_fma_f32 v[30:31], v[30:31], v[110:111], v[118:119] op_sel_hi:[1,0,1]
	v_pk_fma_f32 v[2:3], v[2:3], s[30:31], v[18:19] op_sel:[0,0,1] op_sel_hi:[1,0,0]
	v_pk_add_f32 v[18:19], v[4:5], v[20:21]
	v_pk_add_f32 v[4:5], v[4:5], v[20:21] neg_lo:[0,1] neg_hi:[0,1]
	s_nop 0
	v_pk_mul_f32 v[20:21], v[4:5], s[10:11]
	s_nop 0
	v_pk_fma_f32 v[4:5], v[4:5], s[14:15], v[20:21] op_sel:[0,0,1] op_sel_hi:[1,0,0]
	v_pk_add_f32 v[20:21], v[6:7], v[22:23]
	v_pk_add_f32 v[6:7], v[6:7], v[22:23] neg_lo:[0,1] neg_hi:[0,1]
	s_nop 0
	v_pk_mul_f32 v[22:23], v[6:7], s[34:35]
	s_nop 0
	v_pk_fma_f32 v[6:7], v[6:7], s[0:1], v[22:23] op_sel:[0,0,1] op_sel_hi:[1,0,0]
	v_pk_add_f32 v[22:23], v[8:9], v[26:27]
	v_pk_add_f32 v[8:9], v[8:9], v[26:27] neg_lo:[0,1] neg_hi:[0,1]
	v_pk_add_f32 v[26:27], v[10:11], v[28:29]
	v_pk_add_f32 v[10:11], v[10:11], v[28:29] neg_lo:[0,1] neg_hi:[0,1]
	s_nop 0
	v_pk_mul_f32 v[28:29], v[10:11], s[34:35]
	s_nop 0
	v_pk_fma_f32 v[10:11], v[10:11], s[0:1], v[28:29] op_sel:[0,0,1] op_sel_hi:[1,0,0] neg_lo:[1,0,0] neg_hi:[1,0,0]
	v_pk_add_f32 v[28:29], v[12:13], v[30:31]
	v_pk_add_f32 v[12:13], v[12:13], v[30:31] neg_lo:[0,1] neg_hi:[0,1]
	s_nop 0
	v_pk_mul_f32 v[30:31], v[12:13], s[10:11]
	s_nop 0
	v_pk_fma_f32 v[12:13], v[12:13], s[14:15], v[30:31] op_sel:[0,0,1] op_sel_hi:[1,0,0] neg_lo:[1,0,0] neg_hi:[1,0,0]
	v_pk_add_f32 v[30:31], v[14:15], v[24:25]
	v_pk_add_f32 v[14:15], v[14:15], v[24:25] neg_lo:[0,1] neg_hi:[0,1]
	s_nop 0
	v_pk_mul_f32 v[24:25], v[14:15], s[18:19]
	s_nop 0
	v_pk_fma_f32 v[14:15], v[14:15], s[30:31], v[24:25] op_sel:[0,0,1] op_sel_hi:[1,0,0] neg_lo:[1,0,0] neg_hi:[1,0,0]
	v_pk_add_f32 v[24:25], v[80:81], v[22:23]
	v_pk_add_f32 v[22:23], v[80:81], v[22:23] neg_lo:[0,1] neg_hi:[0,1]
	v_pk_add_f32 v[80:81], v[16:17], v[26:27]
	v_pk_add_f32 v[16:17], v[16:17], v[26:27] neg_lo:[0,1] neg_hi:[0,1]
	s_nop 0
	v_pk_mul_f32 v[26:27], v[16:17], s[10:11]
	s_nop 0
	v_pk_fma_f32 v[16:17], v[16:17], s[14:15], v[26:27] op_sel:[0,0,1] op_sel_hi:[1,0,0]
	v_pk_add_f32 v[26:27], v[18:19], v[28:29]
	v_pk_add_f32 v[18:19], v[18:19], v[28:29] neg_lo:[0,1] neg_hi:[0,1]
	v_pk_add_f32 v[28:29], v[20:21], v[30:31]
	v_pk_add_f32 v[20:21], v[20:21], v[30:31] neg_lo:[0,1] neg_hi:[0,1]
	s_nop 0
	v_pk_mul_f32 v[30:31], v[20:21], s[10:11]
	s_nop 0
	v_pk_fma_f32 v[20:21], v[20:21], s[14:15], v[30:31] op_sel:[0,0,1] op_sel_hi:[1,0,0] neg_lo:[1,0,0] neg_hi:[1,0,0]
	v_pk_add_f32 v[30:31], v[0:1], v[8:9] op_sel:[0,1] op_sel_hi:[1,0] neg_hi:[0,1]
	v_pk_add_f32 v[0:1], v[0:1], v[8:9] op_sel:[0,1] op_sel_hi:[1,0] neg_lo:[0,1]
	v_pk_add_f32 v[8:9], v[2:3], v[10:11]
	v_pk_add_f32 v[2:3], v[2:3], v[10:11] neg_lo:[0,1] neg_hi:[0,1]
	s_nop 0
	v_pk_mul_f32 v[10:11], v[2:3], s[10:11]
	s_nop 0
	v_pk_fma_f32 v[2:3], v[2:3], s[14:15], v[10:11] op_sel:[0,0,1] op_sel_hi:[1,0,0]
	v_pk_add_f32 v[10:11], v[4:5], v[12:13]
	v_pk_add_f32 v[4:5], v[4:5], v[12:13] neg_lo:[0,1] neg_hi:[0,1]
	v_pk_add_f32 v[12:13], v[6:7], v[14:15]
	v_pk_add_f32 v[6:7], v[6:7], v[14:15] neg_lo:[0,1] neg_hi:[0,1]
	s_nop 0
	v_pk_mul_f32 v[14:15], v[6:7], s[10:11]
	s_nop 0
	v_pk_fma_f32 v[6:7], v[6:7], s[14:15], v[14:15] op_sel:[0,0,1] op_sel_hi:[1,0,0] neg_lo:[1,0,0] neg_hi:[1,0,0]
	v_pk_add_f32 v[14:15], v[24:25], v[26:27]
	v_pk_add_f32 v[24:25], v[24:25], v[26:27] neg_lo:[0,1] neg_hi:[0,1]
	v_pk_add_f32 v[26:27], v[80:81], v[28:29]
	v_pk_add_f32 v[28:29], v[80:81], v[28:29] neg_lo:[0,1] neg_hi:[0,1]
	v_pk_add_f32 v[80:81], v[22:23], v[18:19] op_sel:[0,1] op_sel_hi:[1,0] neg_hi:[0,1]
	v_pk_add_f32 v[18:19], v[22:23], v[18:19] op_sel:[0,1] op_sel_hi:[1,0] neg_lo:[0,1]
	v_pk_add_f32 v[22:23], v[16:17], v[20:21]
	v_pk_add_f32 v[16:17], v[16:17], v[20:21] neg_lo:[0,1] neg_hi:[0,1]
	v_pk_add_f32 v[20:21], v[30:31], v[10:11]
	v_pk_add_f32 v[10:11], v[30:31], v[10:11] neg_lo:[0,1] neg_hi:[0,1]
	v_pk_add_f32 v[30:31], v[8:9], v[12:13]
	v_pk_add_f32 v[8:9], v[8:9], v[12:13] neg_lo:[0,1] neg_hi:[0,1]
	v_pk_add_f32 v[12:13], v[0:1], v[4:5] op_sel:[0,1] op_sel_hi:[1,0] neg_hi:[0,1]
	v_pk_add_f32 v[0:1], v[0:1], v[4:5] op_sel:[0,1] op_sel_hi:[1,0] neg_lo:[0,1]
	v_pk_add_f32 v[4:5], v[2:3], v[6:7]
	v_pk_add_f32 v[2:3], v[2:3], v[6:7] neg_lo:[0,1] neg_hi:[0,1]
	s_nop 0
	v_pk_mul_f32 v[2:3], v[2:3], s[22:23]
	v_pk_add_f32 v[6:7], v[14:15], v[26:27]
	v_pk_add_f32 v[14:15], v[14:15], v[26:27] neg_lo:[0,1] neg_hi:[0,1]
	v_pk_add_f32 v[26:27], v[24:25], v[28:29] op_sel:[0,1] op_sel_hi:[1,0] neg_hi:[0,1]
	v_pk_add_f32 v[24:25], v[24:25], v[28:29] op_sel:[0,1] op_sel_hi:[1,0] neg_lo:[0,1]
	v_pk_add_f32 v[28:29], v[80:81], v[22:23]
	v_pk_add_f32 v[22:23], v[80:81], v[22:23] neg_lo:[0,1] neg_hi:[0,1]
	v_pk_add_f32 v[80:81], v[18:19], v[16:17] op_sel:[0,1] op_sel_hi:[1,0] neg_hi:[0,1]
	v_pk_add_f32 v[16:17], v[18:19], v[16:17] op_sel:[0,1] op_sel_hi:[1,0] neg_lo:[0,1]
	v_pk_add_f32 v[18:19], v[20:21], v[30:31]
	v_pk_add_f32 v[20:21], v[20:21], v[30:31] neg_lo:[0,1] neg_hi:[0,1]
	v_pk_add_f32 v[30:31], v[10:11], v[8:9] op_sel:[0,1] op_sel_hi:[1,0] neg_hi:[0,1]
	v_pk_add_f32 v[8:9], v[10:11], v[8:9] op_sel:[0,1] op_sel_hi:[1,0] neg_lo:[0,1]
	v_pk_add_f32 v[10:11], v[12:13], v[4:5]
	v_pk_add_f32 v[4:5], v[12:13], v[4:5] neg_lo:[0,1] neg_hi:[0,1]
	v_pk_add_f32 v[12:13], v[0:1], v[2:3] op_sel:[0,1] op_sel_hi:[1,0]
	v_pk_add_f32 v[0:1], v[0:1], v[2:3] op_sel:[0,1] op_sel_hi:[1,0] neg_lo:[0,1] neg_hi:[0,1]
	v_lshlrev_b32_e32 v2, 4, v120
	v_and_or_b32 v2, v2, s7, v121
	v_ashrrev_i32_e32 v3, 4, v2
	v_lshlrev_b32_e32 v3, 3, v3
	v_lshlrev_b32_e32 v2, 3, v2
	v_add3_u32 v2, 0, v3, v2
	v_add_u32_e32 v3, 0x800, v2
	v_mov_b32_e32 v120, v32
	ds_write2_b64 v2, v[6:7], v[18:19] offset1:34
	ds_write2_b64 v3, v[14:15], v[20:21] offset0:16 offset1:50
	ds_write2_b64 v2, v[26:27], v[30:31] offset0:136 offset1:170
	ds_write2_b64 v3, v[24:25], v[8:9] offset0:152 offset1:186
	ds_write2_b64 v2, v[28:29], v[10:11] offset0:68 offset1:102
	ds_write2_b64 v3, v[22:23], v[4:5] offset0:84 offset1:118
	ds_write2_b64 v2, v[80:81], v[12:13] offset0:204 offset1:238
	ds_write2_b64 v3, v[16:17], v[0:1] offset0:220 offset1:254
	s_waitcnt lgkmcnt(0)
	s_barrier
	s_nop 0
	v_and_b32_e32 v121, 0x1ff, v120
	v_cvt_f32_u32_e32 v24, v121
	v_ashrrev_i32_e32 v0, 4, v120
	v_lshlrev_b32_e32 v0, 3, v0
	v_lshlrev_b32_e32 v1, 3, v120
	v_mul_f32_e32 v102, 0x39000000, v24
	v_sin_f32_e32 v24, v102
	v_cos_f32_e32 v102, v102
	v_add3_u32 v25, 0, v0, v1
	ds_read_b64 v[0:1], v25
	ds_read_b64 v[2:3], v25 offset:4352
	ds_read_b64 v[4:5], v25 offset:8704
	ds_read_b64 v[6:7], v25 offset:13056
	ds_read_b64 v[8:9], v25 offset:17408
	ds_read_b64 v[10:11], v25 offset:21760
	ds_read_b64 v[12:13], v25 offset:26112
	ds_read_b64 v[14:15], v25 offset:30464
	v_xor_b32_e32 v103, 0x80000000, v24
	s_waitcnt lgkmcnt(6)
	v_pk_mul_f32 v[110:111], v[2:3], v[24:25] op_sel:[1,0] op_sel_hi:[0,0] neg_hi:[0,1]
	v_pk_fma_f32 v[2:3], v[2:3], v[102:103], v[110:111] op_sel_hi:[1,0,1]
	v_pk_mul_f32 v[110:111], v[24:25], v[102:103] op_sel:[0,1] op_sel_hi:[0,0] neg_hi:[1,0]
	v_pk_fma_f32 v[110:111], v[102:103], v[102:103], v[110:111] op_sel_hi:[0,1,1]
	ds_read_b64 v[16:17], v25 offset:34816
	ds_read_b64 v[18:19], v25 offset:39168
	ds_read_b64 v[20:21], v25 offset:43520
	ds_read_b64 v[22:23], v25 offset:47872
	s_waitcnt lgkmcnt(9)
	v_pk_mul_f32 v[118:119], v[4:5], v[110:111] op_sel:[1,1] op_sel_hi:[0,1] neg_lo:[0,1]
	v_pk_fma_f32 v[4:5], v[4:5], v[110:111], v[118:119] op_sel_hi:[1,0,1]
	v_pk_mul_f32 v[118:119], v[24:25], v[110:111] op_sel:[0,1] op_sel_hi:[0,0] neg_hi:[1,0]
	v_pk_fma_f32 v[110:111], v[102:103], v[110:111], v[118:119] op_sel_hi:[0,1,1]
	ds_read_b64 v[26:27], v25 offset:52224
	ds_read_b64 v[28:29], v25 offset:56576
	ds_read_b64 v[30:31], v25 offset:60928
	ds_read_b64 v[80:81], v25 offset:65280
	s_waitcnt lgkmcnt(12)
	v_pk_mul_f32 v[118:119], v[6:7], v[110:111] op_sel:[1,1] op_sel_hi:[0,1] neg_lo:[0,1]
	v_pk_fma_f32 v[6:7], v[6:7], v[110:111], v[118:119] op_sel_hi:[1,0,1]
	v_pk_mul_f32 v[118:119], v[24:25], v[110:111] op_sel:[0,1] op_sel_hi:[0,0] neg_hi:[1,0]
	v_pk_fma_f32 v[110:111], v[102:103], v[110:111], v[118:119] op_sel_hi:[0,1,1]
	s_waitcnt lgkmcnt(0)
	v_pk_mul_f32 v[118:119], v[8:9], v[110:111] op_sel:[1,1] op_sel_hi:[0,1] neg_lo:[0,1]
	v_pk_fma_f32 v[8:9], v[8:9], v[110:111], v[118:119] op_sel_hi:[1,0,1]
	v_pk_mul_f32 v[118:119], v[24:25], v[110:111] op_sel:[0,1] op_sel_hi:[0,0] neg_hi:[1,0]
	v_pk_fma_f32 v[110:111], v[102:103], v[110:111], v[118:119] op_sel_hi:[0,1,1]
	s_barrier
	v_pk_mul_f32 v[118:119], v[10:11], v[110:111] op_sel:[1,1] op_sel_hi:[0,1] neg_lo:[0,1]
	v_pk_fma_f32 v[10:11], v[10:11], v[110:111], v[118:119] op_sel_hi:[1,0,1]
	v_pk_mul_f32 v[118:119], v[24:25], v[110:111] op_sel:[0,1] op_sel_hi:[0,0] neg_hi:[1,0]
	v_pk_fma_f32 v[110:111], v[102:103], v[110:111], v[118:119] op_sel_hi:[0,1,1]
	s_nop 0
	v_pk_mul_f32 v[118:119], v[12:13], v[110:111] op_sel:[1,1] op_sel_hi:[0,1] neg_lo:[0,1]
	v_pk_fma_f32 v[12:13], v[12:13], v[110:111], v[118:119] op_sel_hi:[1,0,1]
	v_pk_mul_f32 v[118:119], v[24:25], v[110:111] op_sel:[0,1] op_sel_hi:[0,0] neg_hi:[1,0]
	v_pk_fma_f32 v[110:111], v[102:103], v[110:111], v[118:119] op_sel_hi:[0,1,1]
	s_nop 0
	v_pk_mul_f32 v[118:119], v[14:15], v[110:111] op_sel:[1,1] op_sel_hi:[0,1] neg_lo:[0,1]
	v_pk_fma_f32 v[14:15], v[14:15], v[110:111], v[118:119] op_sel_hi:[1,0,1]
	v_pk_mul_f32 v[118:119], v[24:25], v[110:111] op_sel:[0,1] op_sel_hi:[0,0] neg_hi:[1,0]
	v_pk_fma_f32 v[110:111], v[102:103], v[110:111], v[118:119] op_sel_hi:[0,1,1]
	s_nop 0
	v_pk_mul_f32 v[118:119], v[16:17], v[110:111] op_sel:[1,1] op_sel_hi:[0,1] neg_lo:[0,1]
	v_pk_fma_f32 v[16:17], v[16:17], v[110:111], v[118:119] op_sel_hi:[1,0,1]
	v_pk_mul_f32 v[118:119], v[24:25], v[110:111] op_sel:[0,1] op_sel_hi:[0,0] neg_hi:[1,0]
	v_pk_fma_f32 v[110:111], v[102:103], v[110:111], v[118:119] op_sel_hi:[0,1,1]
	s_nop 0
	v_pk_mul_f32 v[118:119], v[18:19], v[110:111] op_sel:[1,1] op_sel_hi:[0,1] neg_lo:[0,1]
	v_pk_fma_f32 v[18:19], v[18:19], v[110:111], v[118:119] op_sel_hi:[1,0,1]
	v_pk_mul_f32 v[118:119], v[24:25], v[110:111] op_sel:[0,1] op_sel_hi:[0,0] neg_hi:[1,0]
	v_pk_fma_f32 v[110:111], v[102:103], v[110:111], v[118:119] op_sel_hi:[0,1,1]
	s_nop 0
	v_pk_mul_f32 v[118:119], v[20:21], v[110:111] op_sel:[1,1] op_sel_hi:[0,1] neg_lo:[0,1]
	v_pk_fma_f32 v[20:21], v[20:21], v[110:111], v[118:119] op_sel_hi:[1,0,1]
	v_pk_mul_f32 v[118:119], v[24:25], v[110:111] op_sel:[0,1] op_sel_hi:[0,0] neg_hi:[1,0]
	v_pk_fma_f32 v[110:111], v[102:103], v[110:111], v[118:119] op_sel_hi:[0,1,1]
	s_nop 0
	v_pk_mul_f32 v[118:119], v[22:23], v[110:111] op_sel:[1,1] op_sel_hi:[0,1] neg_lo:[0,1]
	v_pk_fma_f32 v[22:23], v[22:23], v[110:111], v[118:119] op_sel_hi:[1,0,1]
	v_pk_mul_f32 v[118:119], v[24:25], v[110:111] op_sel:[0,1] op_sel_hi:[0,0] neg_hi:[1,0]
	v_pk_fma_f32 v[110:111], v[102:103], v[110:111], v[118:119] op_sel_hi:[0,1,1]
	s_nop 0
	v_pk_mul_f32 v[118:119], v[26:27], v[110:111] op_sel:[1,1] op_sel_hi:[0,1] neg_lo:[0,1]
	v_pk_fma_f32 v[26:27], v[26:27], v[110:111], v[118:119] op_sel_hi:[1,0,1]
	v_pk_mul_f32 v[118:119], v[24:25], v[110:111] op_sel:[0,1] op_sel_hi:[0,0] neg_hi:[1,0]
	v_pk_fma_f32 v[110:111], v[102:103], v[110:111], v[118:119] op_sel_hi:[0,1,1]
	s_nop 0
	v_pk_mul_f32 v[118:119], v[28:29], v[110:111] op_sel:[1,1] op_sel_hi:[0,1] neg_lo:[0,1]
	v_pk_fma_f32 v[28:29], v[28:29], v[110:111], v[118:119] op_sel_hi:[1,0,1]
	v_pk_mul_f32 v[118:119], v[24:25], v[110:111] op_sel:[0,1] op_sel_hi:[0,0] neg_hi:[1,0]
	v_pk_fma_f32 v[110:111], v[102:103], v[110:111], v[118:119] op_sel_hi:[0,1,1]
	v_pk_mul_f32 v[24:25], v[24:25], v[110:111] op_sel:[0,1] op_sel_hi:[0,0] neg_hi:[1,0]
	v_pk_fma_f32 v[24:25], v[102:103], v[110:111], v[24:25] op_sel_hi:[0,1,1]
	v_pk_mul_f32 v[102:103], v[80:81], v[24:25] op_sel:[1,1] op_sel_hi:[0,1] neg_lo:[0,1]
	v_pk_fma_f32 v[24:25], v[80:81], v[24:25], v[102:103] op_sel_hi:[1,0,1]
	v_pk_add_f32 v[80:81], v[0:1], v[16:17]
	v_pk_add_f32 v[0:1], v[0:1], v[16:17] neg_lo:[0,1] neg_hi:[0,1]
	v_pk_add_f32 v[16:17], v[2:3], v[18:19]
	v_pk_add_f32 v[2:3], v[2:3], v[18:19] neg_lo:[0,1] neg_hi:[0,1]
	v_pk_mul_f32 v[118:119], v[30:31], v[110:111] op_sel:[1,1] op_sel_hi:[0,1] neg_lo:[0,1]
	v_pk_mul_f32 v[18:19], v[2:3], s[18:19]
	v_pk_fma_f32 v[30:31], v[30:31], v[110:111], v[118:119] op_sel_hi:[1,0,1]
	v_pk_fma_f32 v[2:3], v[2:3], s[30:31], v[18:19] op_sel:[0,0,1] op_sel_hi:[1,0,0]
	v_pk_add_f32 v[18:19], v[4:5], v[20:21]
	v_pk_add_f32 v[4:5], v[4:5], v[20:21] neg_lo:[0,1] neg_hi:[0,1]
	s_nop 0
	v_pk_mul_f32 v[20:21], v[4:5], s[10:11]
	s_nop 0
	v_pk_fma_f32 v[4:5], v[4:5], s[14:15], v[20:21] op_sel:[0,0,1] op_sel_hi:[1,0,0]
	v_pk_add_f32 v[20:21], v[6:7], v[22:23]
	v_pk_add_f32 v[6:7], v[6:7], v[22:23] neg_lo:[0,1] neg_hi:[0,1]
	s_nop 0
	v_pk_mul_f32 v[22:23], v[6:7], s[34:35]
	s_nop 0
	v_pk_fma_f32 v[6:7], v[6:7], s[0:1], v[22:23] op_sel:[0,0,1] op_sel_hi:[1,0,0]
	v_pk_add_f32 v[22:23], v[8:9], v[26:27]
	v_pk_add_f32 v[8:9], v[8:9], v[26:27] neg_lo:[0,1] neg_hi:[0,1]
	v_pk_add_f32 v[26:27], v[10:11], v[28:29]
	v_pk_add_f32 v[10:11], v[10:11], v[28:29] neg_lo:[0,1] neg_hi:[0,1]
	s_nop 0
	v_pk_mul_f32 v[28:29], v[10:11], s[34:35]
	s_nop 0
	v_pk_fma_f32 v[10:11], v[10:11], s[0:1], v[28:29] op_sel:[0,0,1] op_sel_hi:[1,0,0] neg_lo:[1,0,0] neg_hi:[1,0,0]
	v_pk_add_f32 v[28:29], v[12:13], v[30:31]
	v_pk_add_f32 v[12:13], v[12:13], v[30:31] neg_lo:[0,1] neg_hi:[0,1]
	s_mov_b32 s0, 0
	v_pk_mul_f32 v[30:31], v[12:13], s[10:11]
	s_nop 0
	v_pk_fma_f32 v[12:13], v[12:13], s[14:15], v[30:31] op_sel:[0,0,1] op_sel_hi:[1,0,0] neg_lo:[1,0,0] neg_hi:[1,0,0]
	v_pk_add_f32 v[30:31], v[14:15], v[24:25]
	v_pk_add_f32 v[14:15], v[14:15], v[24:25] neg_lo:[0,1] neg_hi:[0,1]
	s_nop 0
	v_pk_mul_f32 v[24:25], v[14:15], s[18:19]
	s_nop 0
	v_pk_fma_f32 v[14:15], v[14:15], s[30:31], v[24:25] op_sel:[0,0,1] op_sel_hi:[1,0,0] neg_lo:[1,0,0] neg_hi:[1,0,0]
	v_pk_add_f32 v[24:25], v[80:81], v[22:23]
	v_pk_add_f32 v[22:23], v[80:81], v[22:23] neg_lo:[0,1] neg_hi:[0,1]
	v_pk_add_f32 v[80:81], v[16:17], v[26:27]
	v_pk_add_f32 v[16:17], v[16:17], v[26:27] neg_lo:[0,1] neg_hi:[0,1]
	s_nop 0
	v_pk_mul_f32 v[26:27], v[16:17], s[10:11]
	s_nop 0
	v_pk_fma_f32 v[16:17], v[16:17], s[14:15], v[26:27] op_sel:[0,0,1] op_sel_hi:[1,0,0]
	v_pk_add_f32 v[26:27], v[18:19], v[28:29]
	v_pk_add_f32 v[18:19], v[18:19], v[28:29] neg_lo:[0,1] neg_hi:[0,1]
	v_pk_add_f32 v[28:29], v[20:21], v[30:31]
	v_pk_add_f32 v[20:21], v[20:21], v[30:31] neg_lo:[0,1] neg_hi:[0,1]
	s_nop 0
	v_pk_mul_f32 v[30:31], v[20:21], s[10:11]
	s_nop 0
	v_pk_fma_f32 v[20:21], v[20:21], s[14:15], v[30:31] op_sel:[0,0,1] op_sel_hi:[1,0,0] neg_lo:[1,0,0] neg_hi:[1,0,0]
	v_pk_add_f32 v[30:31], v[0:1], v[8:9] op_sel:[0,1] op_sel_hi:[1,0] neg_hi:[0,1]
	v_pk_add_f32 v[0:1], v[0:1], v[8:9] op_sel:[0,1] op_sel_hi:[1,0] neg_lo:[0,1]
	v_pk_add_f32 v[8:9], v[2:3], v[10:11]
	v_pk_add_f32 v[2:3], v[2:3], v[10:11] neg_lo:[0,1] neg_hi:[0,1]
	s_nop 0
	v_pk_mul_f32 v[10:11], v[2:3], s[10:11]
	s_nop 0
	v_pk_fma_f32 v[2:3], v[2:3], s[14:15], v[10:11] op_sel:[0,0,1] op_sel_hi:[1,0,0]
	v_pk_add_f32 v[10:11], v[4:5], v[12:13]
	v_pk_add_f32 v[4:5], v[4:5], v[12:13] neg_lo:[0,1] neg_hi:[0,1]
	v_pk_add_f32 v[12:13], v[6:7], v[14:15]
	v_pk_add_f32 v[6:7], v[6:7], v[14:15] neg_lo:[0,1] neg_hi:[0,1]
	s_nop 0
	v_pk_mul_f32 v[14:15], v[6:7], s[10:11]
	s_nop 0
	v_pk_fma_f32 v[6:7], v[6:7], s[14:15], v[14:15] op_sel:[0,0,1] op_sel_hi:[1,0,0] neg_lo:[1,0,0] neg_hi:[1,0,0]
	v_pk_add_f32 v[14:15], v[24:25], v[26:27]
	v_pk_add_f32 v[24:25], v[24:25], v[26:27] neg_lo:[0,1] neg_hi:[0,1]
	v_pk_add_f32 v[26:27], v[80:81], v[28:29]
	v_pk_add_f32 v[28:29], v[80:81], v[28:29] neg_lo:[0,1] neg_hi:[0,1]
	v_pk_add_f32 v[80:81], v[22:23], v[18:19] op_sel:[0,1] op_sel_hi:[1,0] neg_hi:[0,1]
	v_pk_add_f32 v[18:19], v[22:23], v[18:19] op_sel:[0,1] op_sel_hi:[1,0] neg_lo:[0,1]
	v_pk_add_f32 v[22:23], v[16:17], v[20:21]
	v_pk_add_f32 v[16:17], v[16:17], v[20:21] neg_lo:[0,1] neg_hi:[0,1]
	v_pk_add_f32 v[20:21], v[30:31], v[10:11]
	v_pk_add_f32 v[10:11], v[30:31], v[10:11] neg_lo:[0,1] neg_hi:[0,1]
	v_pk_add_f32 v[30:31], v[8:9], v[12:13]
	v_pk_add_f32 v[8:9], v[8:9], v[12:13] neg_lo:[0,1] neg_hi:[0,1]
	v_pk_add_f32 v[12:13], v[0:1], v[4:5] op_sel:[0,1] op_sel_hi:[1,0] neg_hi:[0,1]
	v_pk_add_f32 v[0:1], v[0:1], v[4:5] op_sel:[0,1] op_sel_hi:[1,0] neg_lo:[0,1]
	v_pk_add_f32 v[4:5], v[2:3], v[6:7]
	v_pk_add_f32 v[2:3], v[2:3], v[6:7] neg_lo:[0,1] neg_hi:[0,1]
	s_nop 0
	v_pk_mul_f32 v[2:3], v[2:3], s[22:23]
	v_pk_add_f32 v[6:7], v[14:15], v[26:27]
	v_pk_add_f32 v[14:15], v[14:15], v[26:27] neg_lo:[0,1] neg_hi:[0,1]
	v_pk_add_f32 v[26:27], v[24:25], v[28:29] op_sel:[0,1] op_sel_hi:[1,0] neg_hi:[0,1]
	v_pk_add_f32 v[24:25], v[24:25], v[28:29] op_sel:[0,1] op_sel_hi:[1,0] neg_lo:[0,1]
	v_pk_add_f32 v[28:29], v[80:81], v[22:23]
	v_pk_add_f32 v[22:23], v[80:81], v[22:23] neg_lo:[0,1] neg_hi:[0,1]
	v_pk_add_f32 v[80:81], v[18:19], v[16:17] op_sel:[0,1] op_sel_hi:[1,0] neg_hi:[0,1]
	v_pk_add_f32 v[16:17], v[18:19], v[16:17] op_sel:[0,1] op_sel_hi:[1,0] neg_lo:[0,1]
	v_pk_add_f32 v[18:19], v[20:21], v[30:31]
	v_pk_add_f32 v[20:21], v[20:21], v[30:31] neg_lo:[0,1] neg_hi:[0,1]
	v_pk_add_f32 v[30:31], v[10:11], v[8:9] op_sel:[0,1] op_sel_hi:[1,0] neg_hi:[0,1]
	v_pk_add_f32 v[8:9], v[10:11], v[8:9] op_sel:[0,1] op_sel_hi:[1,0] neg_lo:[0,1]
	v_pk_add_f32 v[10:11], v[12:13], v[4:5]
	v_pk_add_f32 v[4:5], v[12:13], v[4:5] neg_lo:[0,1] neg_hi:[0,1]
	v_pk_add_f32 v[12:13], v[0:1], v[2:3] op_sel:[0,1] op_sel_hi:[1,0]
	v_pk_add_f32 v[0:1], v[0:1], v[2:3] op_sel:[0,1] op_sel_hi:[1,0] neg_lo:[0,1] neg_hi:[0,1]
	v_lshlrev_b32_e32 v2, 4, v120
	v_and_or_b32 v2, v2, s15, v121
	v_ashrrev_i32_e32 v3, 4, v2
	v_lshlrev_b32_e32 v3, 3, v3
	v_lshlrev_b32_e32 v2, 3, v2
	v_add3_u32 v2, 0, v3, v2
	v_sub_u32_e32 v166, 0x2000, v32
	v_ashrrev_i32_e32 v167, 4, v166
	v_add_u32_e32 v154, v167, v166
	v_lshlrev_b32_e32 v168, 3, v167
	v_sub_u32_e32 v156, v168, v157
.LBB0_433:
	v_add_u32_e32 v160, 0x11000, v155
	v_lshlrev_b32_e32 v161, 3, v154
	v_add_u32_e32 v161, 0x2200, v161
	v_add_u32_e32 v162, 0x11100, v156
	v_cmp_ne_u32_e32 vcc, 0, v32
	v_cndmask_b32_e32 v163, 0, v154, vcc
	v_lshlrev_b32_e32 v163, 3, v163
	v_add_u32_e32 v163, 0x11000, v163
	ds_read_b64 v[214:215], v160 offset:0
	ds_read_b64 v[216:217], v163
	ds_read_b64 v[218:219], v160 offset:4352
	ds_read_b64 v[220:221], v162 offset:60928
	ds_read_b64 v[222:223], v160 offset:8704
	ds_read_b64 v[224:225], v161 offset:52224
	ds_read_b64 v[226:227], v160 offset:13056
	ds_read_b64 v[228:229], v162 offset:52224
	s_waitcnt lgkmcnt(6)
	v_add_f32_e32 v164, v214, v216
	v_mul_f32_e32 v214, 0.5, v164
	v_sub_f32_e32 v164, v215, v217
	v_mul_f32_e32 v216, 0.5, v164
	v_pk_mul_f32 v[216:217], v[6:7], v[216:217] op_sel:[1,0] op_sel_hi:[0,0]
	v_pk_fma_f32 v[158:159], v[6:7], v[214:215], v[216:217] neg_lo:[0,0,1] neg_hi:[0,0,1]
	v_pk_fma_f32 v[214:215], v[6:7], v[214:215], v[216:217] op_sel_hi:[1,0,1]
	s_nop 0
	v_mov_b32_e32 v159, v215
	v_pk_mul_f32 v[6:7], v[158:159], s[24:25]
	ds_write_b64 v155, v[6:7] offset:0
	s_waitcnt lgkmcnt(5)
	v_add_f32_e32 v164, v218, v220
	v_mul_f32_e32 v218, 0.5, v164
	v_sub_f32_e32 v164, v219, v221
	v_mul_f32_e32 v220, 0.5, v164
	v_pk_mul_f32 v[220:221], v[18:19], v[220:221] op_sel:[1,0] op_sel_hi:[0,0]
	v_pk_fma_f32 v[158:159], v[18:19], v[218:219], v[220:221] neg_lo:[0,0,1] neg_hi:[0,0,1]
	v_pk_fma_f32 v[218:219], v[18:19], v[218:219], v[220:221] op_sel_hi:[1,0,1]
	s_nop 0
	v_mov_b32_e32 v159, v219
	v_pk_mul_f32 v[18:19], v[158:159], s[24:25]
	ds_write_b64 v155, v[18:19] offset:4352
	ds_read_b64 v[230:231], v160 offset:17408
	ds_read_b64 v[232:233], v161 offset:43520
	ds_read_b64 v[234:235], v160 offset:21760
	ds_read_b64 v[236:237], v162 offset:43520
	s_waitcnt lgkmcnt(8)
	v_add_f32_e32 v164, v222, v224
	v_mul_f32_e32 v222, 0.5, v164
	v_sub_f32_e32 v164, v223, v225
	v_mul_f32_e32 v224, 0.5, v164
	v_pk_mul_f32 v[224:225], v[28:29], v[224:225] op_sel:[1,0] op_sel_hi:[0,0]
	v_pk_fma_f32 v[158:159], v[28:29], v[222:223], v[224:225] neg_lo:[0,0,1] neg_hi:[0,0,1]
	v_pk_fma_f32 v[222:223], v[28:29], v[222:223], v[224:225] op_sel_hi:[1,0,1]
	s_nop 0
	v_mov_b32_e32 v159, v223
	v_pk_mul_f32 v[28:29], v[158:159], s[24:25]
	ds_write_b64 v155, v[28:29] offset:8704
	s_waitcnt lgkmcnt(7)
	v_add_f32_e32 v164, v226, v228
	v_mul_f32_e32 v226, 0.5, v164
	v_sub_f32_e32 v164, v227, v229
	v_mul_f32_e32 v228, 0.5, v164
	v_pk_mul_f32 v[228:229], v[10:11], v[228:229] op_sel:[1,0] op_sel_hi:[0,0]
	v_pk_fma_f32 v[158:159], v[10:11], v[226:227], v[228:229] neg_lo:[0,0,1] neg_hi:[0,0,1]
	v_pk_fma_f32 v[226:227], v[10:11], v[226:227], v[228:229] op_sel_hi:[1,0,1]
	s_nop 0
	v_mov_b32_e32 v159, v227
	v_pk_mul_f32 v[10:11], v[158:159], s[24:25]
	ds_write_b64 v155, v[10:11] offset:13056
	ds_read_b64 v[214:215], v160 offset:26112
	ds_read_b64 v[216:217], v161 offset:34816
	ds_read_b64 v[218:219], v160 offset:30464
	ds_read_b64 v[220:221], v162 offset:34816
	s_waitcnt lgkmcnt(8)
	v_add_f32_e32 v164, v230, v232
	v_mul_f32_e32 v230, 0.5, v164
	v_sub_f32_e32 v164, v231, v233
	v_mul_f32_e32 v232, 0.5, v164
	v_pk_mul_f32 v[232:233], v[26:27], v[232:233] op_sel:[1,0] op_sel_hi:[0,0]
	v_pk_fma_f32 v[158:159], v[26:27], v[230:231], v[232:233] neg_lo:[0,0,1] neg_hi:[0,0,1]
	v_pk_fma_f32 v[230:231], v[26:27], v[230:231], v[232:233] op_sel_hi:[1,0,1]
	s_nop 0
	v_mov_b32_e32 v159, v231
	v_pk_mul_f32 v[26:27], v[158:159], s[24:25]
	ds_write_b64 v155, v[26:27] offset:17408
	s_waitcnt lgkmcnt(7)
	v_add_f32_e32 v164, v234, v236
	v_mul_f32_e32 v234, 0.5, v164
	v_sub_f32_e32 v164, v235, v237
	v_mul_f32_e32 v236, 0.5, v164
	v_pk_mul_f32 v[236:237], v[30:31], v[236:237] op_sel:[1,0] op_sel_hi:[0,0]
	v_pk_fma_f32 v[158:159], v[30:31], v[234:235], v[236:237] neg_lo:[0,0,1] neg_hi:[0,0,1]
	v_pk_fma_f32 v[234:235], v[30:31], v[234:235], v[236:237] op_sel_hi:[1,0,1]
	s_nop 0
	v_mov_b32_e32 v159, v235
	v_pk_mul_f32 v[30:31], v[158:159], s[24:25]
	ds_write_b64 v155, v[30:31] offset:21760
	ds_read_b64 v[222:223], v160 offset:34816
	ds_read_b64 v[224:225], v161 offset:26112
	ds_read_b64 v[226:227], v160 offset:39168
	ds_read_b64 v[228:229], v162 offset:26112
	s_waitcnt lgkmcnt(8)
	v_add_f32_e32 v164, v214, v216
	v_mul_f32_e32 v214, 0.5, v164
	v_sub_f32_e32 v164, v215, v217
	v_mul_f32_e32 v216, 0.5, v164
	v_pk_mul_f32 v[216:217], v[80:81], v[216:217] op_sel:[1,0] op_sel_hi:[0,0]
	v_pk_fma_f32 v[158:159], v[80:81], v[214:215], v[216:217] neg_lo:[0,0,1] neg_hi:[0,0,1]
	v_pk_fma_f32 v[214:215], v[80:81], v[214:215], v[216:217] op_sel_hi:[1,0,1]
	s_nop 0
	v_mov_b32_e32 v159, v215
	v_pk_mul_f32 v[80:81], v[158:159], s[24:25]
	ds_write_b64 v155, v[80:81] offset:26112
	s_waitcnt lgkmcnt(7)
	v_add_f32_e32 v164, v218, v220
	v_mul_f32_e32 v218, 0.5, v164
	v_sub_f32_e32 v164, v219, v221
	v_mul_f32_e32 v220, 0.5, v164
	v_pk_mul_f32 v[220:221], v[12:13], v[220:221] op_sel:[1,0] op_sel_hi:[0,0]
	v_pk_fma_f32 v[158:159], v[12:13], v[218:219], v[220:221] neg_lo:[0,0,1] neg_hi:[0,0,1]
	v_pk_fma_f32 v[218:219], v[12:13], v[218:219], v[220:221] op_sel_hi:[1,0,1]
	s_nop 0
	v_mov_b32_e32 v159, v219
	v_pk_mul_f32 v[12:13], v[158:159], s[24:25]
	ds_write_b64 v155, v[12:13] offset:30464
	ds_read_b64 v[230:231], v160 offset:43520
	ds_read_b64 v[232:233], v161 offset:17408
	ds_read_b64 v[234:235], v160 offset:47872
	ds_read_b64 v[236:237], v162 offset:17408
	s_waitcnt lgkmcnt(8)
	v_add_f32_e32 v164, v222, v224
	v_mul_f32_e32 v222, 0.5, v164
	v_sub_f32_e32 v164, v223, v225
	v_mul_f32_e32 v224, 0.5, v164
	v_pk_mul_f32 v[224:225], v[14:15], v[224:225] op_sel:[1,0] op_sel_hi:[0,0]
	v_pk_fma_f32 v[158:159], v[14:15], v[222:223], v[224:225] neg_lo:[0,0,1] neg_hi:[0,0,1]
	v_pk_fma_f32 v[222:223], v[14:15], v[222:223], v[224:225] op_sel_hi:[1,0,1]
	s_nop 0
	v_mov_b32_e32 v159, v223
	v_pk_mul_f32 v[14:15], v[158:159], s[24:25]
	ds_write_b64 v155, v[14:15] offset:34816
	s_waitcnt lgkmcnt(7)
	v_add_f32_e32 v164, v226, v228
	v_mul_f32_e32 v226, 0.5, v164
	v_sub_f32_e32 v164, v227, v229
	v_mul_f32_e32 v228, 0.5, v164
	v_pk_mul_f32 v[228:229], v[20:21], v[228:229] op_sel:[1,0] op_sel_hi:[0,0]
	v_pk_fma_f32 v[158:159], v[20:21], v[226:227], v[228:229] neg_lo:[0,0,1] neg_hi:[0,0,1]
	v_pk_fma_f32 v[226:227], v[20:21], v[226:227], v[228:229] op_sel_hi:[1,0,1]
	s_nop 0
	v_mov_b32_e32 v159, v227
	v_pk_mul_f32 v[20:21], v[158:159], s[24:25]
	ds_write_b64 v155, v[20:21] offset:39168
	ds_read_b64 v[214:215], v160 offset:52224
	ds_read_b64 v[216:217], v161 offset:8704
	ds_read_b64 v[218:219], v160 offset:56576
	ds_read_b64 v[220:221], v162 offset:8704
	s_waitcnt lgkmcnt(8)
	v_add_f32_e32 v164, v230, v232
	v_mul_f32_e32 v230, 0.5, v164
	v_sub_f32_e32 v164, v231, v233
	v_mul_f32_e32 v232, 0.5, v164
	v_pk_mul_f32 v[232:233], v[22:23], v[232:233] op_sel:[1,0] op_sel_hi:[0,0]
	v_pk_fma_f32 v[158:159], v[22:23], v[230:231], v[232:233] neg_lo:[0,0,1] neg_hi:[0,0,1]
	v_pk_fma_f32 v[230:231], v[22:23], v[230:231], v[232:233] op_sel_hi:[1,0,1]
	s_nop 0
	v_mov_b32_e32 v159, v231
	v_pk_mul_f32 v[22:23], v[158:159], s[24:25]
	ds_write_b64 v155, v[22:23] offset:43520
	s_waitcnt lgkmcnt(7)
	v_add_f32_e32 v164, v234, v236
	v_mul_f32_e32 v234, 0.5, v164
	v_sub_f32_e32 v164, v235, v237
	v_mul_f32_e32 v236, 0.5, v164
	v_pk_mul_f32 v[236:237], v[4:5], v[236:237] op_sel:[1,0] op_sel_hi:[0,0]
	v_pk_fma_f32 v[158:159], v[4:5], v[234:235], v[236:237] neg_lo:[0,0,1] neg_hi:[0,0,1]
	v_pk_fma_f32 v[234:235], v[4:5], v[234:235], v[236:237] op_sel_hi:[1,0,1]
	s_nop 0
	v_mov_b32_e32 v159, v235
	v_pk_mul_f32 v[4:5], v[158:159], s[24:25]
	ds_write_b64 v155, v[4:5] offset:47872
	ds_read_b64 v[222:223], v160 offset:60928
	ds_read_b64 v[224:225], v161 offset:0
	ds_read_b64 v[226:227], v160 offset:65280
	ds_read_b64 v[228:229], v162 offset:0
	s_waitcnt lgkmcnt(8)
	v_add_f32_e32 v164, v214, v216
	v_mul_f32_e32 v214, 0.5, v164
	v_sub_f32_e32 v164, v215, v217
	v_mul_f32_e32 v216, 0.5, v164
	v_pk_mul_f32 v[216:217], v[24:25], v[216:217] op_sel:[1,0] op_sel_hi:[0,0]
	v_pk_fma_f32 v[158:159], v[24:25], v[214:215], v[216:217] neg_lo:[0,0,1] neg_hi:[0,0,1]
	v_pk_fma_f32 v[214:215], v[24:25], v[214:215], v[216:217] op_sel_hi:[1,0,1]
	s_nop 0
	v_mov_b32_e32 v159, v215
	v_pk_mul_f32 v[24:25], v[158:159], s[24:25]
	ds_write_b64 v155, v[24:25] offset:52224
	s_waitcnt lgkmcnt(7)
	v_add_f32_e32 v164, v218, v220
	v_mul_f32_e32 v218, 0.5, v164
	v_sub_f32_e32 v164, v219, v221
	v_mul_f32_e32 v220, 0.5, v164
	v_pk_mul_f32 v[220:221], v[8:9], v[220:221] op_sel:[1,0] op_sel_hi:[0,0]
	v_pk_fma_f32 v[158:159], v[8:9], v[218:219], v[220:221] neg_lo:[0,0,1] neg_hi:[0,0,1]
	v_pk_fma_f32 v[218:219], v[8:9], v[218:219], v[220:221] op_sel_hi:[1,0,1]
	s_nop 0
	v_mov_b32_e32 v159, v219
	v_pk_mul_f32 v[8:9], v[158:159], s[24:25]
	ds_write_b64 v155, v[8:9] offset:56576
	s_waitcnt lgkmcnt(4)
	v_add_f32_e32 v164, v222, v224
	v_mul_f32_e32 v222, 0.5, v164
	v_sub_f32_e32 v164, v223, v225
	v_mul_f32_e32 v224, 0.5, v164
	v_pk_mul_f32 v[224:225], v[16:17], v[224:225] op_sel:[1,0] op_sel_hi:[0,0]
	v_pk_fma_f32 v[158:159], v[16:17], v[222:223], v[224:225] neg_lo:[0,0,1] neg_hi:[0,0,1]
	v_pk_fma_f32 v[222:223], v[16:17], v[222:223], v[224:225] op_sel_hi:[1,0,1]
	s_nop 0
	v_mov_b32_e32 v159, v223
	v_pk_mul_f32 v[16:17], v[158:159], s[24:25]
	ds_write_b64 v155, v[16:17] offset:60928
	s_waitcnt lgkmcnt(3)
	v_add_f32_e32 v164, v226, v228
	v_mul_f32_e32 v226, 0.5, v164
	v_sub_f32_e32 v164, v227, v229
	v_mul_f32_e32 v228, 0.5, v164
	v_pk_mul_f32 v[228:229], v[0:1], v[228:229] op_sel:[1,0] op_sel_hi:[0,0]
	v_pk_fma_f32 v[158:159], v[0:1], v[226:227], v[228:229] neg_lo:[0,0,1] neg_hi:[0,0,1]
	v_pk_fma_f32 v[226:227], v[0:1], v[226:227], v[228:229] op_sel_hi:[1,0,1]
	s_nop 0
	v_mov_b32_e32 v159, v227
	v_pk_mul_f32 v[0:1], v[158:159], s[24:25]
	ds_write_b64 v155, v[0:1] offset:65280
	s_mov_b32 s0, 16
	s_cmp_lg_u32 s0, 16
	s_waitcnt lgkmcnt(0)
	s_barrier
	s_and_saveexec_b64 s[0:1], s[40:41]
	s_cbranch_execz .LBB0_436
	ds_read_b64 v[0:1], v37 offset:2176
	ds_read_b64 v[2:3], v37 offset:4352
	ds_read_b64 v[4:5], v37 offset:6528
	ds_read_b64 v[6:7], v37 offset:8704
	ds_read_b64 v[8:9], v37 offset:10880
	ds_read_b64 v[10:11], v37 offset:13056
	ds_read_b64 v[12:13], v37 offset:15232
	ds_read_b64 v[14:15], v37 offset:17408
	ds_read_b64 v[16:17], v37 offset:19584
	ds_read_b64 v[18:19], v37 offset:21760
	ds_read_b64 v[20:21], v37 offset:23936
	ds_read_b64 v[22:23], v37 offset:26112
	ds_read_b64 v[24:25], v37 offset:34816
	ds_read_b64 v[26:27], v37 offset:36992
	ds_read_b64 v[28:29], v37 offset:39168
	ds_read_b64 v[30:31], v37 offset:41344
	ds_read_b64 v[102:103], v37 offset:43520
	ds_read_b64 v[110:111], v37 offset:45696
	ds_read_b64 v[118:119], v37 offset:47872
	ds_read_b64 v[120:121], v37 offset:50048
	ds_read_b64 v[122:123], v37 offset:52224
	ds_read_b64 v[124:125], v37 offset:54400
	ds_read_b64 v[126:127], v37 offset:56576
	ds_read_b64 v[128:129], v37 offset:58752
	ds_read_b64 v[130:131], v37
	ds_read_b64 v[132:133], v37 offset:60928
	ds_read_b64 v[134:135], v37 offset:63104
	ds_read_b64 v[136:137], v37 offset:65280
	s_mov_b32 s11, s14
	s_waitcnt lgkmcnt(3)
	v_pk_add_f32 v[158:159], v[130:131], v[24:25]
	v_pk_add_f32 v[24:25], v[130:131], v[24:25] neg_lo:[0,1] neg_hi:[0,1]
	v_pk_add_f32 v[130:131], v[0:1], v[26:27]
	v_pk_add_f32 v[0:1], v[0:1], v[26:27] neg_lo:[0,1] neg_hi:[0,1]
	s_mov_b32 s13, s86
	v_pk_mul_f32 v[26:27], v[0:1], s[16:17]
	s_mov_b32 s4, s21
	v_pk_fma_f32 v[0:1], v[0:1], s[6:7], v[26:27] op_sel:[0,0,1] op_sel_hi:[1,0,0]
	v_pk_add_f32 v[26:27], v[2:3], v[28:29]
	v_pk_add_f32 v[2:3], v[2:3], v[28:29] neg_lo:[0,1] neg_hi:[0,1]
	s_mov_b32 s35, s30
	v_pk_mul_f32 v[28:29], v[2:3], s[18:19]
	s_mov_b32 s8, s19
	v_pk_fma_f32 v[2:3], v[2:3], s[30:31], v[28:29] op_sel:[0,0,1] op_sel_hi:[1,0,0]
	v_pk_add_f32 v[28:29], v[4:5], v[30:31]
	v_pk_add_f32 v[4:5], v[4:5], v[30:31] neg_lo:[0,1] neg_hi:[0,1]
	s_mov_b32 s77, s6
	v_pk_mul_f32 v[30:31], v[4:5], s[20:21]
	s_mov_b32 s28, s17
	v_pk_fma_f32 v[4:5], v[4:5], s[86:87], v[30:31] op_sel:[0,0,1] op_sel_hi:[1,0,0]
	v_pk_add_f32 v[30:31], v[6:7], v[102:103]
	v_pk_add_f32 v[6:7], v[6:7], v[102:103] neg_lo:[0,1] neg_hi:[0,1]
	v_add_u32_e32 v47, 0x10780, v37
	v_pk_mul_f32 v[102:103], v[6:7], s[10:11]
	ds_read_b64 v[138:139], v37 offset:28288
	ds_read_b64 v[140:141], v37 offset:30464
	ds_read_b64 v[142:143], v37 offset:32640
	ds_read_b64 v[144:145], v47
	v_pk_fma_f32 v[6:7], v[6:7], s[14:15], v[102:103] op_sel:[0,0,1] op_sel_hi:[1,0,0]
	v_pk_add_f32 v[102:103], v[8:9], v[110:111]
	v_pk_add_f32 v[8:9], v[8:9], v[110:111] neg_lo:[0,1] neg_hi:[0,1]
	s_nop 0
	v_pk_mul_f32 v[110:111], v[8:9], s[12:13]
	s_nop 0
	v_pk_fma_f32 v[8:9], v[8:9], s[4:5], v[110:111] op_sel:[0,0,1] op_sel_hi:[1,0,0]
	v_pk_add_f32 v[110:111], v[10:11], v[118:119]
	v_pk_add_f32 v[10:11], v[10:11], v[118:119] neg_lo:[0,1] neg_hi:[0,1]
	s_nop 0
	v_pk_mul_f32 v[118:119], v[10:11], s[34:35]
	s_nop 0
	v_pk_fma_f32 v[10:11], v[10:11], s[8:9], v[118:119] op_sel:[0,0,1] op_sel_hi:[1,0,0]
	v_pk_add_f32 v[118:119], v[12:13], v[120:121]
	v_pk_add_f32 v[12:13], v[12:13], v[120:121] neg_lo:[0,1] neg_hi:[0,1]
	s_nop 0
	v_pk_mul_f32 v[120:121], v[12:13], s[76:77]
	s_nop 0
	v_pk_fma_f32 v[12:13], v[12:13], s[28:29], v[120:121] op_sel:[0,0,1] op_sel_hi:[1,0,0]
	v_pk_add_f32 v[120:121], v[14:15], v[122:123]
	v_pk_add_f32 v[14:15], v[14:15], v[122:123] neg_lo:[0,1] neg_hi:[0,1]
	v_pk_add_f32 v[122:123], v[16:17], v[124:125]
	v_pk_add_f32 v[16:17], v[16:17], v[124:125] neg_lo:[0,1] neg_hi:[0,1]
	s_nop 0
	v_pk_mul_f32 v[124:125], v[16:17], s[76:77]
	s_nop 0
	v_pk_fma_f32 v[16:17], v[16:17], s[28:29], v[124:125] op_sel:[0,0,1] op_sel_hi:[1,0,0] neg_lo:[1,0,0] neg_hi:[1,0,0]
	v_pk_add_f32 v[124:125], v[18:19], v[126:127]
	v_pk_add_f32 v[18:19], v[18:19], v[126:127] neg_lo:[0,1] neg_hi:[0,1]
	s_nop 0
	v_pk_mul_f32 v[126:127], v[18:19], s[34:35]
	s_nop 0
	v_pk_fma_f32 v[18:19], v[18:19], s[8:9], v[126:127] op_sel:[0,0,1] op_sel_hi:[1,0,0] neg_lo:[1,0,0] neg_hi:[1,0,0]
	v_pk_add_f32 v[126:127], v[20:21], v[128:129]
	v_pk_add_f32 v[20:21], v[20:21], v[128:129] neg_lo:[0,1] neg_hi:[0,1]
	s_nop 0
	v_pk_mul_f32 v[128:129], v[20:21], s[12:13]
	s_nop 0
	v_pk_fma_f32 v[20:21], v[20:21], s[4:5], v[128:129] op_sel:[0,0,1] op_sel_hi:[1,0,0] neg_lo:[1,0,0] neg_hi:[1,0,0]
	s_waitcnt lgkmcnt(6)
	v_pk_add_f32 v[128:129], v[22:23], v[132:133]
	v_pk_add_f32 v[22:23], v[22:23], v[132:133] neg_lo:[0,1] neg_hi:[0,1]
	s_nop 0
	v_pk_mul_f32 v[132:133], v[22:23], s[10:11]
	s_nop 0
	v_pk_fma_f32 v[22:23], v[22:23], s[14:15], v[132:133] op_sel:[0,0,1] op_sel_hi:[1,0,0] neg_lo:[1,0,0] neg_hi:[1,0,0]
	s_waitcnt lgkmcnt(3)
	v_pk_add_f32 v[132:133], v[138:139], v[134:135]
	v_pk_add_f32 v[134:135], v[138:139], v[134:135] neg_lo:[0,1] neg_hi:[0,1]
	s_nop 0
	v_pk_mul_f32 v[138:139], v[134:135], s[20:21]
	s_nop 0
	v_pk_fma_f32 v[134:135], v[134:135], s[86:87], v[138:139] op_sel:[0,0,1] op_sel_hi:[1,0,0] neg_lo:[1,0,0] neg_hi:[1,0,0]
	s_waitcnt lgkmcnt(2)
	v_pk_add_f32 v[138:139], v[140:141], v[136:137]
	v_pk_add_f32 v[136:137], v[140:141], v[136:137] neg_lo:[0,1] neg_hi:[0,1]
	s_nop 0
	v_pk_mul_f32 v[140:141], v[136:137], s[18:19]
	s_nop 0
	v_pk_fma_f32 v[136:137], v[136:137], s[30:31], v[140:141] op_sel:[0,0,1] op_sel_hi:[1,0,0] neg_lo:[1,0,0] neg_hi:[1,0,0]
	s_waitcnt lgkmcnt(0)
	v_pk_add_f32 v[140:141], v[142:143], v[144:145]
	v_pk_add_f32 v[142:143], v[142:143], v[144:145] neg_lo:[0,1] neg_hi:[0,1]
	s_nop 0
	v_pk_mul_f32 v[144:145], v[142:143], s[16:17]
	s_nop 0
	v_pk_fma_f32 v[142:143], v[142:143], s[6:7], v[144:145] op_sel:[0,0,1] op_sel_hi:[1,0,0] neg_lo:[1,0,0] neg_hi:[1,0,0]
	v_pk_add_f32 v[144:145], v[158:159], v[120:121]
	v_pk_add_f32 v[120:121], v[158:159], v[120:121] neg_lo:[0,1] neg_hi:[0,1]
	v_pk_add_f32 v[158:159], v[130:131], v[122:123]
	v_pk_add_f32 v[122:123], v[130:131], v[122:123] neg_lo:[0,1] neg_hi:[0,1]
	s_nop 0
	v_pk_mul_f32 v[130:131], v[122:123], s[18:19]
	s_nop 0
	v_pk_fma_f32 v[122:123], v[122:123], s[30:31], v[130:131] op_sel:[0,0,1] op_sel_hi:[1,0,0]
	v_pk_add_f32 v[130:131], v[26:27], v[124:125]
	v_pk_add_f32 v[26:27], v[26:27], v[124:125] neg_lo:[0,1] neg_hi:[0,1]
	s_nop 0
	v_pk_mul_f32 v[124:125], v[26:27], s[10:11]
	s_nop 0
	v_pk_fma_f32 v[26:27], v[26:27], s[14:15], v[124:125] op_sel:[0,0,1] op_sel_hi:[1,0,0]
	v_pk_add_f32 v[124:125], v[28:29], v[126:127]
	v_pk_add_f32 v[28:29], v[28:29], v[126:127] neg_lo:[0,1] neg_hi:[0,1]
	s_nop 0
	v_pk_mul_f32 v[126:127], v[28:29], s[34:35]
	s_nop 0
	v_pk_fma_f32 v[28:29], v[28:29], s[8:9], v[126:127] op_sel:[0,0,1] op_sel_hi:[1,0,0]
	v_pk_add_f32 v[126:127], v[30:31], v[128:129]
	v_pk_add_f32 v[30:31], v[30:31], v[128:129] neg_lo:[0,1] neg_hi:[0,1]
	v_pk_add_f32 v[128:129], v[102:103], v[132:133]
	v_pk_add_f32 v[102:103], v[102:103], v[132:133] neg_lo:[0,1] neg_hi:[0,1]
	s_nop 0
	v_pk_mul_f32 v[132:133], v[102:103], s[34:35]
	s_nop 0
	v_pk_fma_f32 v[102:103], v[102:103], s[8:9], v[132:133] op_sel:[0,0,1] op_sel_hi:[1,0,0] neg_lo:[1,0,0] neg_hi:[1,0,0]
	v_pk_add_f32 v[132:133], v[110:111], v[138:139]
	v_pk_add_f32 v[110:111], v[110:111], v[138:139] neg_lo:[0,1] neg_hi:[0,1]
	s_nop 0
	v_pk_mul_f32 v[138:139], v[110:111], s[10:11]
	s_nop 0
	v_pk_fma_f32 v[110:111], v[110:111], s[14:15], v[138:139] op_sel:[0,0,1] op_sel_hi:[1,0,0] neg_lo:[1,0,0] neg_hi:[1,0,0]
	v_pk_add_f32 v[138:139], v[118:119], v[140:141]
	v_pk_add_f32 v[118:119], v[118:119], v[140:141] neg_lo:[0,1] neg_hi:[0,1]
	s_nop 0
	v_pk_mul_f32 v[140:141], v[118:119], s[18:19]
	s_nop 0
	v_pk_fma_f32 v[118:119], v[118:119], s[30:31], v[140:141] op_sel:[0,0,1] op_sel_hi:[1,0,0] neg_lo:[1,0,0] neg_hi:[1,0,0]
	v_pk_add_f32 v[140:141], v[24:25], v[14:15] op_sel:[0,1] op_sel_hi:[1,0] neg_hi:[0,1]
	v_pk_add_f32 v[14:15], v[24:25], v[14:15] op_sel:[0,1] op_sel_hi:[1,0] neg_lo:[0,1]
	v_pk_add_f32 v[24:25], v[0:1], v[16:17]
	v_pk_add_f32 v[0:1], v[0:1], v[16:17] neg_lo:[0,1] neg_hi:[0,1]
	s_nop 0
	v_pk_mul_f32 v[16:17], v[0:1], s[18:19]
	s_nop 0
	v_pk_fma_f32 v[0:1], v[0:1], s[30:31], v[16:17] op_sel:[0,0,1] op_sel_hi:[1,0,0]
	v_pk_add_f32 v[16:17], v[2:3], v[18:19]
	v_pk_add_f32 v[2:3], v[2:3], v[18:19] neg_lo:[0,1] neg_hi:[0,1]
	s_nop 0
	v_pk_mul_f32 v[18:19], v[2:3], s[10:11]
	s_nop 0
	v_pk_fma_f32 v[2:3], v[2:3], s[14:15], v[18:19] op_sel:[0,0,1] op_sel_hi:[1,0,0]
	v_pk_add_f32 v[18:19], v[4:5], v[20:21]
	v_pk_add_f32 v[4:5], v[4:5], v[20:21] neg_lo:[0,1] neg_hi:[0,1]
	s_nop 0
	v_pk_mul_f32 v[20:21], v[4:5], s[34:35]
	s_nop 0
	v_pk_fma_f32 v[4:5], v[4:5], s[8:9], v[20:21] op_sel:[0,0,1] op_sel_hi:[1,0,0]
	v_pk_add_f32 v[20:21], v[6:7], v[22:23]
	v_pk_add_f32 v[6:7], v[6:7], v[22:23] neg_lo:[0,1] neg_hi:[0,1]
	v_pk_add_f32 v[22:23], v[8:9], v[134:135]
	v_pk_add_f32 v[8:9], v[8:9], v[134:135] neg_lo:[0,1] neg_hi:[0,1]
	s_nop 0
	v_pk_mul_f32 v[134:135], v[8:9], s[34:35]
	s_nop 0
	v_pk_fma_f32 v[8:9], v[8:9], s[8:9], v[134:135] op_sel:[0,0,1] op_sel_hi:[1,0,0] neg_lo:[1,0,0] neg_hi:[1,0,0]
	v_pk_add_f32 v[134:135], v[10:11], v[136:137]
	v_pk_add_f32 v[10:11], v[10:11], v[136:137] neg_lo:[0,1] neg_hi:[0,1]
	s_nop 0
	v_pk_mul_f32 v[136:137], v[10:11], s[10:11]
	s_nop 0
	v_pk_fma_f32 v[10:11], v[10:11], s[14:15], v[136:137] op_sel:[0,0,1] op_sel_hi:[1,0,0] neg_lo:[1,0,0] neg_hi:[1,0,0]
	v_pk_add_f32 v[136:137], v[12:13], v[142:143]
	v_pk_add_f32 v[12:13], v[12:13], v[142:143] neg_lo:[0,1] neg_hi:[0,1]
	s_nop 0
	v_pk_mul_f32 v[142:143], v[12:13], s[18:19]
	s_nop 0
	v_pk_fma_f32 v[12:13], v[12:13], s[30:31], v[142:143] op_sel:[0,0,1] op_sel_hi:[1,0,0] neg_lo:[1,0,0] neg_hi:[1,0,0]
	v_pk_add_f32 v[142:143], v[144:145], v[126:127]
	v_pk_add_f32 v[126:127], v[144:145], v[126:127] neg_lo:[0,1] neg_hi:[0,1]
	v_pk_add_f32 v[144:145], v[158:159], v[128:129]
	v_pk_add_f32 v[128:129], v[158:159], v[128:129] neg_lo:[0,1] neg_hi:[0,1]
	s_nop 0
	v_pk_mul_f32 v[158:159], v[128:129], s[10:11]
	s_nop 0
	v_pk_fma_f32 v[128:129], v[128:129], s[14:15], v[158:159] op_sel:[0,0,1] op_sel_hi:[1,0,0]
	v_pk_add_f32 v[158:159], v[130:131], v[132:133]
	v_pk_add_f32 v[130:131], v[130:131], v[132:133] neg_lo:[0,1] neg_hi:[0,1]
	v_pk_add_f32 v[132:133], v[124:125], v[138:139]
	v_pk_add_f32 v[124:125], v[124:125], v[138:139] neg_lo:[0,1] neg_hi:[0,1]
	s_nop 0
	v_pk_mul_f32 v[138:139], v[124:125], s[10:11]
	s_nop 0
	v_pk_fma_f32 v[124:125], v[124:125], s[14:15], v[138:139] op_sel:[0,0,1] op_sel_hi:[1,0,0] neg_lo:[1,0,0] neg_hi:[1,0,0]
	v_pk_add_f32 v[138:139], v[120:121], v[30:31] op_sel:[0,1] op_sel_hi:[1,0] neg_hi:[0,1]
	v_pk_add_f32 v[30:31], v[120:121], v[30:31] op_sel:[0,1] op_sel_hi:[1,0] neg_lo:[0,1]
	v_pk_add_f32 v[120:121], v[122:123], v[102:103]
	v_pk_add_f32 v[102:103], v[122:123], v[102:103] neg_lo:[0,1] neg_hi:[0,1]
	v_pk_add_f32 v[160:161], v[128:129], v[124:125]
	v_pk_mul_f32 v[122:123], v[102:103], s[10:11]
	v_pk_add_f32 v[124:125], v[128:129], v[124:125] neg_lo:[0,1] neg_hi:[0,1]
	v_pk_fma_f32 v[102:103], v[102:103], s[14:15], v[122:123] op_sel:[0,0,1] op_sel_hi:[1,0,0]
	v_pk_add_f32 v[122:123], v[26:27], v[110:111]
	v_pk_add_f32 v[26:27], v[26:27], v[110:111] neg_lo:[0,1] neg_hi:[0,1]
	v_pk_add_f32 v[110:111], v[28:29], v[118:119]
	v_pk_add_f32 v[28:29], v[28:29], v[118:119] neg_lo:[0,1] neg_hi:[0,1]
	s_nop 0
	v_pk_mul_f32 v[118:119], v[28:29], s[10:11]
	v_pk_add_f32 v[166:167], v[120:121], v[110:111]
	v_pk_fma_f32 v[28:29], v[28:29], s[14:15], v[118:119] op_sel:[0,0,1] op_sel_hi:[1,0,0] neg_lo:[1,0,0] neg_hi:[1,0,0]
	v_pk_add_f32 v[118:119], v[140:141], v[20:21]
	v_pk_add_f32 v[20:21], v[140:141], v[20:21] neg_lo:[0,1] neg_hi:[0,1]
	v_pk_add_f32 v[140:141], v[24:25], v[22:23]
	v_pk_add_f32 v[22:23], v[24:25], v[22:23] neg_lo:[0,1] neg_hi:[0,1]
	v_pk_add_f32 v[110:111], v[120:121], v[110:111] neg_lo:[0,1] neg_hi:[0,1]
	v_pk_mul_f32 v[24:25], v[22:23], s[10:11]
	v_pk_add_f32 v[168:169], v[30:31], v[26:27] op_sel:[0,1] op_sel_hi:[1,0] neg_hi:[0,1]
	v_pk_fma_f32 v[22:23], v[22:23], s[14:15], v[24:25] op_sel:[0,0,1] op_sel_hi:[1,0,0]
	v_pk_add_f32 v[24:25], v[16:17], v[134:135]
	v_pk_add_f32 v[16:17], v[16:17], v[134:135] neg_lo:[0,1] neg_hi:[0,1]
	v_pk_add_f32 v[134:135], v[18:19], v[136:137]
	v_pk_add_f32 v[18:19], v[18:19], v[136:137] neg_lo:[0,1] neg_hi:[0,1]
	s_nop 0
	v_pk_mul_f32 v[136:137], v[18:19], s[10:11]
	v_pk_add_f32 v[26:27], v[30:31], v[26:27] op_sel:[0,1] op_sel_hi:[1,0] neg_lo:[0,1]
	v_pk_fma_f32 v[18:19], v[18:19], s[14:15], v[136:137] op_sel:[0,0,1] op_sel_hi:[1,0,0] neg_lo:[1,0,0] neg_hi:[1,0,0]
	v_pk_add_f32 v[136:137], v[14:15], v[6:7] op_sel:[0,1] op_sel_hi:[1,0] neg_hi:[0,1]
	v_pk_add_f32 v[6:7], v[14:15], v[6:7] op_sel:[0,1] op_sel_hi:[1,0] neg_lo:[0,1]
	v_pk_add_f32 v[14:15], v[0:1], v[8:9]
	v_pk_add_f32 v[0:1], v[0:1], v[8:9] neg_lo:[0,1] neg_hi:[0,1]
	v_pk_add_f32 v[30:31], v[102:103], v[28:29]
	v_pk_mul_f32 v[8:9], v[0:1], s[10:11]
	v_pk_add_f32 v[28:29], v[102:103], v[28:29] neg_lo:[0,1] neg_hi:[0,1]
	v_pk_fma_f32 v[0:1], v[0:1], s[14:15], v[8:9] op_sel:[0,0,1] op_sel_hi:[1,0,0]
	v_pk_add_f32 v[8:9], v[2:3], v[10:11]
	v_pk_add_f32 v[2:3], v[2:3], v[10:11] neg_lo:[0,1] neg_hi:[0,1]
	v_pk_add_f32 v[10:11], v[4:5], v[12:13]
	v_pk_add_f32 v[4:5], v[4:5], v[12:13] neg_lo:[0,1] neg_hi:[0,1]
	s_nop 0
	v_pk_mul_f32 v[12:13], v[4:5], s[10:11]
	v_pk_add_f32 v[170:171], v[118:119], v[24:25]
	v_pk_fma_f32 v[4:5], v[4:5], s[14:15], v[12:13] op_sel:[0,0,1] op_sel_hi:[1,0,0] neg_lo:[1,0,0] neg_hi:[1,0,0]
	v_pk_add_f32 v[12:13], v[142:143], v[158:159]
	v_pk_add_f32 v[142:143], v[142:143], v[158:159] neg_lo:[0,1] neg_hi:[0,1]
	v_pk_add_f32 v[158:159], v[144:145], v[132:133]
	v_pk_add_f32 v[132:133], v[144:145], v[132:133] neg_lo:[0,1] neg_hi:[0,1]
	v_pk_add_f32 v[182:183], v[118:119], v[24:25] neg_lo:[0,1] neg_hi:[0,1]
	v_pk_add_f32 v[184:185], v[140:141], v[134:135]
	v_pk_add_f32 v[24:25], v[140:141], v[134:135] neg_lo:[0,1] neg_hi:[0,1]
	v_pk_add_f32 v[140:141], v[20:21], v[16:17] op_sel:[0,1] op_sel_hi:[1,0] neg_hi:[0,1]
	v_pk_add_f32 v[186:187], v[20:21], v[16:17] op_sel:[0,1] op_sel_hi:[1,0] neg_lo:[0,1]
	v_pk_add_f32 v[16:17], v[22:23], v[18:19] neg_lo:[0,1] neg_hi:[0,1]
	v_pk_add_f32 v[192:193], v[136:137], v[8:9]
	v_pk_add_f32 v[194:195], v[136:137], v[8:9] neg_lo:[0,1] neg_hi:[0,1]
	v_pk_add_f32 v[8:9], v[14:15], v[10:11] neg_lo:[0,1] neg_hi:[0,1]
	v_pk_add_f32 v[198:199], v[6:7], v[2:3] op_sel:[0,1] op_sel_hi:[1,0] neg_hi:[0,1]
	v_pk_add_f32 v[200:201], v[6:7], v[2:3] op_sel:[0,1] op_sel_hi:[1,0] neg_lo:[0,1]
	v_pk_add_f32 v[2:3], v[0:1], v[4:5]
	v_pk_add_f32 v[0:1], v[0:1], v[4:5] neg_lo:[0,1] neg_hi:[0,1]
	v_pk_add_f32 v[144:145], v[126:127], v[130:131] op_sel:[0,1] op_sel_hi:[1,0] neg_hi:[0,1]
	v_pk_add_f32 v[130:131], v[126:127], v[130:131] op_sel:[0,1] op_sel_hi:[1,0] neg_lo:[0,1]
	v_pk_mul_f32 v[162:163], v[124:125], s[22:23]
	v_pk_add_f32 v[164:165], v[138:139], v[122:123]
	v_pk_add_f32 v[138:139], v[138:139], v[122:123] neg_lo:[0,1] neg_hi:[0,1]
	v_pk_mul_f32 v[102:103], v[28:29], s[22:23]
	v_pk_mul_f32 v[134:135], v[24:25], s[22:23]
	v_pk_add_f32 v[188:189], v[22:23], v[18:19]
	v_pk_mul_f32 v[190:191], v[16:17], s[22:23]
	v_pk_add_f32 v[136:137], v[14:15], v[10:11]
	v_pk_mul_f32 v[196:197], v[8:9], s[22:23]
	v_pk_mul_f32 v[202:203], v[0:1], s[22:23]
	v_pk_add_f32 v[28:29], v[12:13], v[158:159]
	v_pk_add_f32 v[128:129], v[12:13], v[158:159] neg_lo:[0,1] neg_hi:[0,1]
	v_pk_add_f32 v[24:25], v[142:143], v[132:133] op_sel:[0,1] op_sel_hi:[1,0] neg_hi:[0,1]
	v_pk_add_f32 v[126:127], v[142:143], v[132:133] op_sel:[0,1] op_sel_hi:[1,0] neg_lo:[0,1]
	v_pk_add_f32 v[20:21], v[144:145], v[160:161]
	v_pk_add_f32 v[124:125], v[144:145], v[160:161] neg_lo:[0,1] neg_hi:[0,1]
	v_pk_add_f32 v[16:17], v[130:131], v[162:163] op_sel:[0,1] op_sel_hi:[1,0]
	v_pk_add_f32 v[122:123], v[130:131], v[162:163] op_sel:[0,1] op_sel_hi:[1,0] neg_lo:[0,1] neg_hi:[0,1]
	v_pk_add_f32 v[12:13], v[164:165], v[166:167]
	v_pk_add_f32 v[120:121], v[164:165], v[166:167] neg_lo:[0,1] neg_hi:[0,1]
	v_pk_add_f32 v[8:9], v[138:139], v[110:111] op_sel:[0,1] op_sel_hi:[1,0] neg_hi:[0,1]
	v_pk_add_f32 v[118:119], v[138:139], v[110:111] op_sel:[0,1] op_sel_hi:[1,0] neg_lo:[0,1]
	v_pk_add_f32 v[4:5], v[168:169], v[30:31]
	v_pk_add_f32 v[110:111], v[168:169], v[30:31] neg_lo:[0,1] neg_hi:[0,1]
	v_pk_add_f32 v[0:1], v[26:27], v[102:103] op_sel:[0,1] op_sel_hi:[1,0]
	v_pk_add_f32 v[102:103], v[26:27], v[102:103] op_sel:[0,1] op_sel_hi:[1,0] neg_lo:[0,1] neg_hi:[0,1]
	v_pk_add_f32 v[30:31], v[170:171], v[184:185]
	v_pk_add_f32 v[144:145], v[170:171], v[184:185] neg_lo:[0,1] neg_hi:[0,1]
	v_pk_add_f32 v[26:27], v[182:183], v[134:135] op_sel:[0,1] op_sel_hi:[1,0]
	v_pk_add_f32 v[142:143], v[182:183], v[134:135] op_sel:[0,1] op_sel_hi:[1,0] neg_lo:[0,1] neg_hi:[0,1]
	v_pk_add_f32 v[22:23], v[140:141], v[188:189]
	v_pk_add_f32 v[140:141], v[140:141], v[188:189] neg_lo:[0,1] neg_hi:[0,1]
	v_pk_add_f32 v[18:19], v[186:187], v[190:191] op_sel:[0,1] op_sel_hi:[1,0]
	v_pk_add_f32 v[138:139], v[186:187], v[190:191] op_sel:[0,1] op_sel_hi:[1,0] neg_lo:[0,1] neg_hi:[0,1]
	v_pk_add_f32 v[14:15], v[192:193], v[136:137]
	v_pk_add_f32 v[136:137], v[192:193], v[136:137] neg_lo:[0,1] neg_hi:[0,1]
	v_pk_add_f32 v[10:11], v[194:195], v[196:197] op_sel:[0,1] op_sel_hi:[1,0]
	v_pk_add_f32 v[134:135], v[194:195], v[196:197] op_sel:[0,1] op_sel_hi:[1,0] neg_lo:[0,1] neg_hi:[0,1]
	v_pk_add_f32 v[6:7], v[198:199], v[2:3]
	v_pk_add_f32 v[132:133], v[198:199], v[2:3] neg_lo:[0,1] neg_hi:[0,1]
	v_pk_add_f32 v[2:3], v[200:201], v[202:203] op_sel:[0,1] op_sel_hi:[1,0]
	v_pk_add_f32 v[130:131], v[200:201], v[202:203] op_sel:[0,1] op_sel_hi:[1,0] neg_lo:[0,1] neg_hi:[0,1]

.LBB0_485:
	v_add_u32_e32 v160, 0x11000, v155
	v_lshlrev_b32_e32 v161, 3, v154
	v_add_u32_e32 v161, 0x2200, v161
	v_add_u32_e32 v162, 0x11100, v156
	v_cmp_ne_u32_e32 vcc, 0, v32
	v_cndmask_b32_e32 v163, 0, v154, vcc
	v_lshlrev_b32_e32 v163, 3, v163
	v_add_u32_e32 v163, 0x11000, v163
	ds_read_b64 v[214:215], v160 offset:0
	ds_read_b64 v[216:217], v163
	ds_read_b64 v[218:219], v160 offset:4352
	ds_read_b64 v[220:221], v162 offset:60928
	ds_read_b64 v[222:223], v160 offset:8704
	ds_read_b64 v[224:225], v161 offset:52224
	ds_read_b64 v[226:227], v160 offset:13056
	ds_read_b64 v[228:229], v162 offset:52224
	s_waitcnt lgkmcnt(6)
	v_add_f32_e32 v164, v215, v217
	v_sub_f32_e32 v165, v214, v216
	v_mul_f32_e32 v216, 0.5, v164
	v_mul_f32_e32 v214, -0.5, v165
	v_pk_mul_f32 v[214:215], v[6:7], v[214:215] op_sel:[1,0] op_sel_hi:[0,0]
	v_pk_fma_f32 v[158:159], v[6:7], v[216:217], v[214:215] neg_lo:[0,0,1] neg_hi:[0,0,1]
	v_pk_fma_f32 v[216:217], v[6:7], v[216:217], v[214:215] op_sel_hi:[1,0,1]
	s_nop 0
	v_mov_b32_e32 v159, v217
	v_pk_mul_f32 v[6:7], v[158:159], s[24:25]
	ds_write_b64 v155, v[6:7] offset:0
	s_waitcnt lgkmcnt(5)
	v_add_f32_e32 v164, v219, v221
	v_sub_f32_e32 v165, v218, v220
	v_mul_f32_e32 v220, 0.5, v164
	v_mul_f32_e32 v218, -0.5, v165
	v_pk_mul_f32 v[218:219], v[18:19], v[218:219] op_sel:[1,0] op_sel_hi:[0,0]
	v_pk_fma_f32 v[158:159], v[18:19], v[220:221], v[218:219] neg_lo:[0,0,1] neg_hi:[0,0,1]
	v_pk_fma_f32 v[220:221], v[18:19], v[220:221], v[218:219] op_sel_hi:[1,0,1]
	s_nop 0
	v_mov_b32_e32 v159, v221
	v_pk_mul_f32 v[18:19], v[158:159], s[24:25]
	ds_write_b64 v155, v[18:19] offset:4352
	ds_read_b64 v[230:231], v160 offset:17408
	ds_read_b64 v[232:233], v161 offset:43520
	ds_read_b64 v[234:235], v160 offset:21760
	ds_read_b64 v[236:237], v162 offset:43520
	s_waitcnt lgkmcnt(8)
	v_add_f32_e32 v164, v223, v225
	v_sub_f32_e32 v165, v222, v224
	v_mul_f32_e32 v224, 0.5, v164
	v_mul_f32_e32 v222, -0.5, v165
	v_pk_mul_f32 v[222:223], v[28:29], v[222:223] op_sel:[1,0] op_sel_hi:[0,0]
	v_pk_fma_f32 v[158:159], v[28:29], v[224:225], v[222:223] neg_lo:[0,0,1] neg_hi:[0,0,1]
	v_pk_fma_f32 v[224:225], v[28:29], v[224:225], v[222:223] op_sel_hi:[1,0,1]
	s_nop 0
	v_mov_b32_e32 v159, v225
	v_pk_mul_f32 v[28:29], v[158:159], s[24:25]
	ds_write_b64 v155, v[28:29] offset:8704
	s_waitcnt lgkmcnt(7)
	v_add_f32_e32 v164, v227, v229
	v_sub_f32_e32 v165, v226, v228
	v_mul_f32_e32 v228, 0.5, v164
	v_mul_f32_e32 v226, -0.5, v165
	v_pk_mul_f32 v[226:227], v[10:11], v[226:227] op_sel:[1,0] op_sel_hi:[0,0]
	v_pk_fma_f32 v[158:159], v[10:11], v[228:229], v[226:227] neg_lo:[0,0,1] neg_hi:[0,0,1]
	v_pk_fma_f32 v[228:229], v[10:11], v[228:229], v[226:227] op_sel_hi:[1,0,1]
	s_nop 0
	v_mov_b32_e32 v159, v229
	v_pk_mul_f32 v[10:11], v[158:159], s[24:25]
	ds_write_b64 v155, v[10:11] offset:13056
	ds_read_b64 v[214:215], v160 offset:26112
	ds_read_b64 v[216:217], v161 offset:34816
	ds_read_b64 v[218:219], v160 offset:30464
	ds_read_b64 v[220:221], v162 offset:34816
	s_waitcnt lgkmcnt(8)
	v_add_f32_e32 v164, v231, v233
	v_sub_f32_e32 v165, v230, v232
	v_mul_f32_e32 v232, 0.5, v164
	v_mul_f32_e32 v230, -0.5, v165
	v_pk_mul_f32 v[230:231], v[26:27], v[230:231] op_sel:[1,0] op_sel_hi:[0,0]
	v_pk_fma_f32 v[158:159], v[26:27], v[232:233], v[230:231] neg_lo:[0,0,1] neg_hi:[0,0,1]
	v_pk_fma_f32 v[232:233], v[26:27], v[232:233], v[230:231] op_sel_hi:[1,0,1]
	s_nop 0
	v_mov_b32_e32 v159, v233
	v_pk_mul_f32 v[26:27], v[158:159], s[24:25]
	ds_write_b64 v155, v[26:27] offset:17408
	s_waitcnt lgkmcnt(7)
	v_add_f32_e32 v164, v235, v237
	v_sub_f32_e32 v165, v234, v236
	v_mul_f32_e32 v236, 0.5, v164
	v_mul_f32_e32 v234, -0.5, v165
	v_pk_mul_f32 v[234:235], v[30:31], v[234:235] op_sel:[1,0] op_sel_hi:[0,0]
	v_pk_fma_f32 v[158:159], v[30:31], v[236:237], v[234:235] neg_lo:[0,0,1] neg_hi:[0,0,1]
	v_pk_fma_f32 v[236:237], v[30:31], v[236:237], v[234:235] op_sel_hi:[1,0,1]
	s_nop 0
	v_mov_b32_e32 v159, v237
	v_pk_mul_f32 v[30:31], v[158:159], s[24:25]
	ds_write_b64 v155, v[30:31] offset:21760
	ds_read_b64 v[222:223], v160 offset:34816
	ds_read_b64 v[224:225], v161 offset:26112
	ds_read_b64 v[226:227], v160 offset:39168
	ds_read_b64 v[228:229], v162 offset:26112
	s_waitcnt lgkmcnt(8)
	v_add_f32_e32 v164, v215, v217
	v_sub_f32_e32 v165, v214, v216
	v_mul_f32_e32 v216, 0.5, v164
	v_mul_f32_e32 v214, -0.5, v165
	v_pk_mul_f32 v[214:215], v[82:83], v[214:215] op_sel:[1,0] op_sel_hi:[0,0]
	v_pk_fma_f32 v[158:159], v[82:83], v[216:217], v[214:215] neg_lo:[0,0,1] neg_hi:[0,0,1]
	v_pk_fma_f32 v[216:217], v[82:83], v[216:217], v[214:215] op_sel_hi:[1,0,1]
	s_nop 0
	v_mov_b32_e32 v159, v217
	v_pk_mul_f32 v[82:83], v[158:159], s[24:25]
	ds_write_b64 v155, v[82:83] offset:26112
	s_waitcnt lgkmcnt(7)
	v_add_f32_e32 v164, v219, v221
	v_sub_f32_e32 v165, v218, v220
	v_mul_f32_e32 v220, 0.5, v164
	v_mul_f32_e32 v218, -0.5, v165
	v_pk_mul_f32 v[218:219], v[12:13], v[218:219] op_sel:[1,0] op_sel_hi:[0,0]
	v_pk_fma_f32 v[158:159], v[12:13], v[220:221], v[218:219] neg_lo:[0,0,1] neg_hi:[0,0,1]
	v_pk_fma_f32 v[220:221], v[12:13], v[220:221], v[218:219] op_sel_hi:[1,0,1]
	s_nop 0
	v_mov_b32_e32 v159, v221
	v_pk_mul_f32 v[12:13], v[158:159], s[24:25]
	ds_write_b64 v155, v[12:13] offset:30464
	ds_read_b64 v[230:231], v160 offset:43520
	ds_read_b64 v[232:233], v161 offset:17408
	ds_read_b64 v[234:235], v160 offset:47872
	ds_read_b64 v[236:237], v162 offset:17408
	s_waitcnt lgkmcnt(8)
	v_add_f32_e32 v164, v223, v225
	v_sub_f32_e32 v165, v222, v224
	v_mul_f32_e32 v224, 0.5, v164
	v_mul_f32_e32 v222, -0.5, v165
	v_pk_mul_f32 v[222:223], v[14:15], v[222:223] op_sel:[1,0] op_sel_hi:[0,0]
	v_pk_fma_f32 v[158:159], v[14:15], v[224:225], v[222:223] neg_lo:[0,0,1] neg_hi:[0,0,1]
	v_pk_fma_f32 v[224:225], v[14:15], v[224:225], v[222:223] op_sel_hi:[1,0,1]
	s_nop 0
	v_mov_b32_e32 v159, v225
	v_pk_mul_f32 v[14:15], v[158:159], s[24:25]
	ds_write_b64 v155, v[14:15] offset:34816
	s_waitcnt lgkmcnt(7)
	v_add_f32_e32 v164, v227, v229
	v_sub_f32_e32 v165, v226, v228
	v_mul_f32_e32 v228, 0.5, v164
	v_mul_f32_e32 v226, -0.5, v165
	v_pk_mul_f32 v[226:227], v[20:21], v[226:227] op_sel:[1,0] op_sel_hi:[0,0]
	v_pk_fma_f32 v[158:159], v[20:21], v[228:229], v[226:227] neg_lo:[0,0,1] neg_hi:[0,0,1]
	v_pk_fma_f32 v[228:229], v[20:21], v[228:229], v[226:227] op_sel_hi:[1,0,1]
	s_nop 0
	v_mov_b32_e32 v159, v229
	v_pk_mul_f32 v[20:21], v[158:159], s[24:25]
	ds_write_b64 v155, v[20:21] offset:39168
	ds_read_b64 v[214:215], v160 offset:52224
	ds_read_b64 v[216:217], v161 offset:8704
	ds_read_b64 v[218:219], v160 offset:56576
	ds_read_b64 v[220:221], v162 offset:8704
	s_waitcnt lgkmcnt(8)
	v_add_f32_e32 v164, v231, v233
	v_sub_f32_e32 v165, v230, v232
	v_mul_f32_e32 v232, 0.5, v164
	v_mul_f32_e32 v230, -0.5, v165
	v_pk_mul_f32 v[230:231], v[22:23], v[230:231] op_sel:[1,0] op_sel_hi:[0,0]
	v_pk_fma_f32 v[158:159], v[22:23], v[232:233], v[230:231] neg_lo:[0,0,1] neg_hi:[0,0,1]
	v_pk_fma_f32 v[232:233], v[22:23], v[232:233], v[230:231] op_sel_hi:[1,0,1]
	s_nop 0
	v_mov_b32_e32 v159, v233
	v_pk_mul_f32 v[22:23], v[158:159], s[24:25]
	ds_write_b64 v155, v[22:23] offset:43520
	s_waitcnt lgkmcnt(7)
	v_add_f32_e32 v164, v235, v237
	v_sub_f32_e32 v165, v234, v236
	v_mul_f32_e32 v236, 0.5, v164
	v_mul_f32_e32 v234, -0.5, v165
	v_pk_mul_f32 v[234:235], v[4:5], v[234:235] op_sel:[1,0] op_sel_hi:[0,0]
	v_pk_fma_f32 v[158:159], v[4:5], v[236:237], v[234:235] neg_lo:[0,0,1] neg_hi:[0,0,1]
	v_pk_fma_f32 v[236:237], v[4:5], v[236:237], v[234:235] op_sel_hi:[1,0,1]
	s_nop 0
	v_mov_b32_e32 v159, v237
	v_pk_mul_f32 v[4:5], v[158:159], s[24:25]
	ds_write_b64 v155, v[4:5] offset:47872
	ds_read_b64 v[222:223], v160 offset:60928
	ds_read_b64 v[224:225], v161 offset:0
	ds_read_b64 v[226:227], v160 offset:65280
	ds_read_b64 v[228:229], v162 offset:0
	s_waitcnt lgkmcnt(8)
	v_add_f32_e32 v164, v215, v217
	v_sub_f32_e32 v165, v214, v216
	v_mul_f32_e32 v216, 0.5, v164
	v_mul_f32_e32 v214, -0.5, v165
	v_pk_mul_f32 v[214:215], v[24:25], v[214:215] op_sel:[1,0] op_sel_hi:[0,0]
	v_pk_fma_f32 v[158:159], v[24:25], v[216:217], v[214:215] neg_lo:[0,0,1] neg_hi:[0,0,1]
	v_pk_fma_f32 v[216:217], v[24:25], v[216:217], v[214:215] op_sel_hi:[1,0,1]
	s_nop 0
	v_mov_b32_e32 v159, v217
	v_pk_mul_f32 v[24:25], v[158:159], s[24:25]
	ds_write_b64 v155, v[24:25] offset:52224
	s_waitcnt lgkmcnt(7)
	v_add_f32_e32 v164, v219, v221
	v_sub_f32_e32 v165, v218, v220
	v_mul_f32_e32 v220, 0.5, v164
	v_mul_f32_e32 v218, -0.5, v165
	v_pk_mul_f32 v[218:219], v[8:9], v[218:219] op_sel:[1,0] op_sel_hi:[0,0]
	v_pk_fma_f32 v[158:159], v[8:9], v[220:221], v[218:219] neg_lo:[0,0,1] neg_hi:[0,0,1]
	v_pk_fma_f32 v[220:221], v[8:9], v[220:221], v[218:219] op_sel_hi:[1,0,1]
	s_nop 0
	v_mov_b32_e32 v159, v221
	v_pk_mul_f32 v[8:9], v[158:159], s[24:25]
	ds_write_b64 v155, v[8:9] offset:56576
	s_waitcnt lgkmcnt(4)
	v_add_f32_e32 v164, v223, v225
	v_sub_f32_e32 v165, v222, v224
	v_mul_f32_e32 v224, 0.5, v164
	v_mul_f32_e32 v222, -0.5, v165
	v_pk_mul_f32 v[222:223], v[16:17], v[222:223] op_sel:[1,0] op_sel_hi:[0,0]
	v_pk_fma_f32 v[158:159], v[16:17], v[224:225], v[222:223] neg_lo:[0,0,1] neg_hi:[0,0,1]
	v_pk_fma_f32 v[224:225], v[16:17], v[224:225], v[222:223] op_sel_hi:[1,0,1]
	s_nop 0
	v_mov_b32_e32 v159, v225
	v_pk_mul_f32 v[16:17], v[158:159], s[24:25]
	ds_write_b64 v155, v[16:17] offset:60928
	s_waitcnt lgkmcnt(3)
	v_add_f32_e32 v164, v227, v229
	v_sub_f32_e32 v165, v226, v228
	v_mul_f32_e32 v228, 0.5, v164
	v_mul_f32_e32 v226, -0.5, v165
	v_pk_mul_f32 v[226:227], v[0:1], v[226:227] op_sel:[1,0] op_sel_hi:[0,0]
	v_pk_fma_f32 v[158:159], v[0:1], v[228:229], v[226:227] neg_lo:[0,0,1] neg_hi:[0,0,1]
	v_pk_fma_f32 v[228:229], v[0:1], v[228:229], v[226:227] op_sel_hi:[1,0,1]
	s_nop 0
	v_mov_b32_e32 v159, v229
	v_pk_mul_f32 v[0:1], v[158:159], s[24:25]
	ds_write_b64 v155, v[0:1] offset:65280
	s_mov_b32 s0, 16
	s_cmp_lg_u32 s0, 16
	s_waitcnt lgkmcnt(0)
	s_barrier
	s_and_saveexec_b64 s[0:1], s[40:41]
	s_cbranch_execz .LBB0_488
	ds_read_b64 v[0:1], v37 offset:2176
	ds_read_b64 v[2:3], v37 offset:4352
	ds_read_b64 v[4:5], v37 offset:6528
	ds_read_b64 v[6:7], v37 offset:8704
	ds_read_b64 v[8:9], v37 offset:10880
	ds_read_b64 v[10:11], v37 offset:13056
	ds_read_b64 v[12:13], v37 offset:15232
	ds_read_b64 v[14:15], v37 offset:17408
	ds_read_b64 v[16:17], v37 offset:19584
	ds_read_b64 v[18:19], v37 offset:21760
	ds_read_b64 v[20:21], v37 offset:23936
	ds_read_b64 v[22:23], v37 offset:26112
	ds_read_b64 v[24:25], v37 offset:34816
	ds_read_b64 v[26:27], v37 offset:36992
	ds_read_b64 v[28:29], v37 offset:39168
	ds_read_b64 v[30:31], v37 offset:41344
	ds_read_b64 v[82:83], v37 offset:43520
	ds_read_b64 v[84:85], v37 offset:45696
	ds_read_b64 v[118:119], v37 offset:47872
	ds_read_b64 v[120:121], v37 offset:50048
	ds_read_b64 v[122:123], v37 offset:52224
	ds_read_b64 v[124:125], v37 offset:54400
	ds_read_b64 v[126:127], v37 offset:56576
	ds_read_b64 v[128:129], v37 offset:58752
	ds_read_b64 v[130:131], v37
	ds_read_b64 v[132:133], v37 offset:60928
	ds_read_b64 v[134:135], v37 offset:63104
	ds_read_b64 v[136:137], v37 offset:65280
	s_mov_b32 s11, s14
	s_waitcnt lgkmcnt(3)
	v_pk_add_f32 v[158:159], v[130:131], v[24:25]
	v_pk_add_f32 v[24:25], v[130:131], v[24:25] neg_lo:[0,1] neg_hi:[0,1]
	v_pk_add_f32 v[130:131], v[0:1], v[26:27]
	v_pk_add_f32 v[0:1], v[0:1], v[26:27] neg_lo:[0,1] neg_hi:[0,1]
	s_mov_b32 s13, s86
	v_pk_mul_f32 v[26:27], v[0:1], s[16:17]
	s_mov_b32 s4, s21
	v_pk_fma_f32 v[0:1], v[0:1], s[6:7], v[26:27] op_sel:[0,0,1] op_sel_hi:[1,0,0]
	v_pk_add_f32 v[26:27], v[2:3], v[28:29]
	v_pk_add_f32 v[2:3], v[2:3], v[28:29] neg_lo:[0,1] neg_hi:[0,1]
	s_mov_b32 s35, s30
	v_pk_mul_f32 v[28:29], v[2:3], s[18:19]
	s_mov_b32 s8, s19
	v_pk_fma_f32 v[2:3], v[2:3], s[30:31], v[28:29] op_sel:[0,0,1] op_sel_hi:[1,0,0]
	v_pk_add_f32 v[28:29], v[4:5], v[30:31]
	v_pk_add_f32 v[4:5], v[4:5], v[30:31] neg_lo:[0,1] neg_hi:[0,1]
	s_mov_b32 s77, s6
	v_pk_mul_f32 v[30:31], v[4:5], s[20:21]
	s_mov_b32 s28, s17
	v_pk_fma_f32 v[4:5], v[4:5], s[86:87], v[30:31] op_sel:[0,0,1] op_sel_hi:[1,0,0]
	v_pk_add_f32 v[30:31], v[6:7], v[82:83]
	v_pk_add_f32 v[6:7], v[6:7], v[82:83] neg_lo:[0,1] neg_hi:[0,1]
	v_add_u32_e32 v47, 0x10780, v37
	v_pk_mul_f32 v[82:83], v[6:7], s[10:11]
	ds_read_b64 v[138:139], v37 offset:28288
	ds_read_b64 v[140:141], v37 offset:30464
	ds_read_b64 v[142:143], v37 offset:32640
	ds_read_b64 v[144:145], v47
	v_pk_fma_f32 v[6:7], v[6:7], s[14:15], v[82:83] op_sel:[0,0,1] op_sel_hi:[1,0,0]
	v_pk_add_f32 v[82:83], v[8:9], v[84:85]
	v_pk_add_f32 v[8:9], v[8:9], v[84:85] neg_lo:[0,1] neg_hi:[0,1]
	s_nop 0
	v_pk_mul_f32 v[84:85], v[8:9], s[12:13]
	s_nop 0
	v_pk_fma_f32 v[8:9], v[8:9], s[4:5], v[84:85] op_sel:[0,0,1] op_sel_hi:[1,0,0]
	v_pk_add_f32 v[84:85], v[10:11], v[118:119]
	v_pk_add_f32 v[10:11], v[10:11], v[118:119] neg_lo:[0,1] neg_hi:[0,1]
	s_nop 0
	v_pk_mul_f32 v[118:119], v[10:11], s[34:35]
	s_nop 0
	v_pk_fma_f32 v[10:11], v[10:11], s[8:9], v[118:119] op_sel:[0,0,1] op_sel_hi:[1,0,0]
	v_pk_add_f32 v[118:119], v[12:13], v[120:121]
	v_pk_add_f32 v[12:13], v[12:13], v[120:121] neg_lo:[0,1] neg_hi:[0,1]
	s_nop 0
	v_pk_mul_f32 v[120:121], v[12:13], s[76:77]
	s_nop 0
	v_pk_fma_f32 v[12:13], v[12:13], s[28:29], v[120:121] op_sel:[0,0,1] op_sel_hi:[1,0,0]
	v_pk_add_f32 v[120:121], v[14:15], v[122:123]
	v_pk_add_f32 v[14:15], v[14:15], v[122:123] neg_lo:[0,1] neg_hi:[0,1]
	v_pk_add_f32 v[122:123], v[16:17], v[124:125]
	v_pk_add_f32 v[16:17], v[16:17], v[124:125] neg_lo:[0,1] neg_hi:[0,1]
	s_nop 0
	v_pk_mul_f32 v[124:125], v[16:17], s[76:77]
	s_nop 0
	v_pk_fma_f32 v[16:17], v[16:17], s[28:29], v[124:125] op_sel:[0,0,1] op_sel_hi:[1,0,0] neg_lo:[1,0,0] neg_hi:[1,0,0]
	v_pk_add_f32 v[124:125], v[18:19], v[126:127]
	v_pk_add_f32 v[18:19], v[18:19], v[126:127] neg_lo:[0,1] neg_hi:[0,1]
	s_nop 0
	v_pk_mul_f32 v[126:127], v[18:19], s[34:35]
	s_nop 0
	v_pk_fma_f32 v[18:19], v[18:19], s[8:9], v[126:127] op_sel:[0,0,1] op_sel_hi:[1,0,0] neg_lo:[1,0,0] neg_hi:[1,0,0]
	v_pk_add_f32 v[126:127], v[20:21], v[128:129]
	v_pk_add_f32 v[20:21], v[20:21], v[128:129] neg_lo:[0,1] neg_hi:[0,1]
	s_nop 0
	v_pk_mul_f32 v[128:129], v[20:21], s[12:13]
	s_nop 0
	v_pk_fma_f32 v[20:21], v[20:21], s[4:5], v[128:129] op_sel:[0,0,1] op_sel_hi:[1,0,0] neg_lo:[1,0,0] neg_hi:[1,0,0]
	s_waitcnt lgkmcnt(6)
	v_pk_add_f32 v[128:129], v[22:23], v[132:133]
	v_pk_add_f32 v[22:23], v[22:23], v[132:133] neg_lo:[0,1] neg_hi:[0,1]
	s_nop 0
	v_pk_mul_f32 v[132:133], v[22:23], s[10:11]
	s_nop 0
	v_pk_fma_f32 v[22:23], v[22:23], s[14:15], v[132:133] op_sel:[0,0,1] op_sel_hi:[1,0,0] neg_lo:[1,0,0] neg_hi:[1,0,0]
	s_waitcnt lgkmcnt(3)
	v_pk_add_f32 v[132:133], v[138:139], v[134:135]
	v_pk_add_f32 v[134:135], v[138:139], v[134:135] neg_lo:[0,1] neg_hi:[0,1]
	s_nop 0
	v_pk_mul_f32 v[138:139], v[134:135], s[20:21]
	s_nop 0
	v_pk_fma_f32 v[134:135], v[134:135], s[86:87], v[138:139] op_sel:[0,0,1] op_sel_hi:[1,0,0] neg_lo:[1,0,0] neg_hi:[1,0,0]
	s_waitcnt lgkmcnt(2)
	v_pk_add_f32 v[138:139], v[140:141], v[136:137]
	v_pk_add_f32 v[136:137], v[140:141], v[136:137] neg_lo:[0,1] neg_hi:[0,1]
	s_nop 0
	v_pk_mul_f32 v[140:141], v[136:137], s[18:19]
	s_nop 0
	v_pk_fma_f32 v[136:137], v[136:137], s[30:31], v[140:141] op_sel:[0,0,1] op_sel_hi:[1,0,0] neg_lo:[1,0,0] neg_hi:[1,0,0]
	s_waitcnt lgkmcnt(0)
	v_pk_add_f32 v[140:141], v[142:143], v[144:145]
	v_pk_add_f32 v[142:143], v[142:143], v[144:145] neg_lo:[0,1] neg_hi:[0,1]
	s_nop 0
	v_pk_mul_f32 v[144:145], v[142:143], s[16:17]
	s_nop 0
	v_pk_fma_f32 v[142:143], v[142:143], s[6:7], v[144:145] op_sel:[0,0,1] op_sel_hi:[1,0,0] neg_lo:[1,0,0] neg_hi:[1,0,0]
	v_pk_add_f32 v[144:145], v[158:159], v[120:121]
	v_pk_add_f32 v[120:121], v[158:159], v[120:121] neg_lo:[0,1] neg_hi:[0,1]
	v_pk_add_f32 v[158:159], v[130:131], v[122:123]
	v_pk_add_f32 v[122:123], v[130:131], v[122:123] neg_lo:[0,1] neg_hi:[0,1]
	s_nop 0
	v_pk_mul_f32 v[130:131], v[122:123], s[18:19]
	s_nop 0
	v_pk_fma_f32 v[122:123], v[122:123], s[30:31], v[130:131] op_sel:[0,0,1] op_sel_hi:[1,0,0]
	v_pk_add_f32 v[130:131], v[26:27], v[124:125]
	v_pk_add_f32 v[26:27], v[26:27], v[124:125] neg_lo:[0,1] neg_hi:[0,1]
	s_nop 0
	v_pk_mul_f32 v[124:125], v[26:27], s[10:11]
	s_nop 0
	v_pk_fma_f32 v[26:27], v[26:27], s[14:15], v[124:125] op_sel:[0,0,1] op_sel_hi:[1,0,0]
	v_pk_add_f32 v[124:125], v[28:29], v[126:127]
	v_pk_add_f32 v[28:29], v[28:29], v[126:127] neg_lo:[0,1] neg_hi:[0,1]
	s_nop 0
	v_pk_mul_f32 v[126:127], v[28:29], s[34:35]
	s_nop 0
	v_pk_fma_f32 v[28:29], v[28:29], s[8:9], v[126:127] op_sel:[0,0,1] op_sel_hi:[1,0,0]
	v_pk_add_f32 v[126:127], v[30:31], v[128:129]
	v_pk_add_f32 v[30:31], v[30:31], v[128:129] neg_lo:[0,1] neg_hi:[0,1]
	v_pk_add_f32 v[128:129], v[82:83], v[132:133]
	v_pk_add_f32 v[82:83], v[82:83], v[132:133] neg_lo:[0,1] neg_hi:[0,1]
	s_nop 0
	v_pk_mul_f32 v[132:133], v[82:83], s[34:35]
	s_nop 0
	v_pk_fma_f32 v[82:83], v[82:83], s[8:9], v[132:133] op_sel:[0,0,1] op_sel_hi:[1,0,0] neg_lo:[1,0,0] neg_hi:[1,0,0]
	v_pk_add_f32 v[132:133], v[84:85], v[138:139]
	v_pk_add_f32 v[84:85], v[84:85], v[138:139] neg_lo:[0,1] neg_hi:[0,1]
	s_nop 0
	v_pk_mul_f32 v[138:139], v[84:85], s[10:11]
	s_nop 0
	v_pk_fma_f32 v[84:85], v[84:85], s[14:15], v[138:139] op_sel:[0,0,1] op_sel_hi:[1,0,0] neg_lo:[1,0,0] neg_hi:[1,0,0]
	v_pk_add_f32 v[138:139], v[118:119], v[140:141]
	v_pk_add_f32 v[118:119], v[118:119], v[140:141] neg_lo:[0,1] neg_hi:[0,1]
	s_nop 0
	v_pk_mul_f32 v[140:141], v[118:119], s[18:19]
	s_nop 0
	v_pk_fma_f32 v[118:119], v[118:119], s[30:31], v[140:141] op_sel:[0,0,1] op_sel_hi:[1,0,0] neg_lo:[1,0,0] neg_hi:[1,0,0]
	v_pk_add_f32 v[140:141], v[24:25], v[14:15] op_sel:[0,1] op_sel_hi:[1,0] neg_hi:[0,1]
	v_pk_add_f32 v[14:15], v[24:25], v[14:15] op_sel:[0,1] op_sel_hi:[1,0] neg_lo:[0,1]
	v_pk_add_f32 v[24:25], v[0:1], v[16:17]
	v_pk_add_f32 v[0:1], v[0:1], v[16:17] neg_lo:[0,1] neg_hi:[0,1]
	s_nop 0
	v_pk_mul_f32 v[16:17], v[0:1], s[18:19]
	s_nop 0
	v_pk_fma_f32 v[0:1], v[0:1], s[30:31], v[16:17] op_sel:[0,0,1] op_sel_hi:[1,0,0]
	v_pk_add_f32 v[16:17], v[2:3], v[18:19]
	v_pk_add_f32 v[2:3], v[2:3], v[18:19] neg_lo:[0,1] neg_hi:[0,1]
	s_nop 0
	v_pk_mul_f32 v[18:19], v[2:3], s[10:11]
	s_nop 0
	v_pk_fma_f32 v[2:3], v[2:3], s[14:15], v[18:19] op_sel:[0,0,1] op_sel_hi:[1,0,0]
	v_pk_add_f32 v[18:19], v[4:5], v[20:21]
	v_pk_add_f32 v[4:5], v[4:5], v[20:21] neg_lo:[0,1] neg_hi:[0,1]
	s_nop 0
	v_pk_mul_f32 v[20:21], v[4:5], s[34:35]
	s_nop 0
	v_pk_fma_f32 v[4:5], v[4:5], s[8:9], v[20:21] op_sel:[0,0,1] op_sel_hi:[1,0,0]
	v_pk_add_f32 v[20:21], v[6:7], v[22:23]
	v_pk_add_f32 v[6:7], v[6:7], v[22:23] neg_lo:[0,1] neg_hi:[0,1]
	v_pk_add_f32 v[22:23], v[8:9], v[134:135]
	v_pk_add_f32 v[8:9], v[8:9], v[134:135] neg_lo:[0,1] neg_hi:[0,1]
	s_nop 0
	v_pk_mul_f32 v[134:135], v[8:9], s[34:35]
	s_nop 0
	v_pk_fma_f32 v[8:9], v[8:9], s[8:9], v[134:135] op_sel:[0,0,1] op_sel_hi:[1,0,0] neg_lo:[1,0,0] neg_hi:[1,0,0]
	v_pk_add_f32 v[134:135], v[10:11], v[136:137]
	v_pk_add_f32 v[10:11], v[10:11], v[136:137] neg_lo:[0,1] neg_hi:[0,1]
	s_nop 0
	v_pk_mul_f32 v[136:137], v[10:11], s[10:11]
	s_nop 0
	v_pk_fma_f32 v[10:11], v[10:11], s[14:15], v[136:137] op_sel:[0,0,1] op_sel_hi:[1,0,0] neg_lo:[1,0,0] neg_hi:[1,0,0]
	v_pk_add_f32 v[136:137], v[12:13], v[142:143]
	v_pk_add_f32 v[12:13], v[12:13], v[142:143] neg_lo:[0,1] neg_hi:[0,1]
	s_nop 0
	v_pk_mul_f32 v[142:143], v[12:13], s[18:19]
	s_nop 0
	v_pk_fma_f32 v[12:13], v[12:13], s[30:31], v[142:143] op_sel:[0,0,1] op_sel_hi:[1,0,0] neg_lo:[1,0,0] neg_hi:[1,0,0]
	v_pk_add_f32 v[142:143], v[144:145], v[126:127]
	v_pk_add_f32 v[126:127], v[144:145], v[126:127] neg_lo:[0,1] neg_hi:[0,1]
	v_pk_add_f32 v[144:145], v[158:159], v[128:129]
	v_pk_add_f32 v[128:129], v[158:159], v[128:129] neg_lo:[0,1] neg_hi:[0,1]
	s_nop 0
	v_pk_mul_f32 v[158:159], v[128:129], s[10:11]
	s_nop 0
	v_pk_fma_f32 v[128:129], v[128:129], s[14:15], v[158:159] op_sel:[0,0,1] op_sel_hi:[1,0,0]
	v_pk_add_f32 v[158:159], v[130:131], v[132:133]
	v_pk_add_f32 v[130:131], v[130:131], v[132:133] neg_lo:[0,1] neg_hi:[0,1]
	v_pk_add_f32 v[132:133], v[124:125], v[138:139]
	v_pk_add_f32 v[124:125], v[124:125], v[138:139] neg_lo:[0,1] neg_hi:[0,1]
	s_nop 0
	v_pk_mul_f32 v[138:139], v[124:125], s[10:11]
	s_nop 0
	v_pk_fma_f32 v[124:125], v[124:125], s[14:15], v[138:139] op_sel:[0,0,1] op_sel_hi:[1,0,0] neg_lo:[1,0,0] neg_hi:[1,0,0]
	v_pk_add_f32 v[138:139], v[120:121], v[30:31] op_sel:[0,1] op_sel_hi:[1,0] neg_hi:[0,1]
	v_pk_add_f32 v[30:31], v[120:121], v[30:31] op_sel:[0,1] op_sel_hi:[1,0] neg_lo:[0,1]
	v_pk_add_f32 v[120:121], v[122:123], v[82:83]
	v_pk_add_f32 v[82:83], v[122:123], v[82:83] neg_lo:[0,1] neg_hi:[0,1]
	v_pk_add_f32 v[160:161], v[128:129], v[124:125]
	v_pk_mul_f32 v[122:123], v[82:83], s[10:11]
	v_pk_add_f32 v[124:125], v[128:129], v[124:125] neg_lo:[0,1] neg_hi:[0,1]
	v_pk_fma_f32 v[82:83], v[82:83], s[14:15], v[122:123] op_sel:[0,0,1] op_sel_hi:[1,0,0]
	v_pk_add_f32 v[122:123], v[26:27], v[84:85]
	v_pk_add_f32 v[26:27], v[26:27], v[84:85] neg_lo:[0,1] neg_hi:[0,1]
	v_pk_add_f32 v[84:85], v[28:29], v[118:119]
	v_pk_add_f32 v[28:29], v[28:29], v[118:119] neg_lo:[0,1] neg_hi:[0,1]
	s_nop 0
	v_pk_mul_f32 v[118:119], v[28:29], s[10:11]
	v_pk_add_f32 v[166:167], v[120:121], v[84:85]
	v_pk_fma_f32 v[28:29], v[28:29], s[14:15], v[118:119] op_sel:[0,0,1] op_sel_hi:[1,0,0] neg_lo:[1,0,0] neg_hi:[1,0,0]
	v_pk_add_f32 v[118:119], v[140:141], v[20:21]
	v_pk_add_f32 v[20:21], v[140:141], v[20:21] neg_lo:[0,1] neg_hi:[0,1]
	v_pk_add_f32 v[140:141], v[24:25], v[22:23]
	v_pk_add_f32 v[22:23], v[24:25], v[22:23] neg_lo:[0,1] neg_hi:[0,1]
	v_pk_add_f32 v[84:85], v[120:121], v[84:85] neg_lo:[0,1] neg_hi:[0,1]
	v_pk_mul_f32 v[24:25], v[22:23], s[10:11]
	v_pk_add_f32 v[168:169], v[30:31], v[26:27] op_sel:[0,1] op_sel_hi:[1,0] neg_hi:[0,1]
	v_pk_fma_f32 v[22:23], v[22:23], s[14:15], v[24:25] op_sel:[0,0,1] op_sel_hi:[1,0,0]
	v_pk_add_f32 v[24:25], v[16:17], v[134:135]
	v_pk_add_f32 v[16:17], v[16:17], v[134:135] neg_lo:[0,1] neg_hi:[0,1]
	v_pk_add_f32 v[134:135], v[18:19], v[136:137]
	v_pk_add_f32 v[18:19], v[18:19], v[136:137] neg_lo:[0,1] neg_hi:[0,1]
	s_nop 0
	v_pk_mul_f32 v[136:137], v[18:19], s[10:11]
	v_pk_add_f32 v[26:27], v[30:31], v[26:27] op_sel:[0,1] op_sel_hi:[1,0] neg_lo:[0,1]
	v_pk_fma_f32 v[18:19], v[18:19], s[14:15], v[136:137] op_sel:[0,0,1] op_sel_hi:[1,0,0] neg_lo:[1,0,0] neg_hi:[1,0,0]
	v_pk_add_f32 v[136:137], v[14:15], v[6:7] op_sel:[0,1] op_sel_hi:[1,0] neg_hi:[0,1]
	v_pk_add_f32 v[6:7], v[14:15], v[6:7] op_sel:[0,1] op_sel_hi:[1,0] neg_lo:[0,1]
	v_pk_add_f32 v[14:15], v[0:1], v[8:9]
	v_pk_add_f32 v[0:1], v[0:1], v[8:9] neg_lo:[0,1] neg_hi:[0,1]
	v_pk_add_f32 v[30:31], v[82:83], v[28:29]
	v_pk_mul_f32 v[8:9], v[0:1], s[10:11]
	v_pk_add_f32 v[28:29], v[82:83], v[28:29] neg_lo:[0,1] neg_hi:[0,1]
	v_pk_fma_f32 v[0:1], v[0:1], s[14:15], v[8:9] op_sel:[0,0,1] op_sel_hi:[1,0,0]
	v_pk_add_f32 v[8:9], v[2:3], v[10:11]
	v_pk_add_f32 v[2:3], v[2:3], v[10:11] neg_lo:[0,1] neg_hi:[0,1]
	v_pk_add_f32 v[10:11], v[4:5], v[12:13]
	v_pk_add_f32 v[4:5], v[4:5], v[12:13] neg_lo:[0,1] neg_hi:[0,1]
	s_nop 0
	v_pk_mul_f32 v[12:13], v[4:5], s[10:11]
	v_pk_add_f32 v[170:171], v[118:119], v[24:25]
	v_pk_fma_f32 v[4:5], v[4:5], s[14:15], v[12:13] op_sel:[0,0,1] op_sel_hi:[1,0,0] neg_lo:[1,0,0] neg_hi:[1,0,0]
	v_pk_add_f32 v[12:13], v[142:143], v[158:159]
	v_pk_add_f32 v[142:143], v[142:143], v[158:159] neg_lo:[0,1] neg_hi:[0,1]
	v_pk_add_f32 v[158:159], v[144:145], v[132:133]
	v_pk_add_f32 v[132:133], v[144:145], v[132:133] neg_lo:[0,1] neg_hi:[0,1]
	v_pk_add_f32 v[182:183], v[118:119], v[24:25] neg_lo:[0,1] neg_hi:[0,1]
	v_pk_add_f32 v[184:185], v[140:141], v[134:135]
	v_pk_add_f32 v[24:25], v[140:141], v[134:135] neg_lo:[0,1] neg_hi:[0,1]
	v_pk_add_f32 v[140:141], v[20:21], v[16:17] op_sel:[0,1] op_sel_hi:[1,0] neg_hi:[0,1]
	v_pk_add_f32 v[186:187], v[20:21], v[16:17] op_sel:[0,1] op_sel_hi:[1,0] neg_lo:[0,1]
	v_pk_add_f32 v[16:17], v[22:23], v[18:19] neg_lo:[0,1] neg_hi:[0,1]
	v_pk_add_f32 v[192:193], v[136:137], v[8:9]
	v_pk_add_f32 v[194:195], v[136:137], v[8:9] neg_lo:[0,1] neg_hi:[0,1]
	v_pk_add_f32 v[8:9], v[14:15], v[10:11] neg_lo:[0,1] neg_hi:[0,1]
	v_pk_add_f32 v[198:199], v[6:7], v[2:3] op_sel:[0,1] op_sel_hi:[1,0] neg_hi:[0,1]
	v_pk_add_f32 v[200:201], v[6:7], v[2:3] op_sel:[0,1] op_sel_hi:[1,0] neg_lo:[0,1]
	v_pk_add_f32 v[2:3], v[0:1], v[4:5]
	v_pk_add_f32 v[0:1], v[0:1], v[4:5] neg_lo:[0,1] neg_hi:[0,1]
	v_pk_add_f32 v[144:145], v[126:127], v[130:131] op_sel:[0,1] op_sel_hi:[1,0] neg_hi:[0,1]
	v_pk_add_f32 v[130:131], v[126:127], v[130:131] op_sel:[0,1] op_sel_hi:[1,0] neg_lo:[0,1]
	v_pk_mul_f32 v[162:163], v[124:125], s[22:23]
	v_pk_add_f32 v[164:165], v[138:139], v[122:123]
	v_pk_add_f32 v[138:139], v[138:139], v[122:123] neg_lo:[0,1] neg_hi:[0,1]
	v_pk_mul_f32 v[82:83], v[28:29], s[22:23]
	v_pk_mul_f32 v[134:135], v[24:25], s[22:23]
	v_pk_add_f32 v[188:189], v[22:23], v[18:19]
	v_pk_mul_f32 v[190:191], v[16:17], s[22:23]
	v_pk_add_f32 v[136:137], v[14:15], v[10:11]
	v_pk_mul_f32 v[196:197], v[8:9], s[22:23]
	v_pk_mul_f32 v[202:203], v[0:1], s[22:23]
	v_pk_add_f32 v[28:29], v[12:13], v[158:159]
	v_pk_add_f32 v[128:129], v[12:13], v[158:159] neg_lo:[0,1] neg_hi:[0,1]
	v_pk_add_f32 v[24:25], v[142:143], v[132:133] op_sel:[0,1] op_sel_hi:[1,0] neg_hi:[0,1]
	v_pk_add_f32 v[126:127], v[142:143], v[132:133] op_sel:[0,1] op_sel_hi:[1,0] neg_lo:[0,1]
	v_pk_add_f32 v[20:21], v[144:145], v[160:161]
	v_pk_add_f32 v[124:125], v[144:145], v[160:161] neg_lo:[0,1] neg_hi:[0,1]
	v_pk_add_f32 v[16:17], v[130:131], v[162:163] op_sel:[0,1] op_sel_hi:[1,0]
	v_pk_add_f32 v[122:123], v[130:131], v[162:163] op_sel:[0,1] op_sel_hi:[1,0] neg_lo:[0,1] neg_hi:[0,1]
	v_pk_add_f32 v[12:13], v[164:165], v[166:167]
	v_pk_add_f32 v[120:121], v[164:165], v[166:167] neg_lo:[0,1] neg_hi:[0,1]
	v_pk_add_f32 v[8:9], v[138:139], v[84:85] op_sel:[0,1] op_sel_hi:[1,0] neg_hi:[0,1]
	v_pk_add_f32 v[118:119], v[138:139], v[84:85] op_sel:[0,1] op_sel_hi:[1,0] neg_lo:[0,1]
	v_pk_add_f32 v[4:5], v[168:169], v[30:31]
	v_pk_add_f32 v[84:85], v[168:169], v[30:31] neg_lo:[0,1] neg_hi:[0,1]
	v_pk_add_f32 v[0:1], v[26:27], v[82:83] op_sel:[0,1] op_sel_hi:[1,0]
	v_pk_add_f32 v[82:83], v[26:27], v[82:83] op_sel:[0,1] op_sel_hi:[1,0] neg_lo:[0,1] neg_hi:[0,1]
	v_pk_add_f32 v[30:31], v[170:171], v[184:185]
	v_pk_add_f32 v[144:145], v[170:171], v[184:185] neg_lo:[0,1] neg_hi:[0,1]
	v_pk_add_f32 v[26:27], v[182:183], v[134:135] op_sel:[0,1] op_sel_hi:[1,0]
	v_pk_add_f32 v[142:143], v[182:183], v[134:135] op_sel:[0,1] op_sel_hi:[1,0] neg_lo:[0,1] neg_hi:[0,1]
	v_pk_add_f32 v[22:23], v[140:141], v[188:189]
	v_pk_add_f32 v[140:141], v[140:141], v[188:189] neg_lo:[0,1] neg_hi:[0,1]
	v_pk_add_f32 v[18:19], v[186:187], v[190:191] op_sel:[0,1] op_sel_hi:[1,0]
	v_pk_add_f32 v[138:139], v[186:187], v[190:191] op_sel:[0,1] op_sel_hi:[1,0] neg_lo:[0,1] neg_hi:[0,1]
	v_pk_add_f32 v[14:15], v[192:193], v[136:137]
	v_pk_add_f32 v[136:137], v[192:193], v[136:137] neg_lo:[0,1] neg_hi:[0,1]
	v_pk_add_f32 v[10:11], v[194:195], v[196:197] op_sel:[0,1] op_sel_hi:[1,0]
	v_pk_add_f32 v[134:135], v[194:195], v[196:197] op_sel:[0,1] op_sel_hi:[1,0] neg_lo:[0,1] neg_hi:[0,1]
	v_pk_add_f32 v[6:7], v[198:199], v[2:3]
	v_pk_add_f32 v[132:133], v[198:199], v[2:3] neg_lo:[0,1] neg_hi:[0,1]
	v_pk_add_f32 v[2:3], v[200:201], v[202:203] op_sel:[0,1] op_sel_hi:[1,0]
	v_pk_add_f32 v[130:131], v[200:201], v[202:203] op_sel:[0,1] op_sel_hi:[1,0] neg_lo:[0,1] neg_hi:[0,1]

.LBB0_618:
	v_add_u32_e32 v160, 0x11000, v155
	v_lshlrev_b32_e32 v161, 3, v154
	v_add_u32_e32 v161, 0x2200, v161
	v_add_u32_e32 v162, 0x11100, v156
	v_cmp_ne_u32_e32 vcc, 0, v32
	v_cndmask_b32_e32 v163, 0, v154, vcc
	v_lshlrev_b32_e32 v163, 3, v163
	v_add_u32_e32 v163, 0x11000, v163
	ds_read_b64 v[214:215], v160 offset:0
	ds_read_b64 v[216:217], v163
	ds_read_b64 v[218:219], v160 offset:4352
	ds_read_b64 v[220:221], v162 offset:60928
	ds_read_b64 v[222:223], v160 offset:8704
	ds_read_b64 v[224:225], v161 offset:52224
	ds_read_b64 v[226:227], v160 offset:13056
	ds_read_b64 v[228:229], v162 offset:52224
	s_waitcnt lgkmcnt(6)
	v_add_f32_e32 v164, v214, v216
	v_mul_f32_e32 v214, 0.5, v164
	v_sub_f32_e32 v164, v215, v217
	v_mul_f32_e32 v216, 0.5, v164
	v_pk_mul_f32 v[216:217], v[6:7], v[216:217] op_sel:[1,0] op_sel_hi:[0,0]
	v_pk_fma_f32 v[158:159], v[6:7], v[214:215], v[216:217] neg_lo:[0,0,1] neg_hi:[0,0,1]
	v_pk_fma_f32 v[214:215], v[6:7], v[214:215], v[216:217] op_sel_hi:[1,0,1]
	s_nop 0
	v_mov_b32_e32 v159, v215
	v_pk_mul_f32 v[6:7], v[158:159], s[24:25]
	ds_write_b64 v122, v[6:7] offset:0
	s_waitcnt lgkmcnt(5)
	v_add_f32_e32 v164, v218, v220
	v_mul_f32_e32 v218, 0.5, v164
	v_sub_f32_e32 v164, v219, v221
	v_mul_f32_e32 v220, 0.5, v164
	v_pk_mul_f32 v[220:221], v[18:19], v[220:221] op_sel:[1,0] op_sel_hi:[0,0]
	v_pk_fma_f32 v[158:159], v[18:19], v[218:219], v[220:221] neg_lo:[0,0,1] neg_hi:[0,0,1]
	v_pk_fma_f32 v[218:219], v[18:19], v[218:219], v[220:221] op_sel_hi:[1,0,1]
	s_nop 0
	v_mov_b32_e32 v159, v219
	v_pk_mul_f32 v[18:19], v[158:159], s[24:25]
	ds_write_b64 v122, v[18:19] offset:4352
	ds_read_b64 v[230:231], v160 offset:17408
	ds_read_b64 v[232:233], v161 offset:43520
	ds_read_b64 v[234:235], v160 offset:21760
	ds_read_b64 v[236:237], v162 offset:43520
	s_waitcnt lgkmcnt(8)
	v_add_f32_e32 v164, v222, v224
	v_mul_f32_e32 v222, 0.5, v164
	v_sub_f32_e32 v164, v223, v225
	v_mul_f32_e32 v224, 0.5, v164
	v_pk_mul_f32 v[224:225], v[28:29], v[224:225] op_sel:[1,0] op_sel_hi:[0,0]
	v_pk_fma_f32 v[158:159], v[28:29], v[222:223], v[224:225] neg_lo:[0,0,1] neg_hi:[0,0,1]
	v_pk_fma_f32 v[222:223], v[28:29], v[222:223], v[224:225] op_sel_hi:[1,0,1]
	s_nop 0
	v_mov_b32_e32 v159, v223
	v_pk_mul_f32 v[28:29], v[158:159], s[24:25]
	ds_write_b64 v122, v[28:29] offset:8704
	s_waitcnt lgkmcnt(7)
	v_add_f32_e32 v164, v226, v228
	v_mul_f32_e32 v226, 0.5, v164
	v_sub_f32_e32 v164, v227, v229
	v_mul_f32_e32 v228, 0.5, v164
	v_pk_mul_f32 v[228:229], v[10:11], v[228:229] op_sel:[1,0] op_sel_hi:[0,0]
	v_pk_fma_f32 v[158:159], v[10:11], v[226:227], v[228:229] neg_lo:[0,0,1] neg_hi:[0,0,1]
	v_pk_fma_f32 v[226:227], v[10:11], v[226:227], v[228:229] op_sel_hi:[1,0,1]
	s_nop 0
	v_mov_b32_e32 v159, v227
	v_pk_mul_f32 v[10:11], v[158:159], s[24:25]
	ds_write_b64 v122, v[10:11] offset:13056
	ds_read_b64 v[214:215], v160 offset:26112
	ds_read_b64 v[216:217], v161 offset:34816
	ds_read_b64 v[218:219], v160 offset:30464
	ds_read_b64 v[220:221], v162 offset:34816
	s_waitcnt lgkmcnt(8)
	v_add_f32_e32 v164, v230, v232
	v_mul_f32_e32 v230, 0.5, v164
	v_sub_f32_e32 v164, v231, v233
	v_mul_f32_e32 v232, 0.5, v164
	v_pk_mul_f32 v[232:233], v[26:27], v[232:233] op_sel:[1,0] op_sel_hi:[0,0]
	v_pk_fma_f32 v[158:159], v[26:27], v[230:231], v[232:233] neg_lo:[0,0,1] neg_hi:[0,0,1]
	v_pk_fma_f32 v[230:231], v[26:27], v[230:231], v[232:233] op_sel_hi:[1,0,1]
	s_nop 0
	v_mov_b32_e32 v159, v231
	v_pk_mul_f32 v[26:27], v[158:159], s[24:25]
	ds_write_b64 v122, v[26:27] offset:17408
	s_waitcnt lgkmcnt(7)
	v_add_f32_e32 v164, v234, v236
	v_mul_f32_e32 v234, 0.5, v164
	v_sub_f32_e32 v164, v235, v237
	v_mul_f32_e32 v236, 0.5, v164
	v_pk_mul_f32 v[236:237], v[30:31], v[236:237] op_sel:[1,0] op_sel_hi:[0,0]
	v_pk_fma_f32 v[158:159], v[30:31], v[234:235], v[236:237] neg_lo:[0,0,1] neg_hi:[0,0,1]
	v_pk_fma_f32 v[234:235], v[30:31], v[234:235], v[236:237] op_sel_hi:[1,0,1]
	s_nop 0
	v_mov_b32_e32 v159, v235
	v_pk_mul_f32 v[30:31], v[158:159], s[24:25]
	ds_write_b64 v122, v[30:31] offset:21760
	ds_read_b64 v[222:223], v160 offset:34816
	ds_read_b64 v[224:225], v161 offset:26112
	ds_read_b64 v[226:227], v160 offset:39168
	ds_read_b64 v[228:229], v162 offset:26112
	s_waitcnt lgkmcnt(8)
	v_add_f32_e32 v164, v214, v216
	v_mul_f32_e32 v214, 0.5, v164
	v_sub_f32_e32 v164, v215, v217
	v_mul_f32_e32 v216, 0.5, v164
	v_pk_mul_f32 v[216:217], v[86:87], v[216:217] op_sel:[1,0] op_sel_hi:[0,0]
	v_pk_fma_f32 v[158:159], v[86:87], v[214:215], v[216:217] neg_lo:[0,0,1] neg_hi:[0,0,1]
	v_pk_fma_f32 v[214:215], v[86:87], v[214:215], v[216:217] op_sel_hi:[1,0,1]
	s_nop 0
	v_mov_b32_e32 v159, v215
	v_pk_mul_f32 v[86:87], v[158:159], s[24:25]
	ds_write_b64 v122, v[86:87] offset:26112
	s_waitcnt lgkmcnt(7)
	v_add_f32_e32 v164, v218, v220
	v_mul_f32_e32 v218, 0.5, v164
	v_sub_f32_e32 v164, v219, v221
	v_mul_f32_e32 v220, 0.5, v164
	v_pk_mul_f32 v[220:221], v[12:13], v[220:221] op_sel:[1,0] op_sel_hi:[0,0]
	v_pk_fma_f32 v[158:159], v[12:13], v[218:219], v[220:221] neg_lo:[0,0,1] neg_hi:[0,0,1]
	v_pk_fma_f32 v[218:219], v[12:13], v[218:219], v[220:221] op_sel_hi:[1,0,1]
	s_nop 0
	v_mov_b32_e32 v159, v219
	v_pk_mul_f32 v[12:13], v[158:159], s[24:25]
	ds_write_b64 v122, v[12:13] offset:30464
	ds_read_b64 v[230:231], v160 offset:43520
	ds_read_b64 v[232:233], v161 offset:17408
	ds_read_b64 v[234:235], v160 offset:47872
	ds_read_b64 v[236:237], v162 offset:17408
	s_waitcnt lgkmcnt(8)
	v_add_f32_e32 v164, v222, v224
	v_mul_f32_e32 v222, 0.5, v164
	v_sub_f32_e32 v164, v223, v225
	v_mul_f32_e32 v224, 0.5, v164
	v_pk_mul_f32 v[224:225], v[14:15], v[224:225] op_sel:[1,0] op_sel_hi:[0,0]
	v_pk_fma_f32 v[158:159], v[14:15], v[222:223], v[224:225] neg_lo:[0,0,1] neg_hi:[0,0,1]
	v_pk_fma_f32 v[222:223], v[14:15], v[222:223], v[224:225] op_sel_hi:[1,0,1]
	s_nop 0
	v_mov_b32_e32 v159, v223
	v_pk_mul_f32 v[14:15], v[158:159], s[24:25]
	ds_write_b64 v122, v[14:15] offset:34816
	s_waitcnt lgkmcnt(7)
	v_add_f32_e32 v164, v226, v228
	v_mul_f32_e32 v226, 0.5, v164
	v_sub_f32_e32 v164, v227, v229
	v_mul_f32_e32 v228, 0.5, v164
	v_pk_mul_f32 v[228:229], v[20:21], v[228:229] op_sel:[1,0] op_sel_hi:[0,0]
	v_pk_fma_f32 v[158:159], v[20:21], v[226:227], v[228:229] neg_lo:[0,0,1] neg_hi:[0,0,1]
	v_pk_fma_f32 v[226:227], v[20:21], v[226:227], v[228:229] op_sel_hi:[1,0,1]
	s_nop 0
	v_mov_b32_e32 v159, v227
	v_pk_mul_f32 v[20:21], v[158:159], s[24:25]
	ds_write_b64 v122, v[20:21] offset:39168
	ds_read_b64 v[214:215], v160 offset:52224
	ds_read_b64 v[216:217], v161 offset:8704
	ds_read_b64 v[218:219], v160 offset:56576
	ds_read_b64 v[220:221], v162 offset:8704
	s_waitcnt lgkmcnt(8)
	v_add_f32_e32 v164, v230, v232
	v_mul_f32_e32 v230, 0.5, v164
	v_sub_f32_e32 v164, v231, v233
	v_mul_f32_e32 v232, 0.5, v164
	v_pk_mul_f32 v[232:233], v[22:23], v[232:233] op_sel:[1,0] op_sel_hi:[0,0]
	v_pk_fma_f32 v[158:159], v[22:23], v[230:231], v[232:233] neg_lo:[0,0,1] neg_hi:[0,0,1]
	v_pk_fma_f32 v[230:231], v[22:23], v[230:231], v[232:233] op_sel_hi:[1,0,1]
	s_nop 0
	v_mov_b32_e32 v159, v231
	v_pk_mul_f32 v[22:23], v[158:159], s[24:25]
	ds_write_b64 v122, v[22:23] offset:43520
	s_waitcnt lgkmcnt(7)
	v_add_f32_e32 v164, v234, v236
	v_mul_f32_e32 v234, 0.5, v164
	v_sub_f32_e32 v164, v235, v237
	v_mul_f32_e32 v236, 0.5, v164
	v_pk_mul_f32 v[236:237], v[4:5], v[236:237] op_sel:[1,0] op_sel_hi:[0,0]
	v_pk_fma_f32 v[158:159], v[4:5], v[234:235], v[236:237] neg_lo:[0,0,1] neg_hi:[0,0,1]
	v_pk_fma_f32 v[234:235], v[4:5], v[234:235], v[236:237] op_sel_hi:[1,0,1]
	s_nop 0
	v_mov_b32_e32 v159, v235
	v_pk_mul_f32 v[4:5], v[158:159], s[24:25]
	ds_write_b64 v122, v[4:5] offset:47872
	ds_read_b64 v[222:223], v160 offset:60928
	ds_read_b64 v[224:225], v161 offset:0
	ds_read_b64 v[226:227], v160 offset:65280
	ds_read_b64 v[228:229], v162 offset:0
	s_waitcnt lgkmcnt(8)
	v_add_f32_e32 v164, v214, v216
	v_mul_f32_e32 v214, 0.5, v164
	v_sub_f32_e32 v164, v215, v217
	v_mul_f32_e32 v216, 0.5, v164
	v_pk_mul_f32 v[216:217], v[24:25], v[216:217] op_sel:[1,0] op_sel_hi:[0,0]
	v_pk_fma_f32 v[158:159], v[24:25], v[214:215], v[216:217] neg_lo:[0,0,1] neg_hi:[0,0,1]
	v_pk_fma_f32 v[214:215], v[24:25], v[214:215], v[216:217] op_sel_hi:[1,0,1]
	s_nop 0
	v_mov_b32_e32 v159, v215
	v_pk_mul_f32 v[24:25], v[158:159], s[24:25]
	ds_write_b64 v122, v[24:25] offset:52224
	s_waitcnt lgkmcnt(7)
	v_add_f32_e32 v164, v218, v220
	v_mul_f32_e32 v218, 0.5, v164
	v_sub_f32_e32 v164, v219, v221
	v_mul_f32_e32 v220, 0.5, v164
	v_pk_mul_f32 v[220:221], v[8:9], v[220:221] op_sel:[1,0] op_sel_hi:[0,0]
	v_pk_fma_f32 v[158:159], v[8:9], v[218:219], v[220:221] neg_lo:[0,0,1] neg_hi:[0,0,1]
	v_pk_fma_f32 v[218:219], v[8:9], v[218:219], v[220:221] op_sel_hi:[1,0,1]
	s_nop 0
	v_mov_b32_e32 v159, v219
	v_pk_mul_f32 v[8:9], v[158:159], s[24:25]
	ds_write_b64 v122, v[8:9] offset:56576
	s_waitcnt lgkmcnt(4)
	v_add_f32_e32 v164, v222, v224
	v_mul_f32_e32 v222, 0.5, v164
	v_sub_f32_e32 v164, v223, v225
	v_mul_f32_e32 v224, 0.5, v164
	v_pk_mul_f32 v[224:225], v[16:17], v[224:225] op_sel:[1,0] op_sel_hi:[0,0]
	v_pk_fma_f32 v[158:159], v[16:17], v[222:223], v[224:225] neg_lo:[0,0,1] neg_hi:[0,0,1]
	v_pk_fma_f32 v[222:223], v[16:17], v[222:223], v[224:225] op_sel_hi:[1,0,1]
	s_nop 0
	v_mov_b32_e32 v159, v223
	v_pk_mul_f32 v[16:17], v[158:159], s[24:25]
	ds_write_b64 v122, v[16:17] offset:60928
	s_waitcnt lgkmcnt(3)
	v_add_f32_e32 v164, v226, v228
	v_mul_f32_e32 v226, 0.5, v164
	v_sub_f32_e32 v164, v227, v229
	v_mul_f32_e32 v228, 0.5, v164
	v_pk_mul_f32 v[228:229], v[0:1], v[228:229] op_sel:[1,0] op_sel_hi:[0,0]
	v_pk_fma_f32 v[158:159], v[0:1], v[226:227], v[228:229] neg_lo:[0,0,1] neg_hi:[0,0,1]
	v_pk_fma_f32 v[226:227], v[0:1], v[226:227], v[228:229] op_sel_hi:[1,0,1]
	s_nop 0
	v_mov_b32_e32 v159, v227
	v_pk_mul_f32 v[0:1], v[158:159], s[24:25]
	ds_write_b64 v122, v[0:1] offset:65280
	s_mov_b32 s4, 16
	s_cmp_lg_u32 s4, 16
	s_waitcnt lgkmcnt(0)
	s_barrier
	s_and_saveexec_b64 s[28:29], s[40:41]
	s_cbranch_execz .LBB0_621
	ds_read_b64 v[0:1], v153
	ds_read_b64 v[2:3], v153 offset:2176
	ds_read_b64 v[4:5], v153 offset:4352
	ds_read_b64 v[6:7], v153 offset:6528
	ds_read_b64 v[8:9], v153 offset:8704
	ds_read_b64 v[10:11], v153 offset:10880
	ds_read_b64 v[12:13], v153 offset:13056
	ds_read_b64 v[14:15], v153 offset:15232
	ds_read_b64 v[16:17], v153 offset:17408
	ds_read_b64 v[18:19], v153 offset:19584
	ds_read_b64 v[20:21], v153 offset:21760
	ds_read_b64 v[22:23], v153 offset:23936
	ds_read_b64 v[24:25], v153 offset:26112
	ds_read_b64 v[26:27], v153 offset:28288
	ds_read_b64 v[28:29], v153 offset:30464
	ds_read_b64 v[30:31], v153 offset:32640
	ds_read_b64 v[86:87], v153 offset:34816
	ds_read_b64 v[92:93], v153 offset:41344
	ds_read_b64 v[94:95], v153 offset:43520
	ds_read_b64 v[96:97], v153 offset:45696
	ds_read_b64 v[98:99], v153 offset:47872
	ds_read_b64 v[100:101], v153 offset:50048
	ds_read_b64 v[102:103], v153 offset:52224
	ds_read_b64 v[104:105], v153 offset:54400
	ds_read_b64 v[106:107], v153 offset:56576
	ds_read_b64 v[108:109], v153 offset:58752
	ds_read_b64 v[110:111], v153 offset:60928
	ds_read_b64 v[112:113], v153 offset:63104
	ds_read_b64 v[114:115], v153 offset:65280
	ds_read_b64 v[116:117], v153 offset:36992
	ds_read_b64 v[118:119], v153 offset:39168
	ds_read_b64 v[120:121], v33
	s_waitcnt lgkmcnt(14)
	v_pk_add_f32 v[124:125], v[0:1], v[86:87]
	v_pk_add_f32 v[0:1], v[0:1], v[86:87] neg_lo:[0,1] neg_hi:[0,1]
	s_waitcnt lgkmcnt(2)
	v_pk_add_f32 v[86:87], v[2:3], v[116:117]
	v_pk_add_f32 v[2:3], v[2:3], v[116:117] neg_lo:[0,1] neg_hi:[0,1]
	s_mov_b32 s11, s14
	v_pk_mul_f32 v[116:117], v[2:3], s[16:17]
	s_mov_b32 s13, s86
	v_pk_fma_f32 v[2:3], v[2:3], s[6:7], v[116:117] op_sel:[0,0,1] op_sel_hi:[1,0,0]
	s_waitcnt lgkmcnt(1)
	v_pk_add_f32 v[116:117], v[4:5], v[118:119]
	v_pk_add_f32 v[4:5], v[4:5], v[118:119] neg_lo:[0,1] neg_hi:[0,1]
	s_mov_b32 s4, s21
	v_pk_mul_f32 v[118:119], v[4:5], s[18:19]
	s_mov_b32 s35, s30
	v_pk_fma_f32 v[4:5], v[4:5], s[30:31], v[118:119] op_sel:[0,0,1] op_sel_hi:[1,0,0]
	v_pk_add_f32 v[118:119], v[6:7], v[92:93]
	v_pk_add_f32 v[6:7], v[6:7], v[92:93] neg_lo:[0,1] neg_hi:[0,1]
	s_mov_b32 s8, s19
	v_pk_mul_f32 v[92:93], v[6:7], s[20:21]
	s_mov_b32 s77, s6
	v_pk_fma_f32 v[6:7], v[6:7], s[86:87], v[92:93] op_sel:[0,0,1] op_sel_hi:[1,0,0]
	v_pk_add_f32 v[92:93], v[8:9], v[94:95]
	v_pk_add_f32 v[8:9], v[8:9], v[94:95] neg_lo:[0,1] neg_hi:[0,1]
	s_mov_b32 s26, s17
	v_pk_mul_f32 v[94:95], v[8:9], s[10:11]
	s_nop 0
	v_pk_fma_f32 v[8:9], v[8:9], s[14:15], v[94:95] op_sel:[0,0,1] op_sel_hi:[1,0,0]
	v_pk_add_f32 v[94:95], v[10:11], v[96:97]
	v_pk_add_f32 v[10:11], v[10:11], v[96:97] neg_lo:[0,1] neg_hi:[0,1]
	s_nop 0
	v_pk_mul_f32 v[96:97], v[10:11], s[12:13]
	s_nop 0
	v_pk_fma_f32 v[10:11], v[10:11], s[4:5], v[96:97] op_sel:[0,0,1] op_sel_hi:[1,0,0]
	v_pk_add_f32 v[96:97], v[12:13], v[98:99]
	v_pk_add_f32 v[12:13], v[12:13], v[98:99] neg_lo:[0,1] neg_hi:[0,1]
	s_nop 0
	v_pk_mul_f32 v[98:99], v[12:13], s[34:35]
	s_nop 0
	v_pk_fma_f32 v[12:13], v[12:13], s[8:9], v[98:99] op_sel:[0,0,1] op_sel_hi:[1,0,0]
	v_pk_add_f32 v[98:99], v[14:15], v[100:101]
	v_pk_add_f32 v[14:15], v[14:15], v[100:101] neg_lo:[0,1] neg_hi:[0,1]
	s_nop 0
	v_pk_mul_f32 v[100:101], v[14:15], s[76:77]
	s_nop 0
	v_pk_fma_f32 v[14:15], v[14:15], s[26:27], v[100:101] op_sel:[0,0,1] op_sel_hi:[1,0,0]
	v_pk_add_f32 v[100:101], v[16:17], v[102:103]
	v_pk_add_f32 v[16:17], v[16:17], v[102:103] neg_lo:[0,1] neg_hi:[0,1]
	v_pk_add_f32 v[102:103], v[18:19], v[104:105]
	v_pk_add_f32 v[18:19], v[18:19], v[104:105] neg_lo:[0,1] neg_hi:[0,1]
	s_nop 0
	v_pk_mul_f32 v[104:105], v[18:19], s[76:77]
	s_nop 0
	v_pk_fma_f32 v[18:19], v[18:19], s[26:27], v[104:105] op_sel:[0,0,1] op_sel_hi:[1,0,0] neg_lo:[1,0,0] neg_hi:[1,0,0]
	v_pk_add_f32 v[104:105], v[20:21], v[106:107]
	v_pk_add_f32 v[20:21], v[20:21], v[106:107] neg_lo:[0,1] neg_hi:[0,1]
	s_nop 0
	v_pk_mul_f32 v[106:107], v[20:21], s[34:35]
	s_nop 0
	v_pk_fma_f32 v[20:21], v[20:21], s[8:9], v[106:107] op_sel:[0,0,1] op_sel_hi:[1,0,0] neg_lo:[1,0,0] neg_hi:[1,0,0]
	v_pk_add_f32 v[106:107], v[22:23], v[108:109]
	v_pk_add_f32 v[22:23], v[22:23], v[108:109] neg_lo:[0,1] neg_hi:[0,1]
	s_nop 0
	v_pk_mul_f32 v[108:109], v[22:23], s[12:13]
	s_nop 0
	v_pk_fma_f32 v[22:23], v[22:23], s[4:5], v[108:109] op_sel:[0,0,1] op_sel_hi:[1,0,0] neg_lo:[1,0,0] neg_hi:[1,0,0]
	v_pk_add_f32 v[108:109], v[24:25], v[110:111]
	v_pk_add_f32 v[24:25], v[24:25], v[110:111] neg_lo:[0,1] neg_hi:[0,1]
	s_nop 0
	v_pk_mul_f32 v[110:111], v[24:25], s[10:11]
	s_nop 0
	v_pk_fma_f32 v[24:25], v[24:25], s[14:15], v[110:111] op_sel:[0,0,1] op_sel_hi:[1,0,0] neg_lo:[1,0,0] neg_hi:[1,0,0]
	v_pk_add_f32 v[110:111], v[26:27], v[112:113]
	v_pk_add_f32 v[26:27], v[26:27], v[112:113] neg_lo:[0,1] neg_hi:[0,1]
	s_nop 0
	v_pk_mul_f32 v[112:113], v[26:27], s[20:21]
	s_nop 0
	v_pk_fma_f32 v[26:27], v[26:27], s[86:87], v[112:113] op_sel:[0,0,1] op_sel_hi:[1,0,0] neg_lo:[1,0,0] neg_hi:[1,0,0]
	v_pk_add_f32 v[112:113], v[28:29], v[114:115]
	v_pk_add_f32 v[28:29], v[28:29], v[114:115] neg_lo:[0,1] neg_hi:[0,1]
	s_nop 0
	v_pk_mul_f32 v[114:115], v[28:29], s[18:19]
	s_nop 0
	v_pk_fma_f32 v[28:29], v[28:29], s[30:31], v[114:115] op_sel:[0,0,1] op_sel_hi:[1,0,0] neg_lo:[1,0,0] neg_hi:[1,0,0]
	s_waitcnt lgkmcnt(0)
	v_pk_add_f32 v[114:115], v[30:31], v[120:121]
	v_pk_add_f32 v[30:31], v[30:31], v[120:121] neg_lo:[0,1] neg_hi:[0,1]
	s_nop 0
	v_pk_mul_f32 v[120:121], v[30:31], s[16:17]
	s_nop 0
	v_pk_fma_f32 v[30:31], v[30:31], s[6:7], v[120:121] op_sel:[0,0,1] op_sel_hi:[1,0,0] neg_lo:[1,0,0] neg_hi:[1,0,0]
	v_pk_add_f32 v[120:121], v[124:125], v[100:101]
	v_pk_add_f32 v[100:101], v[124:125], v[100:101] neg_lo:[0,1] neg_hi:[0,1]
	v_pk_add_f32 v[124:125], v[86:87], v[102:103]
	v_pk_add_f32 v[86:87], v[86:87], v[102:103] neg_lo:[0,1] neg_hi:[0,1]
	s_nop 0
	v_pk_mul_f32 v[102:103], v[86:87], s[18:19]
	s_nop 0
	v_pk_fma_f32 v[86:87], v[86:87], s[30:31], v[102:103] op_sel:[0,0,1] op_sel_hi:[1,0,0]
	v_pk_add_f32 v[102:103], v[116:117], v[104:105]
	v_pk_add_f32 v[104:105], v[116:117], v[104:105] neg_lo:[0,1] neg_hi:[0,1]
	s_nop 0
	v_pk_mul_f32 v[116:117], v[104:105], s[10:11]
	s_nop 0
	v_pk_fma_f32 v[104:105], v[104:105], s[14:15], v[116:117] op_sel:[0,0,1] op_sel_hi:[1,0,0]
	v_pk_add_f32 v[116:117], v[118:119], v[106:107]
	v_pk_add_f32 v[106:107], v[118:119], v[106:107] neg_lo:[0,1] neg_hi:[0,1]
	s_nop 0
	v_pk_mul_f32 v[118:119], v[106:107], s[34:35]
	s_nop 0
	v_pk_fma_f32 v[106:107], v[106:107], s[8:9], v[118:119] op_sel:[0,0,1] op_sel_hi:[1,0,0]
	v_pk_add_f32 v[118:119], v[92:93], v[108:109]
	v_pk_add_f32 v[92:93], v[92:93], v[108:109] neg_lo:[0,1] neg_hi:[0,1]
	v_pk_add_f32 v[108:109], v[94:95], v[110:111]
	v_pk_add_f32 v[94:95], v[94:95], v[110:111] neg_lo:[0,1] neg_hi:[0,1]
	s_nop 0
	v_pk_mul_f32 v[110:111], v[94:95], s[34:35]
	s_nop 0
	v_pk_fma_f32 v[94:95], v[94:95], s[8:9], v[110:111] op_sel:[0,0,1] op_sel_hi:[1,0,0] neg_lo:[1,0,0] neg_hi:[1,0,0]
	v_pk_add_f32 v[110:111], v[96:97], v[112:113]
	v_pk_add_f32 v[96:97], v[96:97], v[112:113] neg_lo:[0,1] neg_hi:[0,1]
	s_nop 0
	v_pk_mul_f32 v[112:113], v[96:97], s[10:11]
	s_nop 0
	v_pk_fma_f32 v[96:97], v[96:97], s[14:15], v[112:113] op_sel:[0,0,1] op_sel_hi:[1,0,0] neg_lo:[1,0,0] neg_hi:[1,0,0]
	v_pk_add_f32 v[112:113], v[98:99], v[114:115]
	v_pk_add_f32 v[98:99], v[98:99], v[114:115] neg_lo:[0,1] neg_hi:[0,1]
	s_nop 0
	v_pk_mul_f32 v[114:115], v[98:99], s[18:19]
	s_nop 0
	v_pk_fma_f32 v[98:99], v[98:99], s[30:31], v[114:115] op_sel:[0,0,1] op_sel_hi:[1,0,0] neg_lo:[1,0,0] neg_hi:[1,0,0]
	v_pk_add_f32 v[114:115], v[0:1], v[16:17] op_sel:[0,1] op_sel_hi:[1,0] neg_hi:[0,1]
	v_pk_add_f32 v[0:1], v[0:1], v[16:17] op_sel:[0,1] op_sel_hi:[1,0] neg_lo:[0,1]
	v_pk_add_f32 v[16:17], v[2:3], v[18:19]
	v_pk_add_f32 v[2:3], v[2:3], v[18:19] neg_lo:[0,1] neg_hi:[0,1]
	s_nop 0
	v_pk_mul_f32 v[18:19], v[2:3], s[18:19]
	s_nop 0
	v_pk_fma_f32 v[2:3], v[2:3], s[30:31], v[18:19] op_sel:[0,0,1] op_sel_hi:[1,0,0]
	v_pk_add_f32 v[18:19], v[4:5], v[20:21]
	v_pk_add_f32 v[4:5], v[4:5], v[20:21] neg_lo:[0,1] neg_hi:[0,1]
	s_nop 0
	v_pk_mul_f32 v[20:21], v[4:5], s[10:11]
	s_nop 0
	v_pk_fma_f32 v[4:5], v[4:5], s[14:15], v[20:21] op_sel:[0,0,1] op_sel_hi:[1,0,0]
	v_pk_add_f32 v[20:21], v[6:7], v[22:23]
	v_pk_add_f32 v[6:7], v[6:7], v[22:23] neg_lo:[0,1] neg_hi:[0,1]
	s_nop 0
	v_pk_mul_f32 v[22:23], v[6:7], s[34:35]
	s_nop 0
	v_pk_fma_f32 v[6:7], v[6:7], s[8:9], v[22:23] op_sel:[0,0,1] op_sel_hi:[1,0,0]
	v_pk_add_f32 v[22:23], v[8:9], v[24:25]
	v_pk_add_f32 v[8:9], v[8:9], v[24:25] neg_lo:[0,1] neg_hi:[0,1]
	v_pk_add_f32 v[24:25], v[10:11], v[26:27]
	v_pk_add_f32 v[10:11], v[10:11], v[26:27] neg_lo:[0,1] neg_hi:[0,1]
	s_nop 0
	v_pk_mul_f32 v[26:27], v[10:11], s[34:35]
	s_nop 0
	v_pk_fma_f32 v[10:11], v[10:11], s[8:9], v[26:27] op_sel:[0,0,1] op_sel_hi:[1,0,0] neg_lo:[1,0,0] neg_hi:[1,0,0]
	v_pk_add_f32 v[26:27], v[12:13], v[28:29]
	v_pk_add_f32 v[12:13], v[12:13], v[28:29] neg_lo:[0,1] neg_hi:[0,1]
	s_nop 0
	v_pk_mul_f32 v[28:29], v[12:13], s[10:11]
	s_nop 0
	v_pk_fma_f32 v[12:13], v[12:13], s[14:15], v[28:29] op_sel:[0,0,1] op_sel_hi:[1,0,0] neg_lo:[1,0,0] neg_hi:[1,0,0]
	v_pk_add_f32 v[28:29], v[14:15], v[30:31]
	v_pk_add_f32 v[14:15], v[14:15], v[30:31] neg_lo:[0,1] neg_hi:[0,1]
	s_nop 0
	v_pk_mul_f32 v[30:31], v[14:15], s[18:19]
	s_nop 0
	v_pk_fma_f32 v[14:15], v[14:15], s[30:31], v[30:31] op_sel:[0,0,1] op_sel_hi:[1,0,0] neg_lo:[1,0,0] neg_hi:[1,0,0]
	v_pk_add_f32 v[30:31], v[120:121], v[118:119]
	v_pk_add_f32 v[118:119], v[120:121], v[118:119] neg_lo:[0,1] neg_hi:[0,1]
	v_pk_add_f32 v[120:121], v[124:125], v[108:109]
	v_pk_add_f32 v[108:109], v[124:125], v[108:109] neg_lo:[0,1] neg_hi:[0,1]
	s_nop 0
	v_pk_mul_f32 v[124:125], v[108:109], s[10:11]
	s_nop 0
	v_pk_fma_f32 v[108:109], v[108:109], s[14:15], v[124:125] op_sel:[0,0,1] op_sel_hi:[1,0,0]
	v_pk_add_f32 v[124:125], v[102:103], v[110:111]
	v_pk_add_f32 v[102:103], v[102:103], v[110:111] neg_lo:[0,1] neg_hi:[0,1]
	v_pk_add_f32 v[110:111], v[116:117], v[112:113]
	v_pk_add_f32 v[112:113], v[116:117], v[112:113] neg_lo:[0,1] neg_hi:[0,1]
	s_nop 0
	v_pk_mul_f32 v[116:117], v[112:113], s[10:11]
	s_nop 0
	v_pk_fma_f32 v[112:113], v[112:113], s[14:15], v[116:117] op_sel:[0,0,1] op_sel_hi:[1,0,0] neg_lo:[1,0,0] neg_hi:[1,0,0]
	v_pk_add_f32 v[116:117], v[100:101], v[92:93] op_sel:[0,1] op_sel_hi:[1,0] neg_hi:[0,1]
	v_pk_add_f32 v[92:93], v[100:101], v[92:93] op_sel:[0,1] op_sel_hi:[1,0] neg_lo:[0,1]
	v_pk_add_f32 v[100:101], v[86:87], v[94:95]
	v_pk_add_f32 v[86:87], v[86:87], v[94:95] neg_lo:[0,1] neg_hi:[0,1]
	v_pk_add_f32 v[126:127], v[108:109], v[112:113]
	v_pk_mul_f32 v[94:95], v[86:87], s[10:11]
	s_nop 0
	v_pk_fma_f32 v[86:87], v[86:87], s[14:15], v[94:95] op_sel:[0,0,1] op_sel_hi:[1,0,0]
	v_pk_add_f32 v[94:95], v[104:105], v[96:97]
	v_pk_add_f32 v[96:97], v[104:105], v[96:97] neg_lo:[0,1] neg_hi:[0,1]
	v_pk_add_f32 v[104:105], v[106:107], v[98:99]
	v_pk_add_f32 v[98:99], v[106:107], v[98:99] neg_lo:[0,1] neg_hi:[0,1]
	s_nop 0
	v_pk_mul_f32 v[106:107], v[98:99], s[10:11]
	v_pk_add_f32 v[130:131], v[92:93], v[96:97] op_sel:[0,1] op_sel_hi:[1,0] neg_hi:[0,1]
	v_pk_fma_f32 v[98:99], v[98:99], s[14:15], v[106:107] op_sel:[0,0,1] op_sel_hi:[1,0,0] neg_lo:[1,0,0] neg_hi:[1,0,0]
	v_pk_add_f32 v[106:107], v[114:115], v[22:23]
	v_pk_add_f32 v[22:23], v[114:115], v[22:23] neg_lo:[0,1] neg_hi:[0,1]
	v_pk_add_f32 v[114:115], v[16:17], v[24:25]
	v_pk_add_f32 v[16:17], v[16:17], v[24:25] neg_lo:[0,1] neg_hi:[0,1]
	v_pk_add_f32 v[132:133], v[92:93], v[96:97] op_sel:[0,1] op_sel_hi:[1,0] neg_lo:[0,1]
	v_pk_mul_f32 v[24:25], v[16:17], s[10:11]
	v_pk_add_f32 v[92:93], v[86:87], v[98:99]
	v_pk_fma_f32 v[16:17], v[16:17], s[14:15], v[24:25] op_sel:[0,0,1] op_sel_hi:[1,0,0]
	v_pk_add_f32 v[24:25], v[18:19], v[26:27]
	v_pk_add_f32 v[18:19], v[18:19], v[26:27] neg_lo:[0,1] neg_hi:[0,1]
	v_pk_add_f32 v[26:27], v[20:21], v[28:29]
	v_pk_add_f32 v[20:21], v[20:21], v[28:29] neg_lo:[0,1] neg_hi:[0,1]
	s_nop 0
	v_pk_mul_f32 v[28:29], v[20:21], s[10:11]
	v_pk_add_f32 v[86:87], v[86:87], v[98:99] neg_lo:[0,1] neg_hi:[0,1]
	v_pk_fma_f32 v[20:21], v[20:21], s[14:15], v[28:29] op_sel:[0,0,1] op_sel_hi:[1,0,0] neg_lo:[1,0,0] neg_hi:[1,0,0]
	v_pk_add_f32 v[28:29], v[0:1], v[8:9] op_sel:[0,1] op_sel_hi:[1,0] neg_hi:[0,1]
	v_pk_add_f32 v[0:1], v[0:1], v[8:9] op_sel:[0,1] op_sel_hi:[1,0] neg_lo:[0,1]
	v_pk_add_f32 v[8:9], v[2:3], v[10:11]
	v_pk_add_f32 v[2:3], v[2:3], v[10:11] neg_lo:[0,1] neg_hi:[0,1]
	v_pk_add_f32 v[134:135], v[106:107], v[24:25]
	v_pk_mul_f32 v[10:11], v[2:3], s[10:11]
	v_pk_add_f32 v[106:107], v[106:107], v[24:25] neg_lo:[0,1] neg_hi:[0,1]
	v_pk_fma_f32 v[2:3], v[2:3], s[14:15], v[10:11] op_sel:[0,0,1] op_sel_hi:[1,0,0]
	v_pk_add_f32 v[10:11], v[4:5], v[12:13]
	v_pk_add_f32 v[4:5], v[4:5], v[12:13] neg_lo:[0,1] neg_hi:[0,1]
	v_pk_add_f32 v[12:13], v[6:7], v[14:15]
	v_pk_add_f32 v[6:7], v[6:7], v[14:15] neg_lo:[0,1] neg_hi:[0,1]
	s_nop 0
	v_pk_mul_f32 v[14:15], v[6:7], s[10:11]
	v_pk_add_f32 v[24:25], v[114:115], v[26:27] neg_lo:[0,1] neg_hi:[0,1]
	v_pk_fma_f32 v[6:7], v[6:7], s[14:15], v[14:15] op_sel:[0,0,1] op_sel_hi:[1,0,0] neg_lo:[1,0,0] neg_hi:[1,0,0]
	v_pk_add_f32 v[14:15], v[30:31], v[124:125]
	v_pk_add_f32 v[30:31], v[30:31], v[124:125] neg_lo:[0,1] neg_hi:[0,1]
	v_pk_add_f32 v[124:125], v[120:121], v[110:111]
	v_pk_add_f32 v[110:111], v[120:121], v[110:111] neg_lo:[0,1] neg_hi:[0,1]
	v_pk_add_f32 v[120:121], v[118:119], v[102:103] op_sel:[0,1] op_sel_hi:[1,0] neg_hi:[0,1]
	v_pk_add_f32 v[118:119], v[118:119], v[102:103] op_sel:[0,1] op_sel_hi:[1,0] neg_lo:[0,1]
	v_pk_add_f32 v[102:103], v[108:109], v[112:113] neg_lo:[0,1] neg_hi:[0,1]
	v_pk_add_f32 v[112:113], v[116:117], v[94:95]
	v_pk_add_f32 v[94:95], v[116:117], v[94:95] neg_lo:[0,1] neg_hi:[0,1]
	v_pk_add_f32 v[116:117], v[100:101], v[104:105]
	v_pk_add_f32 v[100:101], v[100:101], v[104:105] neg_lo:[0,1] neg_hi:[0,1]
	v_pk_add_f32 v[138:139], v[22:23], v[18:19] op_sel:[0,1] op_sel_hi:[1,0] neg_hi:[0,1]
	v_pk_add_f32 v[140:141], v[22:23], v[18:19] op_sel:[0,1] op_sel_hi:[1,0] neg_lo:[0,1]
	v_pk_add_f32 v[18:19], v[16:17], v[20:21]
	v_pk_add_f32 v[16:17], v[16:17], v[20:21] neg_lo:[0,1] neg_hi:[0,1]
	v_pk_add_f32 v[144:145], v[28:29], v[10:11]
	v_pk_add_f32 v[158:159], v[28:29], v[10:11] neg_lo:[0,1] neg_hi:[0,1]
	v_pk_add_f32 v[10:11], v[8:9], v[12:13]
	v_pk_add_f32 v[8:9], v[8:9], v[12:13] neg_lo:[0,1] neg_hi:[0,1]
	v_pk_add_f32 v[162:163], v[0:1], v[4:5] op_sel:[0,1] op_sel_hi:[1,0] neg_hi:[0,1]
	v_pk_add_f32 v[164:165], v[0:1], v[4:5] op_sel:[0,1] op_sel_hi:[1,0] neg_lo:[0,1]
	v_pk_add_f32 v[0:1], v[2:3], v[6:7] neg_lo:[0,1] neg_hi:[0,1]
	v_pk_mul_f32 v[108:109], v[102:103], s[22:23]
	v_pk_mul_f32 v[128:129], v[100:101], s[22:23]
	v_pk_add_f32 v[136:137], v[114:115], v[26:27]
	v_pk_mul_f32 v[114:115], v[24:25], s[22:23]
	v_pk_mul_f32 v[142:143], v[16:17], s[22:23]
	v_pk_mul_f32 v[160:161], v[8:9], s[22:23]
	v_pk_add_f32 v[166:167], v[2:3], v[6:7]
	v_pk_mul_f32 v[168:169], v[0:1], s[22:23]
	v_pk_add_f32 v[28:29], v[14:15], v[124:125]
	v_pk_add_f32 v[104:105], v[14:15], v[124:125] neg_lo:[0,1] neg_hi:[0,1]
	v_pk_add_f32 v[24:25], v[30:31], v[110:111] op_sel:[0,1] op_sel_hi:[1,0] neg_hi:[0,1]
	v_pk_add_f32 v[102:103], v[30:31], v[110:111] op_sel:[0,1] op_sel_hi:[1,0] neg_lo:[0,1]
	v_pk_add_f32 v[20:21], v[120:121], v[126:127]
	v_pk_add_f32 v[100:101], v[120:121], v[126:127] neg_lo:[0,1] neg_hi:[0,1]
	v_pk_add_f32 v[16:17], v[118:119], v[108:109] op_sel:[0,1] op_sel_hi:[1,0]
	v_pk_add_f32 v[98:99], v[118:119], v[108:109] op_sel:[0,1] op_sel_hi:[1,0] neg_lo:[0,1] neg_hi:[0,1]
	v_pk_add_f32 v[12:13], v[112:113], v[116:117]
	v_pk_add_f32 v[96:97], v[112:113], v[116:117] neg_lo:[0,1] neg_hi:[0,1]
	v_pk_add_f32 v[8:9], v[94:95], v[128:129] op_sel:[0,1] op_sel_hi:[1,0]
	v_pk_add_f32 v[94:95], v[94:95], v[128:129] op_sel:[0,1] op_sel_hi:[1,0] neg_lo:[0,1] neg_hi:[0,1]
	v_pk_add_f32 v[4:5], v[130:131], v[92:93]
	v_pk_add_f32 v[92:93], v[130:131], v[92:93] neg_lo:[0,1] neg_hi:[0,1]
	v_pk_add_f32 v[0:1], v[132:133], v[86:87] op_sel:[0,1] op_sel_hi:[1,0] neg_hi:[0,1]
	v_pk_add_f32 v[86:87], v[132:133], v[86:87] op_sel:[0,1] op_sel_hi:[1,0] neg_lo:[0,1]
	v_pk_add_f32 v[30:31], v[134:135], v[136:137]
	v_pk_add_f32 v[120:121], v[134:135], v[136:137] neg_lo:[0,1] neg_hi:[0,1]
	v_pk_add_f32 v[26:27], v[106:107], v[114:115] op_sel:[0,1] op_sel_hi:[1,0]
	v_pk_add_f32 v[118:119], v[106:107], v[114:115] op_sel:[0,1] op_sel_hi:[1,0] neg_lo:[0,1] neg_hi:[0,1]
	v_pk_add_f32 v[22:23], v[138:139], v[18:19]
	v_pk_add_f32 v[116:117], v[138:139], v[18:19] neg_lo:[0,1] neg_hi:[0,1]
	v_pk_add_f32 v[18:19], v[140:141], v[142:143] op_sel:[0,1] op_sel_hi:[1,0]
	v_pk_add_f32 v[114:115], v[140:141], v[142:143] op_sel:[0,1] op_sel_hi:[1,0] neg_lo:[0,1] neg_hi:[0,1]
	v_pk_add_f32 v[14:15], v[144:145], v[10:11]
	v_pk_add_f32 v[112:113], v[144:145], v[10:11] neg_lo:[0,1] neg_hi:[0,1]
	v_pk_add_f32 v[10:11], v[158:159], v[160:161] op_sel:[0,1] op_sel_hi:[1,0]
	v_pk_add_f32 v[110:111], v[158:159], v[160:161] op_sel:[0,1] op_sel_hi:[1,0] neg_lo:[0,1] neg_hi:[0,1]
	v_pk_add_f32 v[6:7], v[162:163], v[166:167]
	v_pk_add_f32 v[108:109], v[162:163], v[166:167] neg_lo:[0,1] neg_hi:[0,1]
	v_pk_add_f32 v[2:3], v[164:165], v[168:169] op_sel:[0,1] op_sel_hi:[1,0]
	v_pk_add_f32 v[106:107], v[164:165], v[168:169] op_sel:[0,1] op_sel_hi:[1,0] neg_lo:[0,1] neg_hi:[0,1]

.LBB0_670:
	v_add_u32_e32 v160, 0x11000, v155
	v_lshlrev_b32_e32 v161, 3, v154
	v_add_u32_e32 v161, 0x2200, v161
	v_add_u32_e32 v162, 0x11100, v156
	v_cmp_ne_u32_e32 vcc, 0, v32
	v_cndmask_b32_e32 v163, 0, v154, vcc
	v_lshlrev_b32_e32 v163, 3, v163
	v_add_u32_e32 v163, 0x11000, v163
	ds_read_b64 v[214:215], v160 offset:0
	ds_read_b64 v[216:217], v163
	ds_read_b64 v[218:219], v160 offset:4352
	ds_read_b64 v[220:221], v162 offset:60928
	ds_read_b64 v[222:223], v160 offset:8704
	ds_read_b64 v[224:225], v161 offset:52224
	ds_read_b64 v[226:227], v160 offset:13056
	ds_read_b64 v[228:229], v162 offset:52224
	s_waitcnt lgkmcnt(6)
	v_add_f32_e32 v164, v215, v217
	v_sub_f32_e32 v165, v214, v216
	v_mul_f32_e32 v216, 0.5, v164
	v_mul_f32_e32 v214, -0.5, v165
	v_pk_mul_f32 v[214:215], v[6:7], v[214:215] op_sel:[1,0] op_sel_hi:[0,0]
	v_pk_fma_f32 v[158:159], v[6:7], v[216:217], v[214:215] neg_lo:[0,0,1] neg_hi:[0,0,1]
	v_pk_fma_f32 v[216:217], v[6:7], v[216:217], v[214:215] op_sel_hi:[1,0,1]
	s_nop 0
	v_mov_b32_e32 v159, v217
	v_pk_mul_f32 v[6:7], v[158:159], s[24:25]
	ds_write_b64 v155, v[6:7] offset:0
	s_waitcnt lgkmcnt(5)
	v_add_f32_e32 v164, v219, v221
	v_sub_f32_e32 v165, v218, v220
	v_mul_f32_e32 v220, 0.5, v164
	v_mul_f32_e32 v218, -0.5, v165
	v_pk_mul_f32 v[218:219], v[18:19], v[218:219] op_sel:[1,0] op_sel_hi:[0,0]
	v_pk_fma_f32 v[158:159], v[18:19], v[220:221], v[218:219] neg_lo:[0,0,1] neg_hi:[0,0,1]
	v_pk_fma_f32 v[220:221], v[18:19], v[220:221], v[218:219] op_sel_hi:[1,0,1]
	s_nop 0
	v_mov_b32_e32 v159, v221
	v_pk_mul_f32 v[18:19], v[158:159], s[24:25]
	ds_write_b64 v155, v[18:19] offset:4352
	ds_read_b64 v[230:231], v160 offset:17408
	ds_read_b64 v[232:233], v161 offset:43520
	ds_read_b64 v[234:235], v160 offset:21760
	ds_read_b64 v[236:237], v162 offset:43520
	s_waitcnt lgkmcnt(8)
	v_add_f32_e32 v164, v223, v225
	v_sub_f32_e32 v165, v222, v224
	v_mul_f32_e32 v224, 0.5, v164
	v_mul_f32_e32 v222, -0.5, v165
	v_pk_mul_f32 v[222:223], v[28:29], v[222:223] op_sel:[1,0] op_sel_hi:[0,0]
	v_pk_fma_f32 v[158:159], v[28:29], v[224:225], v[222:223] neg_lo:[0,0,1] neg_hi:[0,0,1]
	v_pk_fma_f32 v[224:225], v[28:29], v[224:225], v[222:223] op_sel_hi:[1,0,1]
	s_nop 0
	v_mov_b32_e32 v159, v225
	v_pk_mul_f32 v[28:29], v[158:159], s[24:25]
	ds_write_b64 v155, v[28:29] offset:8704
	s_waitcnt lgkmcnt(7)
	v_add_f32_e32 v164, v227, v229
	v_sub_f32_e32 v165, v226, v228
	v_mul_f32_e32 v228, 0.5, v164
	v_mul_f32_e32 v226, -0.5, v165
	v_pk_mul_f32 v[226:227], v[10:11], v[226:227] op_sel:[1,0] op_sel_hi:[0,0]
	v_pk_fma_f32 v[158:159], v[10:11], v[228:229], v[226:227] neg_lo:[0,0,1] neg_hi:[0,0,1]
	v_pk_fma_f32 v[228:229], v[10:11], v[228:229], v[226:227] op_sel_hi:[1,0,1]
	s_nop 0
	v_mov_b32_e32 v159, v229
	v_pk_mul_f32 v[10:11], v[158:159], s[24:25]
	ds_write_b64 v155, v[10:11] offset:13056
	ds_read_b64 v[214:215], v160 offset:26112
	ds_read_b64 v[216:217], v161 offset:34816
	ds_read_b64 v[218:219], v160 offset:30464
	ds_read_b64 v[220:221], v162 offset:34816
	s_waitcnt lgkmcnt(8)
	v_add_f32_e32 v164, v231, v233
	v_sub_f32_e32 v165, v230, v232
	v_mul_f32_e32 v232, 0.5, v164
	v_mul_f32_e32 v230, -0.5, v165
	v_pk_mul_f32 v[230:231], v[26:27], v[230:231] op_sel:[1,0] op_sel_hi:[0,0]
	v_pk_fma_f32 v[158:159], v[26:27], v[232:233], v[230:231] neg_lo:[0,0,1] neg_hi:[0,0,1]
	v_pk_fma_f32 v[232:233], v[26:27], v[232:233], v[230:231] op_sel_hi:[1,0,1]
	s_nop 0
	v_mov_b32_e32 v159, v233
	v_pk_mul_f32 v[26:27], v[158:159], s[24:25]
	ds_write_b64 v155, v[26:27] offset:17408
	s_waitcnt lgkmcnt(7)
	v_add_f32_e32 v164, v235, v237
	v_sub_f32_e32 v165, v234, v236
	v_mul_f32_e32 v236, 0.5, v164
	v_mul_f32_e32 v234, -0.5, v165
	v_pk_mul_f32 v[234:235], v[30:31], v[234:235] op_sel:[1,0] op_sel_hi:[0,0]
	v_pk_fma_f32 v[158:159], v[30:31], v[236:237], v[234:235] neg_lo:[0,0,1] neg_hi:[0,0,1]
	v_pk_fma_f32 v[236:237], v[30:31], v[236:237], v[234:235] op_sel_hi:[1,0,1]
	s_nop 0
	v_mov_b32_e32 v159, v237
	v_pk_mul_f32 v[30:31], v[158:159], s[24:25]
	ds_write_b64 v155, v[30:31] offset:21760
	ds_read_b64 v[222:223], v160 offset:34816
	ds_read_b64 v[224:225], v161 offset:26112
	ds_read_b64 v[226:227], v160 offset:39168
	ds_read_b64 v[228:229], v162 offset:26112
	s_waitcnt lgkmcnt(8)
	v_add_f32_e32 v164, v215, v217
	v_sub_f32_e32 v165, v214, v216
	v_mul_f32_e32 v216, 0.5, v164
	v_mul_f32_e32 v214, -0.5, v165
	v_pk_mul_f32 v[214:215], v[58:59], v[214:215] op_sel:[1,0] op_sel_hi:[0,0]
	v_pk_fma_f32 v[158:159], v[58:59], v[216:217], v[214:215] neg_lo:[0,0,1] neg_hi:[0,0,1]
	v_pk_fma_f32 v[216:217], v[58:59], v[216:217], v[214:215] op_sel_hi:[1,0,1]
	s_nop 0
	v_mov_b32_e32 v159, v217
	v_pk_mul_f32 v[58:59], v[158:159], s[24:25]
	ds_write_b64 v155, v[58:59] offset:26112
	s_waitcnt lgkmcnt(7)
	v_add_f32_e32 v164, v219, v221
	v_sub_f32_e32 v165, v218, v220
	v_mul_f32_e32 v220, 0.5, v164
	v_mul_f32_e32 v218, -0.5, v165
	v_pk_mul_f32 v[218:219], v[12:13], v[218:219] op_sel:[1,0] op_sel_hi:[0,0]
	v_pk_fma_f32 v[158:159], v[12:13], v[220:221], v[218:219] neg_lo:[0,0,1] neg_hi:[0,0,1]
	v_pk_fma_f32 v[220:221], v[12:13], v[220:221], v[218:219] op_sel_hi:[1,0,1]
	s_nop 0
	v_mov_b32_e32 v159, v221
	v_pk_mul_f32 v[12:13], v[158:159], s[24:25]
	ds_write_b64 v155, v[12:13] offset:30464
	ds_read_b64 v[230:231], v160 offset:43520
	ds_read_b64 v[232:233], v161 offset:17408
	ds_read_b64 v[234:235], v160 offset:47872
	ds_read_b64 v[236:237], v162 offset:17408
	s_waitcnt lgkmcnt(8)
	v_add_f32_e32 v164, v223, v225
	v_sub_f32_e32 v165, v222, v224
	v_mul_f32_e32 v224, 0.5, v164
	v_mul_f32_e32 v222, -0.5, v165
	v_pk_mul_f32 v[222:223], v[14:15], v[222:223] op_sel:[1,0] op_sel_hi:[0,0]
	v_pk_fma_f32 v[158:159], v[14:15], v[224:225], v[222:223] neg_lo:[0,0,1] neg_hi:[0,0,1]
	v_pk_fma_f32 v[224:225], v[14:15], v[224:225], v[222:223] op_sel_hi:[1,0,1]
	s_nop 0
	v_mov_b32_e32 v159, v225
	v_pk_mul_f32 v[14:15], v[158:159], s[24:25]
	ds_write_b64 v155, v[14:15] offset:34816
	s_waitcnt lgkmcnt(7)
	v_add_f32_e32 v164, v227, v229
	v_sub_f32_e32 v165, v226, v228
	v_mul_f32_e32 v228, 0.5, v164
	v_mul_f32_e32 v226, -0.5, v165
	v_pk_mul_f32 v[226:227], v[20:21], v[226:227] op_sel:[1,0] op_sel_hi:[0,0]
	v_pk_fma_f32 v[158:159], v[20:21], v[228:229], v[226:227] neg_lo:[0,0,1] neg_hi:[0,0,1]
	v_pk_fma_f32 v[228:229], v[20:21], v[228:229], v[226:227] op_sel_hi:[1,0,1]
	s_nop 0
	v_mov_b32_e32 v159, v229
	v_pk_mul_f32 v[20:21], v[158:159], s[24:25]
	ds_write_b64 v155, v[20:21] offset:39168
	ds_read_b64 v[214:215], v160 offset:52224
	ds_read_b64 v[216:217], v161 offset:8704
	ds_read_b64 v[218:219], v160 offset:56576
	ds_read_b64 v[220:221], v162 offset:8704
	s_waitcnt lgkmcnt(8)
	v_add_f32_e32 v164, v231, v233
	v_sub_f32_e32 v165, v230, v232
	v_mul_f32_e32 v232, 0.5, v164
	v_mul_f32_e32 v230, -0.5, v165
	v_pk_mul_f32 v[230:231], v[22:23], v[230:231] op_sel:[1,0] op_sel_hi:[0,0]
	v_pk_fma_f32 v[158:159], v[22:23], v[232:233], v[230:231] neg_lo:[0,0,1] neg_hi:[0,0,1]
	v_pk_fma_f32 v[232:233], v[22:23], v[232:233], v[230:231] op_sel_hi:[1,0,1]
	s_nop 0
	v_mov_b32_e32 v159, v233
	v_pk_mul_f32 v[22:23], v[158:159], s[24:25]
	ds_write_b64 v155, v[22:23] offset:43520
	s_waitcnt lgkmcnt(7)
	v_add_f32_e32 v164, v235, v237
	v_sub_f32_e32 v165, v234, v236
	v_mul_f32_e32 v236, 0.5, v164
	v_mul_f32_e32 v234, -0.5, v165
	v_pk_mul_f32 v[234:235], v[4:5], v[234:235] op_sel:[1,0] op_sel_hi:[0,0]
	v_pk_fma_f32 v[158:159], v[4:5], v[236:237], v[234:235] neg_lo:[0,0,1] neg_hi:[0,0,1]
	v_pk_fma_f32 v[236:237], v[4:5], v[236:237], v[234:235] op_sel_hi:[1,0,1]
	s_nop 0
	v_mov_b32_e32 v159, v237
	v_pk_mul_f32 v[4:5], v[158:159], s[24:25]
	ds_write_b64 v155, v[4:5] offset:47872
	ds_read_b64 v[222:223], v160 offset:60928
	ds_read_b64 v[224:225], v161 offset:0
	ds_read_b64 v[226:227], v160 offset:65280
	ds_read_b64 v[228:229], v162 offset:0
	s_waitcnt lgkmcnt(8)
	v_add_f32_e32 v164, v215, v217
	v_sub_f32_e32 v165, v214, v216
	v_mul_f32_e32 v216, 0.5, v164
	v_mul_f32_e32 v214, -0.5, v165
	v_pk_mul_f32 v[214:215], v[24:25], v[214:215] op_sel:[1,0] op_sel_hi:[0,0]
	v_pk_fma_f32 v[158:159], v[24:25], v[216:217], v[214:215] neg_lo:[0,0,1] neg_hi:[0,0,1]
	v_pk_fma_f32 v[216:217], v[24:25], v[216:217], v[214:215] op_sel_hi:[1,0,1]
	s_nop 0
	v_mov_b32_e32 v159, v217
	v_pk_mul_f32 v[24:25], v[158:159], s[24:25]
	ds_write_b64 v155, v[24:25] offset:52224
	s_waitcnt lgkmcnt(7)
	v_add_f32_e32 v164, v219, v221
	v_sub_f32_e32 v165, v218, v220
	v_mul_f32_e32 v220, 0.5, v164
	v_mul_f32_e32 v218, -0.5, v165
	v_pk_mul_f32 v[218:219], v[8:9], v[218:219] op_sel:[1,0] op_sel_hi:[0,0]
	v_pk_fma_f32 v[158:159], v[8:9], v[220:221], v[218:219] neg_lo:[0,0,1] neg_hi:[0,0,1]
	v_pk_fma_f32 v[220:221], v[8:9], v[220:221], v[218:219] op_sel_hi:[1,0,1]
	s_nop 0
	v_mov_b32_e32 v159, v221
	v_pk_mul_f32 v[8:9], v[158:159], s[24:25]
	ds_write_b64 v155, v[8:9] offset:56576
	s_waitcnt lgkmcnt(4)
	v_add_f32_e32 v164, v223, v225
	v_sub_f32_e32 v165, v222, v224
	v_mul_f32_e32 v224, 0.5, v164
	v_mul_f32_e32 v222, -0.5, v165
	v_pk_mul_f32 v[222:223], v[16:17], v[222:223] op_sel:[1,0] op_sel_hi:[0,0]
	v_pk_fma_f32 v[158:159], v[16:17], v[224:225], v[222:223] neg_lo:[0,0,1] neg_hi:[0,0,1]
	v_pk_fma_f32 v[224:225], v[16:17], v[224:225], v[222:223] op_sel_hi:[1,0,1]
	s_nop 0
	v_mov_b32_e32 v159, v225
	v_pk_mul_f32 v[16:17], v[158:159], s[24:25]
	ds_write_b64 v155, v[16:17] offset:60928
	s_waitcnt lgkmcnt(3)
	v_add_f32_e32 v164, v227, v229
	v_sub_f32_e32 v165, v226, v228
	v_mul_f32_e32 v228, 0.5, v164
	v_mul_f32_e32 v226, -0.5, v165
	v_pk_mul_f32 v[226:227], v[0:1], v[226:227] op_sel:[1,0] op_sel_hi:[0,0]
	v_pk_fma_f32 v[158:159], v[0:1], v[228:229], v[226:227] neg_lo:[0,0,1] neg_hi:[0,0,1]
	v_pk_fma_f32 v[228:229], v[0:1], v[228:229], v[226:227] op_sel_hi:[1,0,1]
	s_nop 0
	v_mov_b32_e32 v159, v229
	v_pk_mul_f32 v[0:1], v[158:159], s[24:25]
	ds_write_b64 v155, v[0:1] offset:65280
	s_mov_b32 s4, 16
	s_cmp_lg_u32 s4, 16
	s_waitcnt lgkmcnt(0)
	s_barrier
	s_and_saveexec_b64 s[28:29], s[40:41]
	s_cbranch_execz .LBB0_673
	ds_read_b64 v[0:1], v153
	ds_read_b64 v[2:3], v153 offset:2176
	ds_read_b64 v[4:5], v153 offset:4352
	ds_read_b64 v[6:7], v153 offset:6528
	ds_read_b64 v[8:9], v153 offset:8704
	ds_read_b64 v[10:11], v153 offset:10880
	ds_read_b64 v[12:13], v153 offset:13056
	ds_read_b64 v[14:15], v153 offset:15232
	ds_read_b64 v[16:17], v153 offset:17408
	ds_read_b64 v[18:19], v153 offset:19584
	ds_read_b64 v[20:21], v153 offset:21760
	ds_read_b64 v[22:23], v153 offset:23936
	ds_read_b64 v[24:25], v153 offset:26112
	ds_read_b64 v[26:27], v153 offset:28288
	ds_read_b64 v[28:29], v153 offset:30464
	ds_read_b64 v[30:31], v153 offset:32640
	ds_read_b64 v[58:59], v153 offset:34816
	ds_read_b64 v[60:61], v153 offset:41344
	ds_read_b64 v[94:95], v153 offset:43520
	ds_read_b64 v[96:97], v153 offset:45696
	ds_read_b64 v[98:99], v153 offset:47872
	ds_read_b64 v[100:101], v153 offset:50048
	ds_read_b64 v[102:103], v153 offset:52224
	ds_read_b64 v[104:105], v153 offset:54400
	ds_read_b64 v[106:107], v153 offset:56576
	ds_read_b64 v[108:109], v153 offset:58752
	ds_read_b64 v[110:111], v153 offset:60928
	ds_read_b64 v[112:113], v153 offset:63104
	ds_read_b64 v[114:115], v153 offset:65280
	ds_read_b64 v[116:117], v153 offset:36992
	ds_read_b64 v[118:119], v153 offset:39168
	ds_read_b64 v[120:121], v33
	s_waitcnt lgkmcnt(14)
	v_pk_add_f32 v[124:125], v[0:1], v[58:59]
	v_pk_add_f32 v[0:1], v[0:1], v[58:59] neg_lo:[0,1] neg_hi:[0,1]
	s_waitcnt lgkmcnt(2)
	v_pk_add_f32 v[58:59], v[2:3], v[116:117]
	v_pk_add_f32 v[2:3], v[2:3], v[116:117] neg_lo:[0,1] neg_hi:[0,1]
	s_mov_b32 s11, s14
	v_pk_mul_f32 v[116:117], v[2:3], s[16:17]
	s_mov_b32 s13, s86
	v_pk_fma_f32 v[2:3], v[2:3], s[6:7], v[116:117] op_sel:[0,0,1] op_sel_hi:[1,0,0]
	s_waitcnt lgkmcnt(1)
	v_pk_add_f32 v[116:117], v[4:5], v[118:119]
	v_pk_add_f32 v[4:5], v[4:5], v[118:119] neg_lo:[0,1] neg_hi:[0,1]
	s_mov_b32 s4, s21
	v_pk_mul_f32 v[118:119], v[4:5], s[18:19]
	s_mov_b32 s35, s30
	v_pk_fma_f32 v[4:5], v[4:5], s[30:31], v[118:119] op_sel:[0,0,1] op_sel_hi:[1,0,0]
	v_pk_add_f32 v[118:119], v[6:7], v[60:61]
	v_pk_add_f32 v[6:7], v[6:7], v[60:61] neg_lo:[0,1] neg_hi:[0,1]
	s_mov_b32 s8, s19
	v_pk_mul_f32 v[60:61], v[6:7], s[20:21]
	s_mov_b32 s77, s6
	v_pk_fma_f32 v[6:7], v[6:7], s[86:87], v[60:61] op_sel:[0,0,1] op_sel_hi:[1,0,0]
	v_pk_add_f32 v[60:61], v[8:9], v[94:95]
	v_pk_add_f32 v[8:9], v[8:9], v[94:95] neg_lo:[0,1] neg_hi:[0,1]
	s_mov_b32 s26, s17
	v_pk_mul_f32 v[94:95], v[8:9], s[10:11]
	s_nop 0
	v_pk_fma_f32 v[8:9], v[8:9], s[14:15], v[94:95] op_sel:[0,0,1] op_sel_hi:[1,0,0]
	v_pk_add_f32 v[94:95], v[10:11], v[96:97]
	v_pk_add_f32 v[10:11], v[10:11], v[96:97] neg_lo:[0,1] neg_hi:[0,1]
	s_nop 0
	v_pk_mul_f32 v[96:97], v[10:11], s[12:13]
	s_nop 0
	v_pk_fma_f32 v[10:11], v[10:11], s[4:5], v[96:97] op_sel:[0,0,1] op_sel_hi:[1,0,0]
	v_pk_add_f32 v[96:97], v[12:13], v[98:99]
	v_pk_add_f32 v[12:13], v[12:13], v[98:99] neg_lo:[0,1] neg_hi:[0,1]
	s_nop 0
	v_pk_mul_f32 v[98:99], v[12:13], s[34:35]
	s_nop 0
	v_pk_fma_f32 v[12:13], v[12:13], s[8:9], v[98:99] op_sel:[0,0,1] op_sel_hi:[1,0,0]
	v_pk_add_f32 v[98:99], v[14:15], v[100:101]
	v_pk_add_f32 v[14:15], v[14:15], v[100:101] neg_lo:[0,1] neg_hi:[0,1]
	s_nop 0
	v_pk_mul_f32 v[100:101], v[14:15], s[76:77]
	s_nop 0
	v_pk_fma_f32 v[14:15], v[14:15], s[26:27], v[100:101] op_sel:[0,0,1] op_sel_hi:[1,0,0]
	v_pk_add_f32 v[100:101], v[16:17], v[102:103]
	v_pk_add_f32 v[16:17], v[16:17], v[102:103] neg_lo:[0,1] neg_hi:[0,1]
	v_pk_add_f32 v[102:103], v[18:19], v[104:105]
	v_pk_add_f32 v[18:19], v[18:19], v[104:105] neg_lo:[0,1] neg_hi:[0,1]
	s_nop 0
	v_pk_mul_f32 v[104:105], v[18:19], s[76:77]
	s_nop 0
	v_pk_fma_f32 v[18:19], v[18:19], s[26:27], v[104:105] op_sel:[0,0,1] op_sel_hi:[1,0,0] neg_lo:[1,0,0] neg_hi:[1,0,0]
	v_pk_add_f32 v[104:105], v[20:21], v[106:107]
	v_pk_add_f32 v[20:21], v[20:21], v[106:107] neg_lo:[0,1] neg_hi:[0,1]
	s_nop 0
	v_pk_mul_f32 v[106:107], v[20:21], s[34:35]
	s_nop 0
	v_pk_fma_f32 v[20:21], v[20:21], s[8:9], v[106:107] op_sel:[0,0,1] op_sel_hi:[1,0,0] neg_lo:[1,0,0] neg_hi:[1,0,0]
	v_pk_add_f32 v[106:107], v[22:23], v[108:109]
	v_pk_add_f32 v[22:23], v[22:23], v[108:109] neg_lo:[0,1] neg_hi:[0,1]
	s_nop 0
	v_pk_mul_f32 v[108:109], v[22:23], s[12:13]
	s_nop 0
	v_pk_fma_f32 v[22:23], v[22:23], s[4:5], v[108:109] op_sel:[0,0,1] op_sel_hi:[1,0,0] neg_lo:[1,0,0] neg_hi:[1,0,0]
	v_pk_add_f32 v[108:109], v[24:25], v[110:111]
	v_pk_add_f32 v[24:25], v[24:25], v[110:111] neg_lo:[0,1] neg_hi:[0,1]
	s_nop 0
	v_pk_mul_f32 v[110:111], v[24:25], s[10:11]
	s_nop 0
	v_pk_fma_f32 v[24:25], v[24:25], s[14:15], v[110:111] op_sel:[0,0,1] op_sel_hi:[1,0,0] neg_lo:[1,0,0] neg_hi:[1,0,0]
	v_pk_add_f32 v[110:111], v[26:27], v[112:113]
	v_pk_add_f32 v[26:27], v[26:27], v[112:113] neg_lo:[0,1] neg_hi:[0,1]
	s_nop 0
	v_pk_mul_f32 v[112:113], v[26:27], s[20:21]
	s_nop 0
	v_pk_fma_f32 v[26:27], v[26:27], s[86:87], v[112:113] op_sel:[0,0,1] op_sel_hi:[1,0,0] neg_lo:[1,0,0] neg_hi:[1,0,0]
	v_pk_add_f32 v[112:113], v[28:29], v[114:115]
	v_pk_add_f32 v[28:29], v[28:29], v[114:115] neg_lo:[0,1] neg_hi:[0,1]
	s_nop 0
	v_pk_mul_f32 v[114:115], v[28:29], s[18:19]
	s_nop 0
	v_pk_fma_f32 v[28:29], v[28:29], s[30:31], v[114:115] op_sel:[0,0,1] op_sel_hi:[1,0,0] neg_lo:[1,0,0] neg_hi:[1,0,0]
	s_waitcnt lgkmcnt(0)
	v_pk_add_f32 v[114:115], v[30:31], v[120:121]
	v_pk_add_f32 v[30:31], v[30:31], v[120:121] neg_lo:[0,1] neg_hi:[0,1]
	s_nop 0
	v_pk_mul_f32 v[120:121], v[30:31], s[16:17]
	s_nop 0
	v_pk_fma_f32 v[30:31], v[30:31], s[6:7], v[120:121] op_sel:[0,0,1] op_sel_hi:[1,0,0] neg_lo:[1,0,0] neg_hi:[1,0,0]
	v_pk_add_f32 v[120:121], v[124:125], v[100:101]
	v_pk_add_f32 v[100:101], v[124:125], v[100:101] neg_lo:[0,1] neg_hi:[0,1]
	v_pk_add_f32 v[124:125], v[58:59], v[102:103]
	v_pk_add_f32 v[58:59], v[58:59], v[102:103] neg_lo:[0,1] neg_hi:[0,1]
	s_nop 0
	v_pk_mul_f32 v[102:103], v[58:59], s[18:19]
	s_nop 0
	v_pk_fma_f32 v[58:59], v[58:59], s[30:31], v[102:103] op_sel:[0,0,1] op_sel_hi:[1,0,0]
	v_pk_add_f32 v[102:103], v[116:117], v[104:105]
	v_pk_add_f32 v[104:105], v[116:117], v[104:105] neg_lo:[0,1] neg_hi:[0,1]
	s_nop 0
	v_pk_mul_f32 v[116:117], v[104:105], s[10:11]
	s_nop 0
	v_pk_fma_f32 v[104:105], v[104:105], s[14:15], v[116:117] op_sel:[0,0,1] op_sel_hi:[1,0,0]
	v_pk_add_f32 v[116:117], v[118:119], v[106:107]
	v_pk_add_f32 v[106:107], v[118:119], v[106:107] neg_lo:[0,1] neg_hi:[0,1]
	s_nop 0
	v_pk_mul_f32 v[118:119], v[106:107], s[34:35]
	s_nop 0
	v_pk_fma_f32 v[106:107], v[106:107], s[8:9], v[118:119] op_sel:[0,0,1] op_sel_hi:[1,0,0]
	v_pk_add_f32 v[118:119], v[60:61], v[108:109]
	v_pk_add_f32 v[60:61], v[60:61], v[108:109] neg_lo:[0,1] neg_hi:[0,1]
	v_pk_add_f32 v[108:109], v[94:95], v[110:111]
	v_pk_add_f32 v[94:95], v[94:95], v[110:111] neg_lo:[0,1] neg_hi:[0,1]
	s_nop 0
	v_pk_mul_f32 v[110:111], v[94:95], s[34:35]
	s_nop 0
	v_pk_fma_f32 v[94:95], v[94:95], s[8:9], v[110:111] op_sel:[0,0,1] op_sel_hi:[1,0,0] neg_lo:[1,0,0] neg_hi:[1,0,0]
	v_pk_add_f32 v[110:111], v[96:97], v[112:113]
	v_pk_add_f32 v[96:97], v[96:97], v[112:113] neg_lo:[0,1] neg_hi:[0,1]
	s_nop 0
	v_pk_mul_f32 v[112:113], v[96:97], s[10:11]
	s_nop 0
	v_pk_fma_f32 v[96:97], v[96:97], s[14:15], v[112:113] op_sel:[0,0,1] op_sel_hi:[1,0,0] neg_lo:[1,0,0] neg_hi:[1,0,0]
	v_pk_add_f32 v[112:113], v[98:99], v[114:115]
	v_pk_add_f32 v[98:99], v[98:99], v[114:115] neg_lo:[0,1] neg_hi:[0,1]
	s_nop 0
	v_pk_mul_f32 v[114:115], v[98:99], s[18:19]
	s_nop 0
	v_pk_fma_f32 v[98:99], v[98:99], s[30:31], v[114:115] op_sel:[0,0,1] op_sel_hi:[1,0,0] neg_lo:[1,0,0] neg_hi:[1,0,0]
	v_pk_add_f32 v[114:115], v[0:1], v[16:17] op_sel:[0,1] op_sel_hi:[1,0] neg_hi:[0,1]
	v_pk_add_f32 v[0:1], v[0:1], v[16:17] op_sel:[0,1] op_sel_hi:[1,0] neg_lo:[0,1]
	v_pk_add_f32 v[16:17], v[2:3], v[18:19]
	v_pk_add_f32 v[2:3], v[2:3], v[18:19] neg_lo:[0,1] neg_hi:[0,1]
	s_nop 0
	v_pk_mul_f32 v[18:19], v[2:3], s[18:19]
	s_nop 0
	v_pk_fma_f32 v[2:3], v[2:3], s[30:31], v[18:19] op_sel:[0,0,1] op_sel_hi:[1,0,0]
	v_pk_add_f32 v[18:19], v[4:5], v[20:21]
	v_pk_add_f32 v[4:5], v[4:5], v[20:21] neg_lo:[0,1] neg_hi:[0,1]
	s_nop 0
	v_pk_mul_f32 v[20:21], v[4:5], s[10:11]
	s_nop 0
	v_pk_fma_f32 v[4:5], v[4:5], s[14:15], v[20:21] op_sel:[0,0,1] op_sel_hi:[1,0,0]
	v_pk_add_f32 v[20:21], v[6:7], v[22:23]
	v_pk_add_f32 v[6:7], v[6:7], v[22:23] neg_lo:[0,1] neg_hi:[0,1]
	s_nop 0
	v_pk_mul_f32 v[22:23], v[6:7], s[34:35]
	s_nop 0
	v_pk_fma_f32 v[6:7], v[6:7], s[8:9], v[22:23] op_sel:[0,0,1] op_sel_hi:[1,0,0]
	v_pk_add_f32 v[22:23], v[8:9], v[24:25]
	v_pk_add_f32 v[8:9], v[8:9], v[24:25] neg_lo:[0,1] neg_hi:[0,1]
	v_pk_add_f32 v[24:25], v[10:11], v[26:27]
	v_pk_add_f32 v[10:11], v[10:11], v[26:27] neg_lo:[0,1] neg_hi:[0,1]
	s_nop 0
	v_pk_mul_f32 v[26:27], v[10:11], s[34:35]
	s_nop 0
	v_pk_fma_f32 v[10:11], v[10:11], s[8:9], v[26:27] op_sel:[0,0,1] op_sel_hi:[1,0,0] neg_lo:[1,0,0] neg_hi:[1,0,0]
	v_pk_add_f32 v[26:27], v[12:13], v[28:29]
	v_pk_add_f32 v[12:13], v[12:13], v[28:29] neg_lo:[0,1] neg_hi:[0,1]
	s_nop 0
	v_pk_mul_f32 v[28:29], v[12:13], s[10:11]
	s_nop 0
	v_pk_fma_f32 v[12:13], v[12:13], s[14:15], v[28:29] op_sel:[0,0,1] op_sel_hi:[1,0,0] neg_lo:[1,0,0] neg_hi:[1,0,0]
	v_pk_add_f32 v[28:29], v[14:15], v[30:31]
	v_pk_add_f32 v[14:15], v[14:15], v[30:31] neg_lo:[0,1] neg_hi:[0,1]
	s_nop 0
	v_pk_mul_f32 v[30:31], v[14:15], s[18:19]
	s_nop 0
	v_pk_fma_f32 v[14:15], v[14:15], s[30:31], v[30:31] op_sel:[0,0,1] op_sel_hi:[1,0,0] neg_lo:[1,0,0] neg_hi:[1,0,0]
	v_pk_add_f32 v[30:31], v[120:121], v[118:119]
	v_pk_add_f32 v[118:119], v[120:121], v[118:119] neg_lo:[0,1] neg_hi:[0,1]
	v_pk_add_f32 v[120:121], v[124:125], v[108:109]
	v_pk_add_f32 v[108:109], v[124:125], v[108:109] neg_lo:[0,1] neg_hi:[0,1]
	s_nop 0
	v_pk_mul_f32 v[124:125], v[108:109], s[10:11]
	s_nop 0
	v_pk_fma_f32 v[108:109], v[108:109], s[14:15], v[124:125] op_sel:[0,0,1] op_sel_hi:[1,0,0]
	v_pk_add_f32 v[124:125], v[102:103], v[110:111]
	v_pk_add_f32 v[102:103], v[102:103], v[110:111] neg_lo:[0,1] neg_hi:[0,1]
	v_pk_add_f32 v[110:111], v[116:117], v[112:113]
	v_pk_add_f32 v[112:113], v[116:117], v[112:113] neg_lo:[0,1] neg_hi:[0,1]
	s_nop 0
	v_pk_mul_f32 v[116:117], v[112:113], s[10:11]
	s_nop 0
	v_pk_fma_f32 v[112:113], v[112:113], s[14:15], v[116:117] op_sel:[0,0,1] op_sel_hi:[1,0,0] neg_lo:[1,0,0] neg_hi:[1,0,0]
	v_pk_add_f32 v[116:117], v[100:101], v[60:61] op_sel:[0,1] op_sel_hi:[1,0] neg_hi:[0,1]
	v_pk_add_f32 v[60:61], v[100:101], v[60:61] op_sel:[0,1] op_sel_hi:[1,0] neg_lo:[0,1]
	v_pk_add_f32 v[100:101], v[58:59], v[94:95]
	v_pk_add_f32 v[58:59], v[58:59], v[94:95] neg_lo:[0,1] neg_hi:[0,1]
	v_pk_add_f32 v[126:127], v[108:109], v[112:113]
	v_pk_mul_f32 v[94:95], v[58:59], s[10:11]
	s_nop 0
	v_pk_fma_f32 v[58:59], v[58:59], s[14:15], v[94:95] op_sel:[0,0,1] op_sel_hi:[1,0,0]
	v_pk_add_f32 v[94:95], v[104:105], v[96:97]
	v_pk_add_f32 v[96:97], v[104:105], v[96:97] neg_lo:[0,1] neg_hi:[0,1]
	v_pk_add_f32 v[104:105], v[106:107], v[98:99]
	v_pk_add_f32 v[98:99], v[106:107], v[98:99] neg_lo:[0,1] neg_hi:[0,1]
	s_nop 0
	v_pk_mul_f32 v[106:107], v[98:99], s[10:11]
	v_pk_add_f32 v[130:131], v[60:61], v[96:97] op_sel:[0,1] op_sel_hi:[1,0] neg_hi:[0,1]
	v_pk_fma_f32 v[98:99], v[98:99], s[14:15], v[106:107] op_sel:[0,0,1] op_sel_hi:[1,0,0] neg_lo:[1,0,0] neg_hi:[1,0,0]
	v_pk_add_f32 v[106:107], v[114:115], v[22:23]
	v_pk_add_f32 v[22:23], v[114:115], v[22:23] neg_lo:[0,1] neg_hi:[0,1]
	v_pk_add_f32 v[114:115], v[16:17], v[24:25]
	v_pk_add_f32 v[16:17], v[16:17], v[24:25] neg_lo:[0,1] neg_hi:[0,1]
	v_pk_add_f32 v[132:133], v[60:61], v[96:97] op_sel:[0,1] op_sel_hi:[1,0] neg_lo:[0,1]
	v_pk_mul_f32 v[24:25], v[16:17], s[10:11]
	v_pk_add_f32 v[60:61], v[58:59], v[98:99]
	v_pk_fma_f32 v[16:17], v[16:17], s[14:15], v[24:25] op_sel:[0,0,1] op_sel_hi:[1,0,0]
	v_pk_add_f32 v[24:25], v[18:19], v[26:27]
	v_pk_add_f32 v[18:19], v[18:19], v[26:27] neg_lo:[0,1] neg_hi:[0,1]
	v_pk_add_f32 v[26:27], v[20:21], v[28:29]
	v_pk_add_f32 v[20:21], v[20:21], v[28:29] neg_lo:[0,1] neg_hi:[0,1]
	s_nop 0
	v_pk_mul_f32 v[28:29], v[20:21], s[10:11]
	v_pk_add_f32 v[58:59], v[58:59], v[98:99] neg_lo:[0,1] neg_hi:[0,1]
	v_pk_fma_f32 v[20:21], v[20:21], s[14:15], v[28:29] op_sel:[0,0,1] op_sel_hi:[1,0,0] neg_lo:[1,0,0] neg_hi:[1,0,0]
	v_pk_add_f32 v[28:29], v[0:1], v[8:9] op_sel:[0,1] op_sel_hi:[1,0] neg_hi:[0,1]
	v_pk_add_f32 v[0:1], v[0:1], v[8:9] op_sel:[0,1] op_sel_hi:[1,0] neg_lo:[0,1]
	v_pk_add_f32 v[8:9], v[2:3], v[10:11]
	v_pk_add_f32 v[2:3], v[2:3], v[10:11] neg_lo:[0,1] neg_hi:[0,1]
	v_pk_add_f32 v[134:135], v[106:107], v[24:25]
	v_pk_mul_f32 v[10:11], v[2:3], s[10:11]
	v_pk_add_f32 v[106:107], v[106:107], v[24:25] neg_lo:[0,1] neg_hi:[0,1]
	v_pk_fma_f32 v[2:3], v[2:3], s[14:15], v[10:11] op_sel:[0,0,1] op_sel_hi:[1,0,0]
	v_pk_add_f32 v[10:11], v[4:5], v[12:13]
	v_pk_add_f32 v[4:5], v[4:5], v[12:13] neg_lo:[0,1] neg_hi:[0,1]
	v_pk_add_f32 v[12:13], v[6:7], v[14:15]
	v_pk_add_f32 v[6:7], v[6:7], v[14:15] neg_lo:[0,1] neg_hi:[0,1]
	s_nop 0
	v_pk_mul_f32 v[14:15], v[6:7], s[10:11]
	v_pk_add_f32 v[24:25], v[114:115], v[26:27] neg_lo:[0,1] neg_hi:[0,1]
	v_pk_fma_f32 v[6:7], v[6:7], s[14:15], v[14:15] op_sel:[0,0,1] op_sel_hi:[1,0,0] neg_lo:[1,0,0] neg_hi:[1,0,0]
	v_pk_add_f32 v[14:15], v[30:31], v[124:125]
	v_pk_add_f32 v[30:31], v[30:31], v[124:125] neg_lo:[0,1] neg_hi:[0,1]
	v_pk_add_f32 v[124:125], v[120:121], v[110:111]
	v_pk_add_f32 v[110:111], v[120:121], v[110:111] neg_lo:[0,1] neg_hi:[0,1]
	v_pk_add_f32 v[120:121], v[118:119], v[102:103] op_sel:[0,1] op_sel_hi:[1,0] neg_hi:[0,1]
	v_pk_add_f32 v[118:119], v[118:119], v[102:103] op_sel:[0,1] op_sel_hi:[1,0] neg_lo:[0,1]
	v_pk_add_f32 v[102:103], v[108:109], v[112:113] neg_lo:[0,1] neg_hi:[0,1]
	v_pk_add_f32 v[112:113], v[116:117], v[94:95]
	v_pk_add_f32 v[94:95], v[116:117], v[94:95] neg_lo:[0,1] neg_hi:[0,1]
	v_pk_add_f32 v[116:117], v[100:101], v[104:105]
	v_pk_add_f32 v[100:101], v[100:101], v[104:105] neg_lo:[0,1] neg_hi:[0,1]
	v_pk_add_f32 v[138:139], v[22:23], v[18:19] op_sel:[0,1] op_sel_hi:[1,0] neg_hi:[0,1]
	v_pk_add_f32 v[140:141], v[22:23], v[18:19] op_sel:[0,1] op_sel_hi:[1,0] neg_lo:[0,1]
	v_pk_add_f32 v[18:19], v[16:17], v[20:21]
	v_pk_add_f32 v[16:17], v[16:17], v[20:21] neg_lo:[0,1] neg_hi:[0,1]
	v_pk_add_f32 v[144:145], v[28:29], v[10:11]
	v_pk_add_f32 v[158:159], v[28:29], v[10:11] neg_lo:[0,1] neg_hi:[0,1]
	v_pk_add_f32 v[10:11], v[8:9], v[12:13]
	v_pk_add_f32 v[8:9], v[8:9], v[12:13] neg_lo:[0,1] neg_hi:[0,1]
	v_pk_add_f32 v[162:163], v[0:1], v[4:5] op_sel:[0,1] op_sel_hi:[1,0] neg_hi:[0,1]
	v_pk_add_f32 v[164:165], v[0:1], v[4:5] op_sel:[0,1] op_sel_hi:[1,0] neg_lo:[0,1]
	v_pk_add_f32 v[0:1], v[2:3], v[6:7] neg_lo:[0,1] neg_hi:[0,1]
	v_pk_mul_f32 v[108:109], v[102:103], s[22:23]
	v_pk_mul_f32 v[128:129], v[100:101], s[22:23]
	v_pk_add_f32 v[136:137], v[114:115], v[26:27]
	v_pk_mul_f32 v[114:115], v[24:25], s[22:23]
	v_pk_mul_f32 v[142:143], v[16:17], s[22:23]
	v_pk_mul_f32 v[160:161], v[8:9], s[22:23]
	v_pk_add_f32 v[166:167], v[2:3], v[6:7]
	v_pk_mul_f32 v[168:169], v[0:1], s[22:23]
	v_pk_add_f32 v[28:29], v[14:15], v[124:125]
	v_pk_add_f32 v[104:105], v[14:15], v[124:125] neg_lo:[0,1] neg_hi:[0,1]
	v_pk_add_f32 v[24:25], v[30:31], v[110:111] op_sel:[0,1] op_sel_hi:[1,0] neg_hi:[0,1]
	v_pk_add_f32 v[102:103], v[30:31], v[110:111] op_sel:[0,1] op_sel_hi:[1,0] neg_lo:[0,1]
	v_pk_add_f32 v[20:21], v[120:121], v[126:127]
	v_pk_add_f32 v[100:101], v[120:121], v[126:127] neg_lo:[0,1] neg_hi:[0,1]
	v_pk_add_f32 v[16:17], v[118:119], v[108:109] op_sel:[0,1] op_sel_hi:[1,0]
	v_pk_add_f32 v[98:99], v[118:119], v[108:109] op_sel:[0,1] op_sel_hi:[1,0] neg_lo:[0,1] neg_hi:[0,1]
	v_pk_add_f32 v[12:13], v[112:113], v[116:117]
	v_pk_add_f32 v[96:97], v[112:113], v[116:117] neg_lo:[0,1] neg_hi:[0,1]
	v_pk_add_f32 v[8:9], v[94:95], v[128:129] op_sel:[0,1] op_sel_hi:[1,0]
	v_pk_add_f32 v[94:95], v[94:95], v[128:129] op_sel:[0,1] op_sel_hi:[1,0] neg_lo:[0,1] neg_hi:[0,1]
	v_pk_add_f32 v[4:5], v[130:131], v[60:61]
	v_pk_add_f32 v[60:61], v[130:131], v[60:61] neg_lo:[0,1] neg_hi:[0,1]
	v_pk_add_f32 v[0:1], v[132:133], v[58:59] op_sel:[0,1] op_sel_hi:[1,0] neg_hi:[0,1]
	v_pk_add_f32 v[58:59], v[132:133], v[58:59] op_sel:[0,1] op_sel_hi:[1,0] neg_lo:[0,1]
	v_pk_add_f32 v[30:31], v[134:135], v[136:137]
	v_pk_add_f32 v[120:121], v[134:135], v[136:137] neg_lo:[0,1] neg_hi:[0,1]
	v_pk_add_f32 v[26:27], v[106:107], v[114:115] op_sel:[0,1] op_sel_hi:[1,0]
	v_pk_add_f32 v[118:119], v[106:107], v[114:115] op_sel:[0,1] op_sel_hi:[1,0] neg_lo:[0,1] neg_hi:[0,1]
	v_pk_add_f32 v[22:23], v[138:139], v[18:19]
	v_pk_add_f32 v[116:117], v[138:139], v[18:19] neg_lo:[0,1] neg_hi:[0,1]
	v_pk_add_f32 v[18:19], v[140:141], v[142:143] op_sel:[0,1] op_sel_hi:[1,0]
	v_pk_add_f32 v[114:115], v[140:141], v[142:143] op_sel:[0,1] op_sel_hi:[1,0] neg_lo:[0,1] neg_hi:[0,1]
	v_pk_add_f32 v[14:15], v[144:145], v[10:11]
	v_pk_add_f32 v[112:113], v[144:145], v[10:11] neg_lo:[0,1] neg_hi:[0,1]
	v_pk_add_f32 v[10:11], v[158:159], v[160:161] op_sel:[0,1] op_sel_hi:[1,0]
	v_pk_add_f32 v[110:111], v[158:159], v[160:161] op_sel:[0,1] op_sel_hi:[1,0] neg_lo:[0,1] neg_hi:[0,1]
	v_pk_add_f32 v[6:7], v[162:163], v[166:167]
	v_pk_add_f32 v[108:109], v[162:163], v[166:167] neg_lo:[0,1] neg_hi:[0,1]
	v_pk_add_f32 v[2:3], v[164:165], v[168:169] op_sel:[0,1] op_sel_hi:[1,0]
	v_pk_add_f32 v[106:107], v[164:165], v[168:169] op_sel:[0,1] op_sel_hi:[1,0] neg_lo:[0,1] neg_hi:[0,1]
